# merge combine: packed v_pk_fma_f32 split into scalar v_fma_f32 pairs (bit-identical); on top of g8
# baseline (speedup 1.0000x reference)
; DI int otid() { int t = threadIdx.x; asm volatile("" : "+v"(t)); return t; }
; template <int TJ>
; DI void gemm_core(const u16* __restrict__ W, int ldw, const u16* __restrict__ X, int ldx, int K, f32x16 (&acc)[2][TJ], char* lds) {
;   constexpr int XR = 64 * TJ;
;   constexpr int WBYTES = 128 * 64, XBYTES = XR * 64, STAGE = WBYTES + XBYTES;
;   const int tid = otid(), lane = tid & 63, wid = tid >> 6, r = lane & 31, h = lane >> 5;
;   const int wn = wid & 1, wt = wid >> 1;
;   u32x4 wA[2], xA[TJ], wB[2], xB[TJ];
;   const int lrow = tid >> 2, lch = tid & 3;
;   const u16* wp = W + (size_t)lrow * ldw + lch * 8;
;   const u16* xp = X + (size_t)lrow * ldx + lch * 8;
;   const int nk = K / 32;
;     ...
;   G_LOAD(wA, xA, 0);
;   G_LOAD(wB, xB, 1);
;   G_STORE(wA, xA, 0);
;   __syncthreads();
;   for (int kt = 0; kt < nk; kt += 2) {
;     if (kt + 2 < nk) G_LOAD(wA, xA, kt + 2);
;     G_COMPUTE(0);
;     G_STORE(wB, xB, 1);
;     __syncthreads();
;     if (kt + 3 < nk) G_LOAD(wB, xB, kt + 3);
;     G_COMPUTE(1);
;     if (kt + 2 < nk) G_STORE(wA, xA, 0);
;     __syncthreads();
;   }
.LBB0_43:
	v_mov_b32_e32 v14, v190
	s_add_u32 s42, s22, s38
	v_ashrrev_i32_e32 v12, 2, v14
	v_and_b32_e32 v15, 3, v14
	v_ashrrev_i32_e32 v13, 31, v12
	v_lshlrev_b64 v[0:1], 11, v[12:13]
	s_waitcnt vmcnt(4)
	v_lshlrev_b32_e32 v64, 4, v15
	v_or_b32_e32 v2, v0, v64
	v_mov_b32_e32 v3, v1
	s_addc_u32 s43, s23, s39
	v_lshl_add_u64 v[4:5], s[42:43], 0, v[2:3]
	s_mov_b32 s18, 0x1cd20000
	v_add_co_u32_e32 v80, vcc, s18, v4
	v_lshl_add_u64 v[0:1], s[36:37], 0, v[0:1]
	s_nop 0
	v_addc_co_u32_e32 v81, vcc, 0, v5, vcc
	v_lshl_add_u64 v[78:79], v[0:1], 0, v[64:65]
	global_load_dwordx4 v[0:3], v[80:81], off
	s_mov_b32 s18, 0x1cd40000
	v_add_co_u32_e32 v82, vcc, s18, v4
	v_lshlrev_b32_e32 v17, 5, v15
	s_nop 0
	v_addc_co_u32_e32 v83, vcc, 0, v5, vcc
	global_load_dwordx4 v[4:7], v[82:83], off
	global_load_dwordx4 v[8:11], v[78:79], off
	global_load_dwordx4 v[32:35], v[80:81], off offset:64
	global_load_dwordx4 v[36:39], v[82:83], off offset:64
	v_lshlrev_b32_e32 v12, 4, v12
	v_lshlrev_b32_e32 v16, 11, v15
	v_xor_b32_e32 v18, v12, v17
	v_add_u32_e32 v64, v16, v18
	global_load_dwordx4 v[40:43], v[78:79], off offset:64
	v_bfe_u32 v13, v14, 5, 1
	s_movk_i32 s18, 0xfe00
	s_waitcnt vmcnt(5)
	ds_write_b128 v64, v[0:3]
	v_add_u32_e32 v0, 0x400, v12
	v_xad_u32 v86, v0, v17, v16
	v_lshlrev_b32_e32 v0, 10, v15
	v_sub_u32_e32 v0, v16, v0
	v_add_u32_e32 v87, v0, v18
	s_waitcnt vmcnt(4)
	ds_write_b128 v86, v[4:7]
	s_waitcnt vmcnt(3)
	ds_write_b128 v87, v[8:11] offset:8192
	s_waitcnt lgkmcnt(0)
	s_barrier
	global_load_dwordx4 v[94:97], v[80:81], off offset:128
	global_load_dwordx4 v[98:101], v[82:83], off offset:128
	global_load_dwordx4 v[102:105], v[78:79], off offset:128
	v_lshlrev_b32_e32 v1, 4, v14
	v_lshlrev_b32_e32 v0, 2, v14
	v_and_b32_e32 v2, 0x1f0, v1
	v_and_b32_e32 v1, 0x5f0, v1
	v_and_or_b32 v0, v0, s18, v2
	v_lshlrev_b32_e32 v2, 11, v13
	v_lshlrev_b32_e32 v3, 5, v13
	v_or_b32_e32 v4, 0x200, v1
	v_lshlrev_b32_e32 v5, 10, v13
	v_bitop3_b32 v88, v2, v3, v1 bitop3:0xf6
	v_bitop3_b32 v91, v2, v4, v3 bitop3:0xf6
	v_sub_u32_e32 v2, v2, v5
	v_xad_u32 v93, v3, v0, v2
	v_or_b32_e32 v2, 2, v13
	v_lshlrev_b32_e32 v3, 11, v2
	v_lshlrev_b32_e32 v5, 5, v2
	v_bitop3_b32 v89, v3, v5, v1 bitop3:0xf6
	v_lshlrev_b32_e32 v1, 10, v2
	v_sub_u32_e32 v1, v3, v1
	v_bitop3_b32 v90, v3, v5, v4 bitop3:0xf6
	v_xad_u32 v92, v5, v0, v1
	ds_read_b128 v[0:3], v88
	ds_read_b128 v[4:7], v91
	ds_read_b128 v[8:11], v93 offset:8192
	s_setprio 1
	s_waitcnt lgkmcnt(0)
	v_mfma_f32_32x32x16_bf16 v[16:31], v[0:3], v[8:11], 0
	v_mfma_f32_32x32x16_bf16 v[0:15], v[4:7], v[8:11], 0
	s_setprio 0
	ds_read_b128 v[106:109], v89
	ds_read_b128 v[110:113], v90
	ds_read_b128 v[114:117], v92 offset:8192
	s_setprio 1
	s_waitcnt lgkmcnt(0)
	v_mfma_f32_32x32x16_bf16 v[16:31], v[106:109], v[114:117], v[16:31]
	v_mfma_f32_32x32x16_bf16 v[0:15], v[110:113], v[114:117], v[0:15]
	s_setprio 0
	s_waitcnt vmcnt(5)
	ds_write_b128 v64, v[32:35] offset:12288
	s_waitcnt vmcnt(4)
	ds_write_b128 v86, v[36:39] offset:12288
	s_waitcnt vmcnt(3)
	ds_write_b128 v87, v[40:43] offset:20480
	s_waitcnt lgkmcnt(0)
	s_barrier
	global_load_dwordx4 v[32:35], v[82:83], off offset:192
	global_load_dwordx4 v[36:39], v[80:81], off offset:192
	global_load_dwordx4 v[40:43], v[78:79], off offset:192
	ds_read_b128 v[106:109], v88 offset:12288
	ds_read_b128 v[110:113], v91 offset:12288
	ds_read_b128 v[114:117], v93 offset:20480
	s_setprio 1
	s_waitcnt lgkmcnt(0)
	v_mfma_f32_32x32x16_bf16 v[16:31], v[106:109], v[114:117], v[16:31]
	v_mfma_f32_32x32x16_bf16 v[0:15], v[110:113], v[114:117], v[0:15]
	s_setprio 0
	ds_read_b128 v[106:109], v89 offset:12288
	ds_read_b128 v[110:113], v90 offset:12288
	ds_read_b128 v[114:117], v92 offset:20480
	s_setprio 1
	s_waitcnt lgkmcnt(0)
	v_mfma_f32_32x32x16_bf16 v[16:31], v[106:109], v[114:117], v[16:31]
	v_mfma_f32_32x32x16_bf16 v[0:15], v[110:113], v[114:117], v[0:15]
	s_setprio 0
	s_waitcnt vmcnt(5)
	ds_write_b128 v64, v[94:97]
	s_waitcnt vmcnt(4)
	ds_write_b128 v86, v[98:101]
	s_waitcnt vmcnt(3)
	ds_write_b128 v87, v[102:105] offset:8192
	s_waitcnt lgkmcnt(0)
	s_barrier
	global_load_dwordx4 v[94:97], v[82:83], off offset:256
	global_load_dwordx4 v[98:101], v[80:81], off offset:256
	global_load_dwordx4 v[102:105], v[78:79], off offset:256
	ds_read_b128 v[106:109], v88
	ds_read_b128 v[110:113], v91
	ds_read_b128 v[114:117], v93 offset:8192
	s_setprio 1
	s_waitcnt lgkmcnt(0)
	v_mfma_f32_32x32x16_bf16 v[16:31], v[106:109], v[114:117], v[16:31]
	v_mfma_f32_32x32x16_bf16 v[0:15], v[110:113], v[114:117], v[0:15]
	s_setprio 0
	ds_read_b128 v[106:109], v89
	ds_read_b128 v[110:113], v90
	ds_read_b128 v[114:117], v92 offset:8192
	s_setprio 1
	s_waitcnt lgkmcnt(0)
	v_mfma_f32_32x32x16_bf16 v[16:31], v[106:109], v[114:117], v[16:31]
	v_mfma_f32_32x32x16_bf16 v[0:15], v[110:113], v[114:117], v[0:15]
	s_setprio 0
	s_waitcnt vmcnt(4)
	ds_write_b128 v64, v[36:39] offset:12288
	ds_write_b128 v86, v[32:35] offset:12288
	s_waitcnt vmcnt(3)
	ds_write_b128 v87, v[40:43] offset:20480
	s_waitcnt lgkmcnt(0)
	s_barrier
	global_load_dwordx4 v[32:35], v[82:83], off offset:320
	global_load_dwordx4 v[36:39], v[80:81], off offset:320
	global_load_dwordx4 v[40:43], v[78:79], off offset:320
	ds_read_b128 v[106:109], v88 offset:12288
	ds_read_b128 v[110:113], v91 offset:12288
	ds_read_b128 v[114:117], v93 offset:20480
	s_setprio 1
	s_waitcnt lgkmcnt(0)
	v_mfma_f32_32x32x16_bf16 v[16:31], v[106:109], v[114:117], v[16:31]
	v_mfma_f32_32x32x16_bf16 v[0:15], v[110:113], v[114:117], v[0:15]
	s_setprio 0
	ds_read_b128 v[106:109], v89 offset:12288
	ds_read_b128 v[110:113], v90 offset:12288
	ds_read_b128 v[114:117], v92 offset:20480
	s_setprio 1
	s_waitcnt lgkmcnt(0)
	v_mfma_f32_32x32x16_bf16 v[16:31], v[106:109], v[114:117], v[16:31]
	v_mfma_f32_32x32x16_bf16 v[0:15], v[110:113], v[114:117], v[0:15]
	s_setprio 0
	s_waitcnt vmcnt(4)
	ds_write_b128 v64, v[98:101]
	ds_write_b128 v86, v[94:97]
	s_waitcnt vmcnt(3)
	ds_write_b128 v87, v[102:105] offset:8192
	s_waitcnt lgkmcnt(0)
	s_barrier
; template <int TJ>
; DI void gemm_core(const u16* __restrict__ W, int ldw, const u16* __restrict__ X, int ldx, int K, f32x16 (&acc)[2][TJ], char* lds) {
;     ...
;   G_LOAD(wA, xA, 0);
;   G_LOAD(wB, xB, 1);
;   G_STORE(wA, xA, 0);
;   __syncthreads();
;   for (int kt = 0; kt < nk; kt += 2) {
;     if (kt + 2 < nk) G_LOAD(wA, xA, kt + 2);
;     G_COMPUTE(0);
;     G_STORE(wB, xB, 1);
;     __syncthreads();
;     if (kt + 3 < nk) G_LOAD(wB, xB, kt + 3);
;     G_COMPUTE(1);
;     if (kt + 2 < nk) G_STORE(wA, xA, 0);
;     __syncthreads();
	global_load_dwordx4 v[94:97], v[82:83], off offset:384
	global_load_dwordx4 v[98:101], v[80:81], off offset:384
	global_load_dwordx4 v[102:105], v[78:79], off offset:384
	ds_read_b128 v[106:109], v88
	ds_read_b128 v[110:113], v91
	ds_read_b128 v[114:117], v93 offset:8192
	s_setprio 1
	s_waitcnt lgkmcnt(0)
	v_mfma_f32_32x32x16_bf16 v[16:31], v[106:109], v[114:117], v[16:31]
	v_mfma_f32_32x32x16_bf16 v[0:15], v[110:113], v[114:117], v[0:15]
	s_setprio 0
	ds_read_b128 v[106:109], v89
	ds_read_b128 v[110:113], v90
	ds_read_b128 v[114:117], v92 offset:8192
	s_setprio 1
	s_waitcnt lgkmcnt(0)
	v_mfma_f32_32x32x16_bf16 v[16:31], v[106:109], v[114:117], v[16:31]
	v_mfma_f32_32x32x16_bf16 v[0:15], v[110:113], v[114:117], v[0:15]
	s_setprio 0
	s_waitcnt vmcnt(4)
	ds_write_b128 v64, v[36:39] offset:12288
	ds_write_b128 v86, v[32:35] offset:12288
	s_waitcnt vmcnt(3)
	ds_write_b128 v87, v[40:43] offset:20480
	s_waitcnt lgkmcnt(0)
	s_barrier
	global_load_dwordx4 v[32:35], v[82:83], off offset:448
	global_load_dwordx4 v[36:39], v[80:81], off offset:448
	global_load_dwordx4 v[40:43], v[78:79], off offset:448
	ds_read_b128 v[106:109], v88 offset:12288
	ds_read_b128 v[110:113], v91 offset:12288
	ds_read_b128 v[114:117], v93 offset:20480
	s_setprio 1
	s_waitcnt lgkmcnt(0)
	v_mfma_f32_32x32x16_bf16 v[16:31], v[106:109], v[114:117], v[16:31]
	v_mfma_f32_32x32x16_bf16 v[0:15], v[110:113], v[114:117], v[0:15]
	s_setprio 0
	ds_read_b128 v[106:109], v89 offset:12288
	ds_read_b128 v[110:113], v90 offset:12288
	ds_read_b128 v[114:117], v92 offset:20480
	s_setprio 1
	s_waitcnt lgkmcnt(0)
	v_mfma_f32_32x32x16_bf16 v[16:31], v[106:109], v[114:117], v[16:31]
	v_mfma_f32_32x32x16_bf16 v[0:15], v[110:113], v[114:117], v[0:15]
	s_setprio 0
	s_waitcnt vmcnt(4)
	ds_write_b128 v64, v[98:101]
	ds_write_b128 v86, v[94:97]
	s_waitcnt vmcnt(3)
	ds_write_b128 v87, v[102:105] offset:8192
	s_waitcnt lgkmcnt(0)
	s_barrier
	global_load_dwordx4 v[94:97], v[82:83], off offset:512
	global_load_dwordx4 v[98:101], v[80:81], off offset:512
	global_load_dwordx4 v[102:105], v[78:79], off offset:512
	ds_read_b128 v[106:109], v88
	ds_read_b128 v[110:113], v91
	ds_read_b128 v[114:117], v93 offset:8192
	s_setprio 1
	s_waitcnt lgkmcnt(0)
	v_mfma_f32_32x32x16_bf16 v[16:31], v[106:109], v[114:117], v[16:31]
	v_mfma_f32_32x32x16_bf16 v[0:15], v[110:113], v[114:117], v[0:15]
	s_setprio 0
	ds_read_b128 v[106:109], v89
	ds_read_b128 v[110:113], v90
	ds_read_b128 v[114:117], v92 offset:8192
	s_setprio 1
	s_waitcnt lgkmcnt(0)
	v_mfma_f32_32x32x16_bf16 v[16:31], v[106:109], v[114:117], v[16:31]
	v_mfma_f32_32x32x16_bf16 v[0:15], v[110:113], v[114:117], v[0:15]
	s_setprio 0
	s_waitcnt vmcnt(4)
	ds_write_b128 v64, v[36:39] offset:12288
	ds_write_b128 v86, v[32:35] offset:12288
	s_waitcnt vmcnt(3)
	ds_write_b128 v87, v[40:43] offset:20480
	s_waitcnt lgkmcnt(0)
	s_barrier
	global_load_dwordx4 v[32:35], v[82:83], off offset:576
	global_load_dwordx4 v[36:39], v[80:81], off offset:576
	global_load_dwordx4 v[40:43], v[78:79], off offset:576
	ds_read_b128 v[106:109], v88 offset:12288
	ds_read_b128 v[110:113], v91 offset:12288
	ds_read_b128 v[114:117], v93 offset:20480
	s_setprio 1
	s_waitcnt lgkmcnt(0)
	v_mfma_f32_32x32x16_bf16 v[16:31], v[106:109], v[114:117], v[16:31]
	v_mfma_f32_32x32x16_bf16 v[0:15], v[110:113], v[114:117], v[0:15]
	s_setprio 0
	ds_read_b128 v[106:109], v89 offset:12288
	ds_read_b128 v[110:113], v90 offset:12288
	ds_read_b128 v[114:117], v92 offset:20480
	s_setprio 1
	s_waitcnt lgkmcnt(0)
	v_mfma_f32_32x32x16_bf16 v[16:31], v[106:109], v[114:117], v[16:31]
	v_mfma_f32_32x32x16_bf16 v[0:15], v[110:113], v[114:117], v[0:15]
	s_setprio 0
	s_waitcnt vmcnt(4)
	ds_write_b128 v64, v[98:101]
	ds_write_b128 v86, v[94:97]
	s_waitcnt vmcnt(3)
	ds_write_b128 v87, v[102:105] offset:8192
	s_waitcnt lgkmcnt(0)
	s_barrier
	global_load_dwordx4 v[94:97], v[82:83], off offset:640
	global_load_dwordx4 v[98:101], v[80:81], off offset:640
	global_load_dwordx4 v[102:105], v[78:79], off offset:640
	ds_read_b128 v[106:109], v88
	ds_read_b128 v[110:113], v91
	ds_read_b128 v[114:117], v93 offset:8192
	s_setprio 1
	s_waitcnt lgkmcnt(0)
	v_mfma_f32_32x32x16_bf16 v[16:31], v[106:109], v[114:117], v[16:31]
	v_mfma_f32_32x32x16_bf16 v[0:15], v[110:113], v[114:117], v[0:15]
	s_setprio 0
	ds_read_b128 v[106:109], v89
	ds_read_b128 v[110:113], v90
	ds_read_b128 v[114:117], v92 offset:8192
	s_setprio 1
	s_waitcnt lgkmcnt(0)
	v_mfma_f32_32x32x16_bf16 v[16:31], v[106:109], v[114:117], v[16:31]
	v_mfma_f32_32x32x16_bf16 v[0:15], v[110:113], v[114:117], v[0:15]
	s_setprio 0
	s_waitcnt vmcnt(4)
	ds_write_b128 v64, v[36:39] offset:12288
	ds_write_b128 v86, v[32:35] offset:12288
	s_waitcnt vmcnt(3)
	ds_write_b128 v87, v[40:43] offset:20480
	s_waitcnt lgkmcnt(0)
	s_barrier
	global_load_dwordx4 v[32:35], v[82:83], off offset:704
	global_load_dwordx4 v[36:39], v[80:81], off offset:704
	global_load_dwordx4 v[40:43], v[78:79], off offset:704
	ds_read_b128 v[106:109], v88 offset:12288
	ds_read_b128 v[110:113], v91 offset:12288
	ds_read_b128 v[114:117], v93 offset:20480
	s_setprio 1
	s_waitcnt lgkmcnt(0)
	v_mfma_f32_32x32x16_bf16 v[16:31], v[106:109], v[114:117], v[16:31]
	v_mfma_f32_32x32x16_bf16 v[0:15], v[110:113], v[114:117], v[0:15]
	s_setprio 0
	ds_read_b128 v[106:109], v89 offset:12288
	ds_read_b128 v[110:113], v90 offset:12288
	ds_read_b128 v[114:117], v92 offset:20480
	s_setprio 1
	s_waitcnt lgkmcnt(0)
	v_mfma_f32_32x32x16_bf16 v[16:31], v[106:109], v[114:117], v[16:31]
	v_mfma_f32_32x32x16_bf16 v[0:15], v[110:113], v[114:117], v[0:15]
	s_setprio 0
	s_waitcnt vmcnt(4)
	ds_write_b128 v64, v[98:101]
	ds_write_b128 v86, v[94:97]
	s_waitcnt vmcnt(3)
	ds_write_b128 v87, v[102:105] offset:8192
	s_waitcnt lgkmcnt(0)
	s_barrier
; template <int TJ>
; DI void gemm_core(const u16* __restrict__ W, int ldw, const u16* __restrict__ X, int ldx, int K, f32x16 (&acc)[2][TJ], char* lds) {
;     ...
;   G_LOAD(wA, xA, 0);
;   G_LOAD(wB, xB, 1);
;   G_STORE(wA, xA, 0);
;   __syncthreads();
;   for (int kt = 0; kt < nk; kt += 2) {
;     if (kt + 2 < nk) G_LOAD(wA, xA, kt + 2);
;     G_COMPUTE(0);
;     G_STORE(wB, xB, 1);
;     __syncthreads();
;     if (kt + 3 < nk) G_LOAD(wB, xB, kt + 3);
;     G_COMPUTE(1);
;     if (kt + 2 < nk) G_STORE(wA, xA, 0);
;     __syncthreads();
	global_load_dwordx4 v[94:97], v[82:83], off offset:768
	global_load_dwordx4 v[98:101], v[80:81], off offset:768
	global_load_dwordx4 v[102:105], v[78:79], off offset:768
	ds_read_b128 v[106:109], v88
	ds_read_b128 v[110:113], v91
	ds_read_b128 v[114:117], v93 offset:8192
	s_setprio 1
	s_waitcnt lgkmcnt(0)
	v_mfma_f32_32x32x16_bf16 v[16:31], v[106:109], v[114:117], v[16:31]
	v_mfma_f32_32x32x16_bf16 v[0:15], v[110:113], v[114:117], v[0:15]
	s_setprio 0
	ds_read_b128 v[106:109], v89
	ds_read_b128 v[110:113], v90
	ds_read_b128 v[114:117], v92 offset:8192
	s_setprio 1
	s_waitcnt lgkmcnt(0)
	v_mfma_f32_32x32x16_bf16 v[16:31], v[106:109], v[114:117], v[16:31]
	v_mfma_f32_32x32x16_bf16 v[0:15], v[110:113], v[114:117], v[0:15]
	s_setprio 0
	s_waitcnt vmcnt(4)
	ds_write_b128 v64, v[36:39] offset:12288
	ds_write_b128 v86, v[32:35] offset:12288
	s_waitcnt vmcnt(3)
	ds_write_b128 v87, v[40:43] offset:20480
	s_waitcnt lgkmcnt(0)
	s_barrier
	global_load_dwordx4 v[32:35], v[82:83], off offset:832
	global_load_dwordx4 v[36:39], v[80:81], off offset:832
	global_load_dwordx4 v[40:43], v[78:79], off offset:832
	ds_read_b128 v[106:109], v88 offset:12288
	ds_read_b128 v[110:113], v91 offset:12288
	ds_read_b128 v[114:117], v93 offset:20480
	s_setprio 1
	s_waitcnt lgkmcnt(0)
	v_mfma_f32_32x32x16_bf16 v[16:31], v[106:109], v[114:117], v[16:31]
	v_mfma_f32_32x32x16_bf16 v[0:15], v[110:113], v[114:117], v[0:15]
	s_setprio 0
	ds_read_b128 v[106:109], v89 offset:12288
	ds_read_b128 v[110:113], v90 offset:12288
	ds_read_b128 v[114:117], v92 offset:20480
	s_setprio 1
	s_waitcnt lgkmcnt(0)
	v_mfma_f32_32x32x16_bf16 v[16:31], v[106:109], v[114:117], v[16:31]
	v_mfma_f32_32x32x16_bf16 v[0:15], v[110:113], v[114:117], v[0:15]
	s_setprio 0
	s_waitcnt vmcnt(4)
	ds_write_b128 v64, v[98:101]
	ds_write_b128 v86, v[94:97]
	s_waitcnt vmcnt(3)
	ds_write_b128 v87, v[102:105] offset:8192
	s_waitcnt lgkmcnt(0)
	s_barrier
	global_load_dwordx4 v[94:97], v[82:83], off offset:896
	global_load_dwordx4 v[98:101], v[80:81], off offset:896
	global_load_dwordx4 v[102:105], v[78:79], off offset:896
	ds_read_b128 v[106:109], v88
	ds_read_b128 v[110:113], v91
	ds_read_b128 v[114:117], v93 offset:8192
	s_setprio 1
	s_waitcnt lgkmcnt(0)
	v_mfma_f32_32x32x16_bf16 v[16:31], v[106:109], v[114:117], v[16:31]
	v_mfma_f32_32x32x16_bf16 v[0:15], v[110:113], v[114:117], v[0:15]
	s_setprio 0
	ds_read_b128 v[106:109], v89
	ds_read_b128 v[110:113], v90
	ds_read_b128 v[114:117], v92 offset:8192
	s_setprio 1
	s_waitcnt lgkmcnt(0)
	v_mfma_f32_32x32x16_bf16 v[16:31], v[106:109], v[114:117], v[16:31]
	v_mfma_f32_32x32x16_bf16 v[0:15], v[110:113], v[114:117], v[0:15]
	s_setprio 0
	s_waitcnt vmcnt(4)
	ds_write_b128 v64, v[36:39] offset:12288
	ds_write_b128 v86, v[32:35] offset:12288
	s_waitcnt vmcnt(3)
	ds_write_b128 v87, v[40:43] offset:20480
	s_waitcnt lgkmcnt(0)
	s_barrier
	global_load_dwordx4 v[32:35], v[82:83], off offset:960
	global_load_dwordx4 v[36:39], v[80:81], off offset:960
	global_load_dwordx4 v[40:43], v[78:79], off offset:960
	ds_read_b128 v[106:109], v88 offset:12288
	ds_read_b128 v[110:113], v91 offset:12288
	ds_read_b128 v[114:117], v93 offset:20480
	s_setprio 1
	s_waitcnt lgkmcnt(0)
	v_mfma_f32_32x32x16_bf16 v[16:31], v[106:109], v[114:117], v[16:31]
	v_mfma_f32_32x32x16_bf16 v[0:15], v[110:113], v[114:117], v[0:15]
	s_setprio 0
	ds_read_b128 v[106:109], v89 offset:12288
	ds_read_b128 v[110:113], v90 offset:12288
	ds_read_b128 v[114:117], v92 offset:20480
	s_setprio 1
	s_waitcnt lgkmcnt(0)
	v_mfma_f32_32x32x16_bf16 v[16:31], v[106:109], v[114:117], v[16:31]
	v_mfma_f32_32x32x16_bf16 v[0:15], v[110:113], v[114:117], v[0:15]
	s_setprio 0
	s_waitcnt vmcnt(4)
	ds_write_b128 v64, v[98:101]
	ds_write_b128 v86, v[94:97]
	s_waitcnt vmcnt(3)
	ds_write_b128 v87, v[102:105] offset:8192
	s_waitcnt lgkmcnt(0)
	s_barrier
	global_load_dwordx4 v[94:97], v[82:83], off offset:1024
	global_load_dwordx4 v[98:101], v[80:81], off offset:1024
	global_load_dwordx4 v[102:105], v[78:79], off offset:1024
	ds_read_b128 v[106:109], v88
	ds_read_b128 v[110:113], v91
	ds_read_b128 v[114:117], v93 offset:8192
	s_setprio 1
	s_waitcnt lgkmcnt(0)
	v_mfma_f32_32x32x16_bf16 v[16:31], v[106:109], v[114:117], v[16:31]
	v_mfma_f32_32x32x16_bf16 v[0:15], v[110:113], v[114:117], v[0:15]
	s_setprio 0
	ds_read_b128 v[106:109], v89
	ds_read_b128 v[110:113], v90
	ds_read_b128 v[114:117], v92 offset:8192
	s_setprio 1
	s_waitcnt lgkmcnt(0)
	v_mfma_f32_32x32x16_bf16 v[16:31], v[106:109], v[114:117], v[16:31]
	v_mfma_f32_32x32x16_bf16 v[0:15], v[110:113], v[114:117], v[0:15]
	s_setprio 0
	s_waitcnt vmcnt(4)
	ds_write_b128 v64, v[36:39] offset:12288
	ds_write_b128 v86, v[32:35] offset:12288
	s_waitcnt vmcnt(3)
	ds_write_b128 v87, v[40:43] offset:20480
	s_waitcnt lgkmcnt(0)
	s_barrier
	global_load_dwordx4 v[32:35], v[82:83], off offset:1088
	global_load_dwordx4 v[36:39], v[80:81], off offset:1088
	global_load_dwordx4 v[40:43], v[78:79], off offset:1088
	ds_read_b128 v[106:109], v88 offset:12288
	ds_read_b128 v[110:113], v91 offset:12288
	ds_read_b128 v[114:117], v93 offset:20480
	s_setprio 1
	s_waitcnt lgkmcnt(0)
	v_mfma_f32_32x32x16_bf16 v[16:31], v[106:109], v[114:117], v[16:31]
	v_mfma_f32_32x32x16_bf16 v[0:15], v[110:113], v[114:117], v[0:15]
	s_setprio 0
	ds_read_b128 v[106:109], v89 offset:12288
	ds_read_b128 v[110:113], v90 offset:12288
	ds_read_b128 v[114:117], v92 offset:20480
	s_setprio 1
	s_waitcnt lgkmcnt(0)
	v_mfma_f32_32x32x16_bf16 v[16:31], v[106:109], v[114:117], v[16:31]
	v_mfma_f32_32x32x16_bf16 v[0:15], v[110:113], v[114:117], v[0:15]
	s_setprio 0
	s_waitcnt vmcnt(4)
	ds_write_b128 v64, v[98:101]
	ds_write_b128 v86, v[94:97]
	s_waitcnt vmcnt(3)
	ds_write_b128 v87, v[102:105] offset:8192
	s_waitcnt lgkmcnt(0)
	s_barrier
; template <int TJ>
; DI void gemm_core(const u16* __restrict__ W, int ldw, const u16* __restrict__ X, int ldx, int K, f32x16 (&acc)[2][TJ], char* lds) {
;     ...
;   G_LOAD(wA, xA, 0);
;   G_LOAD(wB, xB, 1);
;   G_STORE(wA, xA, 0);
;   __syncthreads();
;   for (int kt = 0; kt < nk; kt += 2) {
;     if (kt + 2 < nk) G_LOAD(wA, xA, kt + 2);
;     G_COMPUTE(0);
;     G_STORE(wB, xB, 1);
;     __syncthreads();
;     if (kt + 3 < nk) G_LOAD(wB, xB, kt + 3);
;     G_COMPUTE(1);
;     if (kt + 2 < nk) G_STORE(wA, xA, 0);
;     __syncthreads();
	global_load_dwordx4 v[94:97], v[82:83], off offset:1152
	global_load_dwordx4 v[98:101], v[80:81], off offset:1152
	global_load_dwordx4 v[102:105], v[78:79], off offset:1152
	ds_read_b128 v[106:109], v88
	ds_read_b128 v[110:113], v91
	ds_read_b128 v[114:117], v93 offset:8192
	s_setprio 1
	s_waitcnt lgkmcnt(0)
	v_mfma_f32_32x32x16_bf16 v[16:31], v[106:109], v[114:117], v[16:31]
	v_mfma_f32_32x32x16_bf16 v[0:15], v[110:113], v[114:117], v[0:15]
	s_setprio 0
	ds_read_b128 v[106:109], v89
	ds_read_b128 v[110:113], v90
	ds_read_b128 v[114:117], v92 offset:8192
	s_setprio 1
	s_waitcnt lgkmcnt(0)
	v_mfma_f32_32x32x16_bf16 v[16:31], v[106:109], v[114:117], v[16:31]
	v_mfma_f32_32x32x16_bf16 v[0:15], v[110:113], v[114:117], v[0:15]
	s_setprio 0
	s_waitcnt vmcnt(4)
	ds_write_b128 v64, v[36:39] offset:12288
	ds_write_b128 v86, v[32:35] offset:12288
	s_waitcnt vmcnt(3)
	ds_write_b128 v87, v[40:43] offset:20480
	s_waitcnt lgkmcnt(0)
	s_barrier
	global_load_dwordx4 v[32:35], v[82:83], off offset:1216
	global_load_dwordx4 v[36:39], v[80:81], off offset:1216
	global_load_dwordx4 v[40:43], v[78:79], off offset:1216
	ds_read_b128 v[106:109], v88 offset:12288
	ds_read_b128 v[110:113], v91 offset:12288
	ds_read_b128 v[114:117], v93 offset:20480
	s_setprio 1
	s_waitcnt lgkmcnt(0)
	v_mfma_f32_32x32x16_bf16 v[16:31], v[106:109], v[114:117], v[16:31]
	v_mfma_f32_32x32x16_bf16 v[0:15], v[110:113], v[114:117], v[0:15]
	s_setprio 0
	ds_read_b128 v[106:109], v89 offset:12288
	ds_read_b128 v[110:113], v90 offset:12288
	ds_read_b128 v[114:117], v92 offset:20480
	s_setprio 1
	s_waitcnt lgkmcnt(0)
	v_mfma_f32_32x32x16_bf16 v[16:31], v[106:109], v[114:117], v[16:31]
	v_mfma_f32_32x32x16_bf16 v[0:15], v[110:113], v[114:117], v[0:15]
	s_setprio 0
	s_waitcnt vmcnt(4)
	ds_write_b128 v64, v[98:101]
	ds_write_b128 v86, v[94:97]
	s_waitcnt vmcnt(3)
	ds_write_b128 v87, v[102:105] offset:8192
	s_waitcnt lgkmcnt(0)
	s_barrier
	global_load_dwordx4 v[94:97], v[82:83], off offset:1280
	global_load_dwordx4 v[98:101], v[80:81], off offset:1280
	global_load_dwordx4 v[102:105], v[78:79], off offset:1280
	ds_read_b128 v[106:109], v88
	ds_read_b128 v[110:113], v91
	ds_read_b128 v[114:117], v93 offset:8192
	s_setprio 1
	s_waitcnt lgkmcnt(0)
	v_mfma_f32_32x32x16_bf16 v[16:31], v[106:109], v[114:117], v[16:31]
	v_mfma_f32_32x32x16_bf16 v[0:15], v[110:113], v[114:117], v[0:15]
	s_setprio 0
	ds_read_b128 v[106:109], v89
	ds_read_b128 v[110:113], v90
	ds_read_b128 v[114:117], v92 offset:8192
	s_setprio 1
	s_waitcnt lgkmcnt(0)
	v_mfma_f32_32x32x16_bf16 v[16:31], v[106:109], v[114:117], v[16:31]
	v_mfma_f32_32x32x16_bf16 v[0:15], v[110:113], v[114:117], v[0:15]
	s_setprio 0
	s_waitcnt vmcnt(4)
	ds_write_b128 v64, v[36:39] offset:12288
	ds_write_b128 v86, v[32:35] offset:12288
	s_waitcnt vmcnt(3)
	ds_write_b128 v87, v[40:43] offset:20480
	s_waitcnt lgkmcnt(0)
	s_barrier
	global_load_dwordx4 v[32:35], v[82:83], off offset:1344
	global_load_dwordx4 v[36:39], v[80:81], off offset:1344
	global_load_dwordx4 v[40:43], v[78:79], off offset:1344
	ds_read_b128 v[106:109], v88 offset:12288
	ds_read_b128 v[110:113], v91 offset:12288
	ds_read_b128 v[114:117], v93 offset:20480
	s_setprio 1
	s_waitcnt lgkmcnt(0)
	v_mfma_f32_32x32x16_bf16 v[16:31], v[106:109], v[114:117], v[16:31]
	v_mfma_f32_32x32x16_bf16 v[0:15], v[110:113], v[114:117], v[0:15]
	s_setprio 0
	ds_read_b128 v[106:109], v89 offset:12288
	ds_read_b128 v[110:113], v90 offset:12288
	ds_read_b128 v[114:117], v92 offset:20480
	s_setprio 1
	s_waitcnt lgkmcnt(0)
	v_mfma_f32_32x32x16_bf16 v[16:31], v[106:109], v[114:117], v[16:31]
	v_mfma_f32_32x32x16_bf16 v[0:15], v[110:113], v[114:117], v[0:15]
	s_setprio 0
	s_waitcnt vmcnt(4)
	ds_write_b128 v64, v[98:101]
	ds_write_b128 v86, v[94:97]
	s_waitcnt vmcnt(3)
	ds_write_b128 v87, v[102:105] offset:8192
	s_waitcnt lgkmcnt(0)
	s_barrier
	global_load_dwordx4 v[94:97], v[82:83], off offset:1408
	global_load_dwordx4 v[98:101], v[80:81], off offset:1408
	global_load_dwordx4 v[102:105], v[78:79], off offset:1408
	ds_read_b128 v[106:109], v88
	ds_read_b128 v[110:113], v91
	ds_read_b128 v[114:117], v93 offset:8192
	s_setprio 1
	s_waitcnt lgkmcnt(0)
	v_mfma_f32_32x32x16_bf16 v[16:31], v[106:109], v[114:117], v[16:31]
	v_mfma_f32_32x32x16_bf16 v[0:15], v[110:113], v[114:117], v[0:15]
	s_setprio 0
	ds_read_b128 v[106:109], v89
	ds_read_b128 v[110:113], v90
	ds_read_b128 v[114:117], v92 offset:8192
	s_setprio 1
	s_waitcnt lgkmcnt(0)
	v_mfma_f32_32x32x16_bf16 v[16:31], v[106:109], v[114:117], v[16:31]
	v_mfma_f32_32x32x16_bf16 v[0:15], v[110:113], v[114:117], v[0:15]
	s_setprio 0
	s_waitcnt vmcnt(4)
	ds_write_b128 v64, v[36:39] offset:12288
	ds_write_b128 v86, v[32:35] offset:12288
	s_waitcnt vmcnt(3)
	ds_write_b128 v87, v[40:43] offset:20480
	s_waitcnt lgkmcnt(0)
	s_barrier
	global_load_dwordx4 v[32:35], v[82:83], off offset:1472
	global_load_dwordx4 v[36:39], v[80:81], off offset:1472
	global_load_dwordx4 v[40:43], v[78:79], off offset:1472
	ds_read_b128 v[106:109], v88 offset:12288
	ds_read_b128 v[110:113], v91 offset:12288
	ds_read_b128 v[114:117], v93 offset:20480
	s_setprio 1
	s_waitcnt lgkmcnt(0)
	v_mfma_f32_32x32x16_bf16 v[16:31], v[106:109], v[114:117], v[16:31]
	v_mfma_f32_32x32x16_bf16 v[0:15], v[110:113], v[114:117], v[0:15]
	s_setprio 0
	ds_read_b128 v[106:109], v89 offset:12288
	ds_read_b128 v[110:113], v90 offset:12288
	ds_read_b128 v[114:117], v92 offset:20480
	s_setprio 1
	s_waitcnt lgkmcnt(0)
	v_mfma_f32_32x32x16_bf16 v[16:31], v[106:109], v[114:117], v[16:31]
	v_mfma_f32_32x32x16_bf16 v[0:15], v[110:113], v[114:117], v[0:15]
	s_setprio 0
	s_waitcnt vmcnt(4)
	ds_write_b128 v64, v[98:101]
	ds_write_b128 v86, v[94:97]
	s_waitcnt vmcnt(3)
	ds_write_b128 v87, v[102:105] offset:8192
	s_waitcnt lgkmcnt(0)
	s_barrier
; template <int TJ>
; DI void gemm_core(const u16* __restrict__ W, int ldw, const u16* __restrict__ X, int ldx, int K, f32x16 (&acc)[2][TJ], char* lds) {
;     ...
;   G_LOAD(wA, xA, 0);
;   G_LOAD(wB, xB, 1);
;   G_STORE(wA, xA, 0);
;   __syncthreads();
;   for (int kt = 0; kt < nk; kt += 2) {
;     if (kt + 2 < nk) G_LOAD(wA, xA, kt + 2);
;     G_COMPUTE(0);
;     G_STORE(wB, xB, 1);
;     __syncthreads();
;     if (kt + 3 < nk) G_LOAD(wB, xB, kt + 3);
;     G_COMPUTE(1);
;     if (kt + 2 < nk) G_STORE(wA, xA, 0);
;     __syncthreads();
	global_load_dwordx4 v[94:97], v[82:83], off offset:1536
	global_load_dwordx4 v[98:101], v[80:81], off offset:1536
	global_load_dwordx4 v[102:105], v[78:79], off offset:1536
	ds_read_b128 v[106:109], v88
	ds_read_b128 v[110:113], v91
	ds_read_b128 v[114:117], v93 offset:8192
	s_setprio 1
	s_waitcnt lgkmcnt(0)
	v_mfma_f32_32x32x16_bf16 v[16:31], v[106:109], v[114:117], v[16:31]
	v_mfma_f32_32x32x16_bf16 v[0:15], v[110:113], v[114:117], v[0:15]
	s_setprio 0
	ds_read_b128 v[106:109], v89
	ds_read_b128 v[110:113], v90
	ds_read_b128 v[114:117], v92 offset:8192
	s_setprio 1
	s_waitcnt lgkmcnt(0)
	v_mfma_f32_32x32x16_bf16 v[16:31], v[106:109], v[114:117], v[16:31]
	v_mfma_f32_32x32x16_bf16 v[0:15], v[110:113], v[114:117], v[0:15]
	s_setprio 0
	s_waitcnt vmcnt(4)
	ds_write_b128 v64, v[36:39] offset:12288
	ds_write_b128 v86, v[32:35] offset:12288
	s_waitcnt vmcnt(3)
	ds_write_b128 v87, v[40:43] offset:20480
	s_waitcnt lgkmcnt(0)
	s_barrier
	global_load_dwordx4 v[32:35], v[82:83], off offset:1600
	global_load_dwordx4 v[36:39], v[80:81], off offset:1600
	global_load_dwordx4 v[40:43], v[78:79], off offset:1600
	ds_read_b128 v[106:109], v88 offset:12288
	ds_read_b128 v[110:113], v91 offset:12288
	ds_read_b128 v[114:117], v93 offset:20480
	s_setprio 1
	s_waitcnt lgkmcnt(0)
	v_mfma_f32_32x32x16_bf16 v[16:31], v[106:109], v[114:117], v[16:31]
	v_mfma_f32_32x32x16_bf16 v[0:15], v[110:113], v[114:117], v[0:15]
	s_setprio 0
	ds_read_b128 v[106:109], v89 offset:12288
	ds_read_b128 v[110:113], v90 offset:12288
	ds_read_b128 v[114:117], v92 offset:20480
	s_setprio 1
	s_waitcnt lgkmcnt(0)
	v_mfma_f32_32x32x16_bf16 v[16:31], v[106:109], v[114:117], v[16:31]
	v_mfma_f32_32x32x16_bf16 v[0:15], v[110:113], v[114:117], v[0:15]
	s_setprio 0
	s_waitcnt vmcnt(4)
	ds_write_b128 v64, v[98:101]
	ds_write_b128 v86, v[94:97]
	s_waitcnt vmcnt(3)
	ds_write_b128 v87, v[102:105] offset:8192
	s_waitcnt lgkmcnt(0)
	s_barrier
	global_load_dwordx4 v[94:97], v[82:83], off offset:1664
	global_load_dwordx4 v[98:101], v[80:81], off offset:1664
	global_load_dwordx4 v[102:105], v[78:79], off offset:1664
	ds_read_b128 v[106:109], v88
	ds_read_b128 v[110:113], v91
	ds_read_b128 v[114:117], v93 offset:8192
	s_setprio 1
	s_waitcnt lgkmcnt(0)
	v_mfma_f32_32x32x16_bf16 v[16:31], v[106:109], v[114:117], v[16:31]
	v_mfma_f32_32x32x16_bf16 v[0:15], v[110:113], v[114:117], v[0:15]
	s_setprio 0
	ds_read_b128 v[106:109], v89
	ds_read_b128 v[110:113], v90
	ds_read_b128 v[114:117], v92 offset:8192
	s_setprio 1
	s_waitcnt lgkmcnt(0)
	v_mfma_f32_32x32x16_bf16 v[16:31], v[106:109], v[114:117], v[16:31]
	v_mfma_f32_32x32x16_bf16 v[0:15], v[110:113], v[114:117], v[0:15]
	s_setprio 0
	s_waitcnt vmcnt(4)
	ds_write_b128 v64, v[36:39] offset:12288
	ds_write_b128 v86, v[32:35] offset:12288
	s_waitcnt vmcnt(3)
	ds_write_b128 v87, v[40:43] offset:20480
	s_waitcnt lgkmcnt(0)
	s_barrier
	global_load_dwordx4 v[32:35], v[82:83], off offset:1728
	global_load_dwordx4 v[36:39], v[80:81], off offset:1728
	global_load_dwordx4 v[40:43], v[78:79], off offset:1728
	ds_read_b128 v[106:109], v88 offset:12288
	ds_read_b128 v[110:113], v91 offset:12288
	ds_read_b128 v[114:117], v93 offset:20480
	s_setprio 1
	s_waitcnt lgkmcnt(0)
	v_mfma_f32_32x32x16_bf16 v[16:31], v[106:109], v[114:117], v[16:31]
	v_mfma_f32_32x32x16_bf16 v[0:15], v[110:113], v[114:117], v[0:15]
	s_setprio 0
	ds_read_b128 v[106:109], v89 offset:12288
	ds_read_b128 v[110:113], v90 offset:12288
	ds_read_b128 v[114:117], v92 offset:20480
	s_setprio 1
	s_waitcnt lgkmcnt(0)
	v_mfma_f32_32x32x16_bf16 v[16:31], v[106:109], v[114:117], v[16:31]
	v_mfma_f32_32x32x16_bf16 v[0:15], v[110:113], v[114:117], v[0:15]
	s_setprio 0
	s_waitcnt vmcnt(4)
	ds_write_b128 v64, v[98:101]
	ds_write_b128 v86, v[94:97]
	s_waitcnt vmcnt(3)
	ds_write_b128 v87, v[102:105] offset:8192
	s_waitcnt lgkmcnt(0)
	s_barrier
	global_load_dwordx4 v[94:97], v[82:83], off offset:1792
	global_load_dwordx4 v[98:101], v[80:81], off offset:1792
	global_load_dwordx4 v[102:105], v[78:79], off offset:1792
	ds_read_b128 v[106:109], v88
	ds_read_b128 v[110:113], v91
	ds_read_b128 v[114:117], v93 offset:8192
	s_setprio 1
	s_waitcnt lgkmcnt(0)
	v_mfma_f32_32x32x16_bf16 v[16:31], v[106:109], v[114:117], v[16:31]
	v_mfma_f32_32x32x16_bf16 v[0:15], v[110:113], v[114:117], v[0:15]
	s_setprio 0
	ds_read_b128 v[106:109], v89
	ds_read_b128 v[110:113], v90
	ds_read_b128 v[114:117], v92 offset:8192
	s_setprio 1
	s_waitcnt lgkmcnt(0)
	v_mfma_f32_32x32x16_bf16 v[16:31], v[106:109], v[114:117], v[16:31]
	v_mfma_f32_32x32x16_bf16 v[0:15], v[110:113], v[114:117], v[0:15]
	s_setprio 0
	s_waitcnt vmcnt(4)
	ds_write_b128 v64, v[36:39] offset:12288
	ds_write_b128 v86, v[32:35] offset:12288
	s_waitcnt vmcnt(3)
	ds_write_b128 v87, v[40:43] offset:20480
	s_waitcnt lgkmcnt(0)
	s_barrier
	global_load_dwordx4 v[32:35], v[82:83], off offset:1856
	global_load_dwordx4 v[36:39], v[80:81], off offset:1856
	global_load_dwordx4 v[40:43], v[78:79], off offset:1856
	ds_read_b128 v[106:109], v88 offset:12288
	ds_read_b128 v[110:113], v91 offset:12288
	ds_read_b128 v[114:117], v93 offset:20480
	s_setprio 1
	s_waitcnt lgkmcnt(0)
	v_mfma_f32_32x32x16_bf16 v[16:31], v[106:109], v[114:117], v[16:31]
	v_mfma_f32_32x32x16_bf16 v[0:15], v[110:113], v[114:117], v[0:15]
	s_setprio 0
	ds_read_b128 v[106:109], v89 offset:12288
	ds_read_b128 v[110:113], v90 offset:12288
	ds_read_b128 v[114:117], v92 offset:20480
	s_setprio 1
	s_waitcnt lgkmcnt(0)
	v_mfma_f32_32x32x16_bf16 v[16:31], v[106:109], v[114:117], v[16:31]
	v_mfma_f32_32x32x16_bf16 v[0:15], v[110:113], v[114:117], v[0:15]
	s_setprio 0
	s_waitcnt vmcnt(4)
	ds_write_b128 v64, v[98:101]
	ds_write_b128 v86, v[94:97]
	s_waitcnt vmcnt(3)
	ds_write_b128 v87, v[102:105] offset:8192
	s_waitcnt lgkmcnt(0)
	s_barrier
; DI unsigned cvtpk(float lo, float hi) { f32x2_t v = {lo, hi}; bf16x2_t b = __builtin_convertvector(v, bf16x2_t); return __builtin_bit_cast(unsigned, b); }
; DI float sigmoidf_(float x) { return __builtin_amdgcn_rcpf(1.f + __expf(-x)); }
; template <int TJ>
; DI void gemm_core(const u16* __restrict__ W, int ldw, const u16* __restrict__ X, int ldx, int K, f32x16 (&acc)[2][TJ], char* lds) {
;     ...
;   G_LOAD(wA, xA, 0);
;   G_LOAD(wB, xB, 1);
;   G_STORE(wA, xA, 0);
;   __syncthreads();
;   for (int kt = 0; kt < nk; kt += 2) {
;     if (kt + 2 < nk) G_LOAD(wA, xA, kt + 2);
;     G_COMPUTE(0);
;     G_STORE(wB, xB, 1);
;     __syncthreads();
;     if (kt + 3 < nk) G_LOAD(wB, xB, kt + 3);
;     G_COMPUTE(1);
;     if (kt + 2 < nk) G_STORE(wA, xA, 0);
;     __syncthreads();
;   }
; template <int TJ>
; DI void merge_tile(const Params& p, size_t t0, int nt, char* lds) {
;     ...
;     unsigned* sgl = (unsigned*)(lds + 32768) + tid;
; #pragma unroll
;     for (int i = 0; i < 2; ++i)
; #pragma unroll
;       for (int j = 0; j < TJ; ++j)
; #pragma unroll
;         for (int e = 0; e < 8; ++e) sgl[((i * TJ + j) * 8 + e) * 256] = cvtpk(sigmoidf_(ag[i][j][2 * e]), sigmoidf_(ag[i][j][2 * e + 1]));
	global_load_dwordx4 v[94:97], v[82:83], off offset:1920
	global_load_dwordx4 v[98:101], v[80:81], off offset:1920
	global_load_dwordx4 v[102:105], v[78:79], off offset:1920
	ds_read_b128 v[106:109], v88
	ds_read_b128 v[110:113], v91
	ds_read_b128 v[114:117], v93 offset:8192
	s_setprio 1
	s_waitcnt lgkmcnt(0)
	v_mfma_f32_32x32x16_bf16 v[16:31], v[106:109], v[114:117], v[16:31]
	v_mfma_f32_32x32x16_bf16 v[0:15], v[110:113], v[114:117], v[0:15]
	s_setprio 0
	ds_read_b128 v[106:109], v89
	ds_read_b128 v[110:113], v90
	ds_read_b128 v[114:117], v92 offset:8192
	s_setprio 1
	s_waitcnt lgkmcnt(0)
	v_mfma_f32_32x32x16_bf16 v[16:31], v[106:109], v[114:117], v[16:31]
	v_mfma_f32_32x32x16_bf16 v[0:15], v[110:113], v[114:117], v[0:15]
	s_setprio 0
	s_waitcnt vmcnt(4)
	ds_write_b128 v64, v[36:39] offset:12288
	ds_write_b128 v86, v[32:35] offset:12288
	s_waitcnt vmcnt(3)
	ds_write_b128 v87, v[40:43] offset:20480
	s_waitcnt lgkmcnt(0)
	s_barrier
	global_load_dwordx4 v[32:35], v[82:83], off offset:1984
	global_load_dwordx4 v[36:39], v[80:81], off offset:1984
	global_load_dwordx4 v[40:43], v[78:79], off offset:1984
	ds_read_b128 v[78:81], v88 offset:12288
	ds_read_b128 v[106:109], v91 offset:12288
	ds_read_b128 v[110:113], v93 offset:20480
	s_setprio 1
	s_waitcnt lgkmcnt(0)
	v_mfma_f32_32x32x16_bf16 v[16:31], v[78:81], v[110:113], v[16:31]
	v_mfma_f32_32x32x16_bf16 v[0:15], v[106:109], v[110:113], v[0:15]
	s_setprio 0
	ds_read_b128 v[78:81], v89 offset:12288
	ds_read_b128 v[106:109], v90 offset:12288
	ds_read_b128 v[110:113], v92 offset:20480
	s_setprio 1
	s_waitcnt lgkmcnt(0)
	v_mfma_f32_32x32x16_bf16 v[16:31], v[78:81], v[110:113], v[16:31]
	v_mfma_f32_32x32x16_bf16 v[0:15], v[106:109], v[110:113], v[0:15]
	s_setprio 0
	s_waitcnt vmcnt(4)
	ds_write_b128 v64, v[98:101]
	ds_write_b128 v86, v[94:97]
	s_waitcnt vmcnt(3)
	ds_write_b128 v87, v[102:105] offset:8192
	s_waitcnt lgkmcnt(0)
	s_barrier
	ds_read_b128 v[78:81], v88
	ds_read_b128 v[94:97], v91
	ds_read_b128 v[98:101], v93 offset:8192
	s_setprio 1
	s_waitcnt lgkmcnt(0)
	v_mfma_f32_32x32x16_bf16 v[16:31], v[78:81], v[98:101], v[16:31]
	v_mfma_f32_32x32x16_bf16 v[0:15], v[94:97], v[98:101], v[0:15]
	s_setprio 0
	ds_read_b128 v[78:81], v89
	ds_read_b128 v[94:97], v90
	ds_read_b128 v[98:101], v92 offset:8192
	s_setprio 1
	s_waitcnt lgkmcnt(0)
	v_mfma_f32_32x32x16_bf16 v[16:31], v[78:81], v[98:101], v[16:31]
	v_mfma_f32_32x32x16_bf16 v[0:15], v[94:97], v[98:101], v[0:15]
	s_setprio 0
	s_waitcnt vmcnt(1)
	ds_write_b128 v64, v[36:39] offset:12288
	ds_write_b128 v86, v[32:35] offset:12288
	s_waitcnt vmcnt(0)
	ds_write_b128 v87, v[40:43] offset:20480
	s_waitcnt lgkmcnt(0)
	s_barrier
	ds_read_b128 v[32:35], v88 offset:12288
	ds_read_b128 v[36:39], v91 offset:12288
	ds_read_b128 v[40:43], v93 offset:20480
	s_setprio 1
	s_waitcnt lgkmcnt(0)
	v_mfma_f32_32x32x16_bf16 v[16:31], v[32:35], v[40:43], v[16:31]
	v_mfma_f32_32x32x16_bf16 v[0:15], v[36:39], v[40:43], v[0:15]
	s_setprio 0
	ds_read_b128 v[32:35], v89 offset:12288
	ds_read_b128 v[36:39], v90 offset:12288
	ds_read_b128 v[40:43], v92 offset:20480
	s_setprio 1
	s_waitcnt lgkmcnt(0)
	v_mfma_f32_32x32x16_bf16 v[16:31], v[32:35], v[40:43], v[16:31]
	v_mfma_f32_32x32x16_bf16 v[0:15], v[36:39], v[40:43], v[0:15]
	s_setprio 0
	s_nop 9
	v_mul_f32_e32 v16, 0xbfb8aa3b, v16
	v_mul_f32_e32 v17, 0xbfb8aa3b, v17
	v_mul_f32_e32 v0, 0xbfb8aa3b, v0
	v_mul_f32_e32 v1, 0xbfb8aa3b, v1
	v_exp_f32_e32 v16, v16
	v_exp_f32_e32 v17, v17
	v_exp_f32_e32 v0, v0
	v_exp_f32_e32 v1, v1
	v_add_f32_e32 v16, 1.0, v16
	v_add_f32_e32 v17, 1.0, v17
	v_add_f32_e32 v0, 1.0, v0
	v_add_f32_e32 v1, 1.0, v1
	v_rcp_f32_e32 v16, v16
	v_rcp_f32_e32 v17, v17
	v_rcp_f32_e32 v0, v0
	v_rcp_f32_e32 v1, v1
	v_cvt_pk_bf16_f32 v16, v16, v17
	v_mul_f32_e32 v17, 0xbfb8aa3b, v18
	v_mul_f32_e32 v18, 0xbfb8aa3b, v19
	v_cvt_pk_bf16_f32 v0, v0, v1
	v_mul_f32_e32 v1, 0xbfb8aa3b, v2
	v_mul_f32_e32 v2, 0xbfb8aa3b, v3
	v_exp_f32_e32 v17, v17
	v_exp_f32_e32 v18, v18
	v_exp_f32_e32 v1, v1
	v_exp_f32_e32 v2, v2
	v_add_f32_e32 v17, 1.0, v17
	v_add_f32_e32 v18, 1.0, v18
	v_add_f32_e32 v1, 1.0, v1
	v_add_f32_e32 v2, 1.0, v2
	v_rcp_f32_e32 v17, v17
	v_rcp_f32_e32 v18, v18
	v_rcp_f32_e32 v1, v1
	v_rcp_f32_e32 v2, v2
	s_barrier
	v_cvt_pk_bf16_f32 v17, v17, v18
	v_cvt_pk_bf16_f32 v1, v1, v2
	ds_write2st64_b32 v85, v16, v17 offset0:128 offset1:132
	v_mul_f32_e32 v16, 0xbfb8aa3b, v20
	v_mul_f32_e32 v17, 0xbfb8aa3b, v21
	ds_write2st64_b32 v85, v0, v1 offset0:160 offset1:164
	v_mul_f32_e32 v0, 0xbfb8aa3b, v4
	v_mul_f32_e32 v1, 0xbfb8aa3b, v5
	v_exp_f32_e32 v16, v16
	v_exp_f32_e32 v17, v17
	v_exp_f32_e32 v0, v0
	v_exp_f32_e32 v1, v1
	v_add_f32_e32 v16, 1.0, v16
	v_add_f32_e32 v17, 1.0, v17
	v_add_f32_e32 v0, 1.0, v0
	v_add_f32_e32 v1, 1.0, v1
	v_rcp_f32_e32 v16, v16
	v_rcp_f32_e32 v17, v17
	v_rcp_f32_e32 v0, v0
	v_rcp_f32_e32 v1, v1
	v_mul_f32_e32 v18, 0xbfb8aa3b, v23
	v_cvt_pk_bf16_f32 v16, v16, v17
	v_mul_f32_e32 v17, 0xbfb8aa3b, v22
	v_cvt_pk_bf16_f32 v0, v0, v1
	v_mul_f32_e32 v1, 0xbfb8aa3b, v6
	v_mul_f32_e32 v2, 0xbfb8aa3b, v7
	v_exp_f32_e32 v17, v17
	v_exp_f32_e32 v18, v18
	v_exp_f32_e32 v1, v1
	v_exp_f32_e32 v2, v2
	v_add_f32_e32 v17, 1.0, v17
	v_add_f32_e32 v18, 1.0, v18
	v_add_f32_e32 v1, 1.0, v1
	v_add_f32_e32 v2, 1.0, v2
	v_rcp_f32_e32 v17, v17
	v_rcp_f32_e32 v18, v18
	v_rcp_f32_e32 v1, v1
	v_rcp_f32_e32 v2, v2
	s_lshl_b64 s[0:1], s[0:1], 1
	v_cvt_pk_bf16_f32 v17, v17, v18
	ds_write2st64_b32 v85, v16, v17 offset0:136 offset1:140
	v_cvt_pk_bf16_f32 v1, v1, v2
	v_mul_f32_e32 v16, 0xbfb8aa3b, v24
	v_mul_f32_e32 v17, 0xbfb8aa3b, v25
	ds_write2st64_b32 v85, v0, v1 offset0:168 offset1:172
	v_mul_f32_e32 v0, 0xbfb8aa3b, v8
; DI int otid() { int t = threadIdx.x; asm volatile("" : "+v"(t)); return t; }
; DI unsigned cvtpk(float lo, float hi) { f32x2_t v = {lo, hi}; bf16x2_t b = __builtin_convertvector(v, bf16x2_t); return __builtin_bit_cast(unsigned, b); }
; DI float sigmoidf_(float x) { return __builtin_amdgcn_rcpf(1.f + __expf(-x)); }
; template <int TJ>
; DI void gemm_core(const u16* __restrict__ W, int ldw, const u16* __restrict__ X, int ldx, int K, f32x16 (&acc)[2][TJ], char* lds) {
;   constexpr int XR = 64 * TJ;
;   constexpr int WBYTES = 128 * 64, XBYTES = XR * 64, STAGE = WBYTES + XBYTES;
;   const int tid = otid(), lane = tid & 63, wid = tid >> 6, r = lane & 31, h = lane >> 5;
;   const int wn = wid & 1, wt = wid >> 1;
;   u32x4 wA[2], xA[TJ], wB[2], xB[TJ];
;   const int lrow = tid >> 2, lch = tid & 3;
;   const u16* wp = W + (size_t)lrow * ldw + lch * 8;
;   const u16* xp = X + (size_t)lrow * ldx + lch * 8;
;   const int nk = K / 32;
;     ...
;   G_LOAD(wA, xA, 0);
;   G_LOAD(wB, xB, 1);
;   G_STORE(wA, xA, 0);
;   __syncthreads();
; template <int TJ>
; DI void merge_tile(const Params& p, size_t t0, int nt, char* lds) {
;     ...
;     unsigned* sgl = (unsigned*)(lds + 32768) + tid;
; #pragma unroll
;     for (int i = 0; i < 2; ++i)
; #pragma unroll
;       for (int j = 0; j < TJ; ++j)
; #pragma unroll
;         for (int e = 0; e < 8; ++e) sgl[((i * TJ + j) * 8 + e) * 256] = cvtpk(sigmoidf_(ag[i][j][2 * e]), sigmoidf_(ag[i][j][2 * e + 1]));
	v_mul_f32_e32 v1, 0xbfb8aa3b, v9
	v_exp_f32_e32 v16, v16
	v_exp_f32_e32 v17, v17
	v_exp_f32_e32 v0, v0
	v_exp_f32_e32 v1, v1
	v_add_f32_e32 v16, 1.0, v16
	v_add_f32_e32 v17, 1.0, v17
	v_add_f32_e32 v0, 1.0, v0
	v_add_f32_e32 v1, 1.0, v1
	v_rcp_f32_e32 v16, v16
	v_rcp_f32_e32 v17, v17
	v_rcp_f32_e32 v0, v0
	v_rcp_f32_e32 v1, v1
	v_mul_f32_e32 v18, 0xbfb8aa3b, v27
	v_cvt_pk_bf16_f32 v16, v16, v17
	v_mul_f32_e32 v17, 0xbfb8aa3b, v26
	v_cvt_pk_bf16_f32 v0, v0, v1
	v_mul_f32_e32 v1, 0xbfb8aa3b, v10
	v_mul_f32_e32 v2, 0xbfb8aa3b, v11
	v_exp_f32_e32 v17, v17
	v_exp_f32_e32 v18, v18
	v_exp_f32_e32 v1, v1
	v_exp_f32_e32 v2, v2
	v_add_f32_e32 v17, 1.0, v17
	v_add_f32_e32 v18, 1.0, v18
	v_add_f32_e32 v1, 1.0, v1
	v_add_f32_e32 v2, 1.0, v2
	v_rcp_f32_e32 v17, v17
	v_rcp_f32_e32 v18, v18
	v_rcp_f32_e32 v1, v1
	v_rcp_f32_e32 v2, v2
	s_add_u32 s0, s47, s0
	v_cvt_pk_bf16_f32 v17, v17, v18
	ds_write2st64_b32 v85, v16, v17 offset0:144 offset1:148
	v_cvt_pk_bf16_f32 v1, v1, v2
	v_mul_f32_e32 v16, 0xbfb8aa3b, v28
	v_mul_f32_e32 v17, 0xbfb8aa3b, v29
	ds_write2st64_b32 v85, v0, v1 offset0:176 offset1:180
	v_mul_f32_e32 v0, 0xbfb8aa3b, v12
	v_mul_f32_e32 v1, 0xbfb8aa3b, v13
	v_exp_f32_e32 v16, v16
	v_exp_f32_e32 v17, v17
	v_exp_f32_e32 v0, v0
	v_exp_f32_e32 v1, v1
	v_add_f32_e32 v16, 1.0, v16
	v_add_f32_e32 v17, 1.0, v17
	v_add_f32_e32 v0, 1.0, v0
	v_add_f32_e32 v1, 1.0, v1
	v_rcp_f32_e32 v16, v16
	v_rcp_f32_e32 v17, v17
	v_rcp_f32_e32 v0, v0
	v_rcp_f32_e32 v1, v1
	v_mul_f32_e32 v18, 0xbfb8aa3b, v31
	v_cvt_pk_bf16_f32 v16, v16, v17
	v_mul_f32_e32 v17, 0xbfb8aa3b, v30
	v_cvt_pk_bf16_f32 v0, v0, v1
	v_mul_f32_e32 v1, 0xbfb8aa3b, v14
	v_mul_f32_e32 v2, 0xbfb8aa3b, v15
	v_exp_f32_e32 v17, v17
	v_exp_f32_e32 v18, v18
	v_exp_f32_e32 v1, v1
	v_exp_f32_e32 v2, v2
	v_add_f32_e32 v17, 1.0, v17
	v_add_f32_e32 v18, 1.0, v18
	v_add_f32_e32 v1, 1.0, v1
	v_add_f32_e32 v2, 1.0, v2
	v_rcp_f32_e32 v17, v17
	v_rcp_f32_e32 v18, v18
	v_rcp_f32_e32 v1, v1
	v_rcp_f32_e32 v2, v2
	v_mov_b32_e32 v14, v190
	v_cvt_pk_bf16_f32 v17, v17, v18
	ds_write2st64_b32 v85, v16, v17 offset0:152 offset1:156
	v_cvt_pk_bf16_f32 v1, v1, v2
	ds_write2st64_b32 v85, v0, v1 offset0:184 offset1:188
	s_addc_u32 s1, s48, s1
	v_ashrrev_i32_e32 v12, 2, v14
	v_and_b32_e32 v15, 3, v14
	v_ashrrev_i32_e32 v13, 31, v12
	v_lshlrev_b64 v[0:1], 10, v[12:13]
	v_lshlrev_b32_e32 v64, 4, v15
	s_add_u32 s42, s22, s40
	v_or_b32_e32 v0, v0, v64
	s_addc_u32 s43, s23, s41
	v_lshl_add_u64 v[4:5], s[42:43], 0, v[0:1]
	v_mov_b64_e32 v[0:1], s[0:1]
	v_mad_i64_i32 v[0:1], s[0:1], v12, s89, v[0:1]
	s_mov_b32 s0, 0x1d520000
	s_nop 0
	v_add_co_u32_e32 v34, vcc, s0, v4
	v_lshl_add_u64 v[32:33], v[0:1], 0, v[64:65]
	s_nop 0
	v_addc_co_u32_e32 v35, vcc, 0, v5, vcc
	global_load_dwordx4 v[0:3], v[34:35], off
	s_mov_b32 s0, 0x1d530000
	v_add_co_u32_e32 v36, vcc, s0, v4
	v_lshlrev_b32_e32 v17, 5, v15
	s_nop 0
	v_addc_co_u32_e32 v37, vcc, 0, v5, vcc
	global_load_dwordx4 v[4:7], v[36:37], off
	global_load_dwordx4 v[8:11], v[32:33], off
	global_load_dwordx4 v[80:83], v[34:35], off offset:64
	global_load_dwordx4 v[86:89], v[36:37], off offset:64
	v_lshlrev_b32_e32 v12, 4, v12
	v_lshlrev_b32_e32 v16, 11, v15
	v_xor_b32_e32 v18, v12, v17
	v_add_u32_e32 v38, v16, v18
	global_load_dwordx4 v[90:93], v[32:33], off offset:64
	v_bfe_u32 v13, v14, 5, 1
	s_waitcnt vmcnt(5)
	ds_write_b128 v38, v[0:3]
	v_add_u32_e32 v0, 0x400, v12
	v_xad_u32 v39, v0, v17, v16
	v_lshlrev_b32_e32 v0, 10, v15
	v_sub_u32_e32 v0, v16, v0
	v_add_u32_e32 v40, v0, v18
	s_waitcnt vmcnt(4)
	ds_write_b128 v39, v[4:7]
	s_waitcnt vmcnt(3)
	ds_write_b128 v40, v[8:11] offset:8192
	s_waitcnt lgkmcnt(0)
	s_barrier
	global_load_dwordx4 v[94:97], v[34:35], off offset:128
	global_load_dwordx4 v[98:101], v[36:37], off offset:128
	global_load_dwordx4 v[102:105], v[32:33], off offset:128
	v_lshlrev_b32_e32 v1, 4, v14
	v_lshlrev_b32_e32 v0, 2, v14
	v_and_b32_e32 v2, 0x1f0, v1
	v_and_b32_e32 v1, 0x5f0, v1
	v_and_or_b32 v0, v0, s18, v2
	v_lshlrev_b32_e32 v2, 11, v13
	v_lshlrev_b32_e32 v3, 5, v13
	v_or_b32_e32 v4, 0x200, v1
	v_lshlrev_b32_e32 v5, 10, v13
	v_bitop3_b32 v41, v2, v3, v1 bitop3:0xf6
	v_bitop3_b32 v64, v2, v4, v3 bitop3:0xf6
	v_sub_u32_e32 v2, v2, v5
	v_xad_u32 v79, v3, v0, v2
	v_or_b32_e32 v2, 2, v13
	v_lshlrev_b32_e32 v3, 11, v2
	v_lshlrev_b32_e32 v5, 5, v2
	v_bitop3_b32 v42, v3, v5, v1 bitop3:0xf6
	v_lshlrev_b32_e32 v1, 10, v2
	v_sub_u32_e32 v1, v3, v1
	v_bitop3_b32 v43, v3, v5, v4 bitop3:0xf6
	v_xad_u32 v78, v5, v0, v1
	ds_read_b128 v[0:3], v41
	ds_read_b128 v[4:7], v64
	ds_read_b128 v[8:11], v79 offset:8192
	s_setprio 1
	s_waitcnt lgkmcnt(0)
	v_mfma_f32_32x32x16_bf16 v[16:31], v[0:3], v[8:11], 0
	v_mfma_f32_32x32x16_bf16 v[0:15], v[4:7], v[8:11], 0
	s_setprio 0
	ds_read_b128 v[106:109], v42
	ds_read_b128 v[110:113], v43
	ds_read_b128 v[114:117], v78 offset:8192
	s_setprio 1
	s_waitcnt lgkmcnt(0)
	v_mfma_f32_32x32x16_bf16 v[16:31], v[106:109], v[114:117], v[16:31]
	v_mfma_f32_32x32x16_bf16 v[0:15], v[110:113], v[114:117], v[0:15]
	s_setprio 0
	s_waitcnt vmcnt(5)
	ds_write_b128 v38, v[80:83] offset:12288
	s_waitcnt vmcnt(4)
	ds_write_b128 v39, v[86:89] offset:12288
	s_waitcnt vmcnt(3)
	ds_write_b128 v40, v[90:93] offset:20480
	s_waitcnt lgkmcnt(0)
	s_barrier
; template <int TJ>
; DI void gemm_core(const u16* __restrict__ W, int ldw, const u16* __restrict__ X, int ldx, int K, f32x16 (&acc)[2][TJ], char* lds) {
;     ...
;   G_LOAD(wA, xA, 0);
;   G_LOAD(wB, xB, 1);
;   G_STORE(wA, xA, 0);
;   __syncthreads();
;   for (int kt = 0; kt < nk; kt += 2) {
;     if (kt + 2 < nk) G_LOAD(wA, xA, kt + 2);
;     G_COMPUTE(0);
;     G_STORE(wB, xB, 1);
;     __syncthreads();
;     if (kt + 3 < nk) G_LOAD(wB, xB, kt + 3);
;     G_COMPUTE(1);
;     if (kt + 2 < nk) G_STORE(wA, xA, 0);
;     __syncthreads();
	global_load_dwordx4 v[80:83], v[36:37], off offset:192
	global_load_dwordx4 v[86:89], v[34:35], off offset:192
	global_load_dwordx4 v[90:93], v[32:33], off offset:192
	ds_read_b128 v[106:109], v41 offset:12288
	ds_read_b128 v[110:113], v64 offset:12288
	ds_read_b128 v[114:117], v79 offset:20480
	s_setprio 1
	s_waitcnt lgkmcnt(0)
	v_mfma_f32_32x32x16_bf16 v[16:31], v[106:109], v[114:117], v[16:31]
	v_mfma_f32_32x32x16_bf16 v[0:15], v[110:113], v[114:117], v[0:15]
	s_setprio 0
	ds_read_b128 v[106:109], v42 offset:12288
	ds_read_b128 v[110:113], v43 offset:12288
	ds_read_b128 v[114:117], v78 offset:20480
	s_setprio 1
	s_waitcnt lgkmcnt(0)
	v_mfma_f32_32x32x16_bf16 v[16:31], v[106:109], v[114:117], v[16:31]
	v_mfma_f32_32x32x16_bf16 v[0:15], v[110:113], v[114:117], v[0:15]
	s_setprio 0
	s_waitcnt vmcnt(5)
	ds_write_b128 v38, v[94:97]
	s_waitcnt vmcnt(4)
	ds_write_b128 v39, v[98:101]
	s_waitcnt vmcnt(3)
	ds_write_b128 v40, v[102:105] offset:8192
	s_waitcnt lgkmcnt(0)
	s_barrier
	global_load_dwordx4 v[94:97], v[36:37], off offset:256
	global_load_dwordx4 v[98:101], v[34:35], off offset:256
	global_load_dwordx4 v[102:105], v[32:33], off offset:256
	ds_read_b128 v[106:109], v41
	ds_read_b128 v[110:113], v64
	ds_read_b128 v[114:117], v79 offset:8192
	s_setprio 1
	s_waitcnt lgkmcnt(0)
	v_mfma_f32_32x32x16_bf16 v[16:31], v[106:109], v[114:117], v[16:31]
	v_mfma_f32_32x32x16_bf16 v[0:15], v[110:113], v[114:117], v[0:15]
	s_setprio 0
	ds_read_b128 v[106:109], v42
	ds_read_b128 v[110:113], v43
	ds_read_b128 v[114:117], v78 offset:8192
	s_setprio 1
	s_waitcnt lgkmcnt(0)
	v_mfma_f32_32x32x16_bf16 v[16:31], v[106:109], v[114:117], v[16:31]
	v_mfma_f32_32x32x16_bf16 v[0:15], v[110:113], v[114:117], v[0:15]
	s_setprio 0
	s_waitcnt vmcnt(4)
	ds_write_b128 v38, v[86:89] offset:12288
	ds_write_b128 v39, v[80:83] offset:12288
	s_waitcnt vmcnt(3)
	ds_write_b128 v40, v[90:93] offset:20480
	s_waitcnt lgkmcnt(0)
	s_barrier
	global_load_dwordx4 v[80:83], v[36:37], off offset:320
	global_load_dwordx4 v[86:89], v[34:35], off offset:320
	global_load_dwordx4 v[90:93], v[32:33], off offset:320
	ds_read_b128 v[106:109], v41 offset:12288
	ds_read_b128 v[110:113], v64 offset:12288
	ds_read_b128 v[114:117], v79 offset:20480
	s_setprio 1
	s_waitcnt lgkmcnt(0)
	v_mfma_f32_32x32x16_bf16 v[16:31], v[106:109], v[114:117], v[16:31]
	v_mfma_f32_32x32x16_bf16 v[0:15], v[110:113], v[114:117], v[0:15]
	s_setprio 0
	ds_read_b128 v[106:109], v42 offset:12288
	ds_read_b128 v[110:113], v43 offset:12288
	ds_read_b128 v[114:117], v78 offset:20480
	s_setprio 1
	s_waitcnt lgkmcnt(0)
	v_mfma_f32_32x32x16_bf16 v[16:31], v[106:109], v[114:117], v[16:31]
	v_mfma_f32_32x32x16_bf16 v[0:15], v[110:113], v[114:117], v[0:15]
	s_setprio 0
	s_waitcnt vmcnt(4)
	ds_write_b128 v38, v[98:101]
	ds_write_b128 v39, v[94:97]
	s_waitcnt vmcnt(3)
	ds_write_b128 v40, v[102:105] offset:8192
	s_waitcnt lgkmcnt(0)
	s_barrier
	global_load_dwordx4 v[94:97], v[36:37], off offset:384
	global_load_dwordx4 v[98:101], v[34:35], off offset:384
	global_load_dwordx4 v[102:105], v[32:33], off offset:384
	ds_read_b128 v[106:109], v41
	ds_read_b128 v[110:113], v64
	ds_read_b128 v[114:117], v79 offset:8192
	s_setprio 1
	s_waitcnt lgkmcnt(0)
	v_mfma_f32_32x32x16_bf16 v[16:31], v[106:109], v[114:117], v[16:31]
	v_mfma_f32_32x32x16_bf16 v[0:15], v[110:113], v[114:117], v[0:15]
	s_setprio 0
	ds_read_b128 v[106:109], v42
	ds_read_b128 v[110:113], v43
	ds_read_b128 v[114:117], v78 offset:8192
	s_setprio 1
	s_waitcnt lgkmcnt(0)
	v_mfma_f32_32x32x16_bf16 v[16:31], v[106:109], v[114:117], v[16:31]
	v_mfma_f32_32x32x16_bf16 v[0:15], v[110:113], v[114:117], v[0:15]
	s_setprio 0
	s_waitcnt vmcnt(4)
	ds_write_b128 v38, v[86:89] offset:12288
	ds_write_b128 v39, v[80:83] offset:12288
	s_waitcnt vmcnt(3)
	ds_write_b128 v40, v[90:93] offset:20480
	s_waitcnt lgkmcnt(0)
	s_barrier
	global_load_dwordx4 v[80:83], v[36:37], off offset:448
	global_load_dwordx4 v[86:89], v[34:35], off offset:448
	global_load_dwordx4 v[90:93], v[32:33], off offset:448
	ds_read_b128 v[106:109], v41 offset:12288
	ds_read_b128 v[110:113], v64 offset:12288
	ds_read_b128 v[114:117], v79 offset:20480
	s_setprio 1
	s_waitcnt lgkmcnt(0)
	v_mfma_f32_32x32x16_bf16 v[16:31], v[106:109], v[114:117], v[16:31]
	v_mfma_f32_32x32x16_bf16 v[0:15], v[110:113], v[114:117], v[0:15]
	s_setprio 0
	ds_read_b128 v[106:109], v42 offset:12288
	ds_read_b128 v[110:113], v43 offset:12288
	ds_read_b128 v[114:117], v78 offset:20480
	s_setprio 1
	s_waitcnt lgkmcnt(0)
	v_mfma_f32_32x32x16_bf16 v[16:31], v[106:109], v[114:117], v[16:31]
	v_mfma_f32_32x32x16_bf16 v[0:15], v[110:113], v[114:117], v[0:15]
	s_setprio 0
	s_waitcnt vmcnt(4)
	ds_write_b128 v38, v[98:101]
	ds_write_b128 v39, v[94:97]
	s_waitcnt vmcnt(3)
	ds_write_b128 v40, v[102:105] offset:8192
	s_waitcnt lgkmcnt(0)
	s_barrier
	global_load_dwordx4 v[94:97], v[36:37], off offset:512
	global_load_dwordx4 v[98:101], v[34:35], off offset:512
	global_load_dwordx4 v[102:105], v[32:33], off offset:512
	ds_read_b128 v[106:109], v41
	ds_read_b128 v[110:113], v64
	ds_read_b128 v[114:117], v79 offset:8192
	s_setprio 1
	s_waitcnt lgkmcnt(0)
	v_mfma_f32_32x32x16_bf16 v[16:31], v[106:109], v[114:117], v[16:31]
	v_mfma_f32_32x32x16_bf16 v[0:15], v[110:113], v[114:117], v[0:15]
	s_setprio 0
	ds_read_b128 v[106:109], v42
	ds_read_b128 v[110:113], v43
	ds_read_b128 v[114:117], v78 offset:8192
	s_setprio 1
	s_waitcnt lgkmcnt(0)
	v_mfma_f32_32x32x16_bf16 v[16:31], v[106:109], v[114:117], v[16:31]
	v_mfma_f32_32x32x16_bf16 v[0:15], v[110:113], v[114:117], v[0:15]
	s_setprio 0
	s_waitcnt vmcnt(4)
	ds_write_b128 v38, v[86:89] offset:12288
	ds_write_b128 v39, v[80:83] offset:12288
	s_waitcnt vmcnt(3)
	ds_write_b128 v40, v[90:93] offset:20480
	s_waitcnt lgkmcnt(0)
	s_barrier
; template <int TJ>
; DI void gemm_core(const u16* __restrict__ W, int ldw, const u16* __restrict__ X, int ldx, int K, f32x16 (&acc)[2][TJ], char* lds) {
;     ...
;   G_LOAD(wA, xA, 0);
;   G_LOAD(wB, xB, 1);
;   G_STORE(wA, xA, 0);
;   __syncthreads();
;   for (int kt = 0; kt < nk; kt += 2) {
;     if (kt + 2 < nk) G_LOAD(wA, xA, kt + 2);
;     G_COMPUTE(0);
;     G_STORE(wB, xB, 1);
;     __syncthreads();
;     if (kt + 3 < nk) G_LOAD(wB, xB, kt + 3);
;     G_COMPUTE(1);
;     if (kt + 2 < nk) G_STORE(wA, xA, 0);
;     __syncthreads();
	global_load_dwordx4 v[80:83], v[36:37], off offset:576
	global_load_dwordx4 v[86:89], v[34:35], off offset:576
	global_load_dwordx4 v[90:93], v[32:33], off offset:576
	ds_read_b128 v[106:109], v41 offset:12288
	ds_read_b128 v[110:113], v64 offset:12288
	ds_read_b128 v[114:117], v79 offset:20480
	s_setprio 1
	s_waitcnt lgkmcnt(0)
	v_mfma_f32_32x32x16_bf16 v[16:31], v[106:109], v[114:117], v[16:31]
	v_mfma_f32_32x32x16_bf16 v[0:15], v[110:113], v[114:117], v[0:15]
	s_setprio 0
	ds_read_b128 v[106:109], v42 offset:12288
	ds_read_b128 v[110:113], v43 offset:12288
	ds_read_b128 v[114:117], v78 offset:20480
	s_setprio 1
	s_waitcnt lgkmcnt(0)
	v_mfma_f32_32x32x16_bf16 v[16:31], v[106:109], v[114:117], v[16:31]
	v_mfma_f32_32x32x16_bf16 v[0:15], v[110:113], v[114:117], v[0:15]
	s_setprio 0
	s_waitcnt vmcnt(4)
	ds_write_b128 v38, v[98:101]
	ds_write_b128 v39, v[94:97]
	s_waitcnt vmcnt(3)
	ds_write_b128 v40, v[102:105] offset:8192
	s_waitcnt lgkmcnt(0)
	s_barrier
	global_load_dwordx4 v[94:97], v[36:37], off offset:640
	global_load_dwordx4 v[98:101], v[34:35], off offset:640
	global_load_dwordx4 v[102:105], v[32:33], off offset:640
	ds_read_b128 v[106:109], v41
	ds_read_b128 v[110:113], v64
	ds_read_b128 v[114:117], v79 offset:8192
	s_setprio 1
	s_waitcnt lgkmcnt(0)
	v_mfma_f32_32x32x16_bf16 v[16:31], v[106:109], v[114:117], v[16:31]
	v_mfma_f32_32x32x16_bf16 v[0:15], v[110:113], v[114:117], v[0:15]
	s_setprio 0
	ds_read_b128 v[106:109], v42
	ds_read_b128 v[110:113], v43
	ds_read_b128 v[114:117], v78 offset:8192
	s_setprio 1
	s_waitcnt lgkmcnt(0)
	v_mfma_f32_32x32x16_bf16 v[16:31], v[106:109], v[114:117], v[16:31]
	v_mfma_f32_32x32x16_bf16 v[0:15], v[110:113], v[114:117], v[0:15]
	s_setprio 0
	s_waitcnt vmcnt(4)
	ds_write_b128 v38, v[86:89] offset:12288
	ds_write_b128 v39, v[80:83] offset:12288
	s_waitcnt vmcnt(3)
	ds_write_b128 v40, v[90:93] offset:20480
	s_waitcnt lgkmcnt(0)
	s_barrier
	global_load_dwordx4 v[80:83], v[36:37], off offset:704
	global_load_dwordx4 v[86:89], v[34:35], off offset:704
	global_load_dwordx4 v[90:93], v[32:33], off offset:704
	ds_read_b128 v[106:109], v41 offset:12288
	ds_read_b128 v[110:113], v64 offset:12288
	ds_read_b128 v[114:117], v79 offset:20480
	s_setprio 1
	s_waitcnt lgkmcnt(0)
	v_mfma_f32_32x32x16_bf16 v[16:31], v[106:109], v[114:117], v[16:31]
	v_mfma_f32_32x32x16_bf16 v[0:15], v[110:113], v[114:117], v[0:15]
	s_setprio 0
	ds_read_b128 v[106:109], v42 offset:12288
	ds_read_b128 v[110:113], v43 offset:12288
	ds_read_b128 v[114:117], v78 offset:20480
	s_setprio 1
	s_waitcnt lgkmcnt(0)
	v_mfma_f32_32x32x16_bf16 v[16:31], v[106:109], v[114:117], v[16:31]
	v_mfma_f32_32x32x16_bf16 v[0:15], v[110:113], v[114:117], v[0:15]
	s_setprio 0
	s_waitcnt vmcnt(4)
	ds_write_b128 v38, v[98:101]
	ds_write_b128 v39, v[94:97]
	s_waitcnt vmcnt(3)
	ds_write_b128 v40, v[102:105] offset:8192
	s_waitcnt lgkmcnt(0)
	s_barrier
	global_load_dwordx4 v[94:97], v[36:37], off offset:768
	global_load_dwordx4 v[98:101], v[34:35], off offset:768
	global_load_dwordx4 v[102:105], v[32:33], off offset:768
	ds_read_b128 v[106:109], v41
	ds_read_b128 v[110:113], v64
	ds_read_b128 v[114:117], v79 offset:8192
	s_setprio 1
	s_waitcnt lgkmcnt(0)
	v_mfma_f32_32x32x16_bf16 v[16:31], v[106:109], v[114:117], v[16:31]
	v_mfma_f32_32x32x16_bf16 v[0:15], v[110:113], v[114:117], v[0:15]
	s_setprio 0
	ds_read_b128 v[106:109], v42
	ds_read_b128 v[110:113], v43
	ds_read_b128 v[114:117], v78 offset:8192
	s_setprio 1
	s_waitcnt lgkmcnt(0)
	v_mfma_f32_32x32x16_bf16 v[16:31], v[106:109], v[114:117], v[16:31]
	v_mfma_f32_32x32x16_bf16 v[0:15], v[110:113], v[114:117], v[0:15]
	s_setprio 0
	s_waitcnt vmcnt(4)
	ds_write_b128 v38, v[86:89] offset:12288
	ds_write_b128 v39, v[80:83] offset:12288
	s_waitcnt vmcnt(3)
	ds_write_b128 v40, v[90:93] offset:20480
	s_waitcnt lgkmcnt(0)
	s_barrier
	global_load_dwordx4 v[80:83], v[36:37], off offset:832
	global_load_dwordx4 v[86:89], v[34:35], off offset:832
	global_load_dwordx4 v[90:93], v[32:33], off offset:832
	ds_read_b128 v[106:109], v41 offset:12288
	ds_read_b128 v[110:113], v64 offset:12288
	ds_read_b128 v[114:117], v79 offset:20480
	s_setprio 1
	s_waitcnt lgkmcnt(0)
	v_mfma_f32_32x32x16_bf16 v[16:31], v[106:109], v[114:117], v[16:31]
	v_mfma_f32_32x32x16_bf16 v[0:15], v[110:113], v[114:117], v[0:15]
	s_setprio 0
	ds_read_b128 v[106:109], v42 offset:12288
	ds_read_b128 v[110:113], v43 offset:12288
	ds_read_b128 v[114:117], v78 offset:20480
	s_setprio 1
	s_waitcnt lgkmcnt(0)
	v_mfma_f32_32x32x16_bf16 v[16:31], v[106:109], v[114:117], v[16:31]
	v_mfma_f32_32x32x16_bf16 v[0:15], v[110:113], v[114:117], v[0:15]
	s_setprio 0
	s_waitcnt vmcnt(4)
	ds_write_b128 v38, v[98:101]
	ds_write_b128 v39, v[94:97]
	s_waitcnt vmcnt(3)
	ds_write_b128 v40, v[102:105] offset:8192
	s_waitcnt lgkmcnt(0)
	s_barrier
	global_load_dwordx4 v[94:97], v[36:37], off offset:896
	global_load_dwordx4 v[98:101], v[34:35], off offset:896
	global_load_dwordx4 v[102:105], v[32:33], off offset:896
	ds_read_b128 v[106:109], v41
	ds_read_b128 v[110:113], v64
	ds_read_b128 v[114:117], v79 offset:8192
	s_setprio 1
	s_waitcnt lgkmcnt(0)
	v_mfma_f32_32x32x16_bf16 v[16:31], v[106:109], v[114:117], v[16:31]
	v_mfma_f32_32x32x16_bf16 v[0:15], v[110:113], v[114:117], v[0:15]
	s_setprio 0
	ds_read_b128 v[106:109], v42
	ds_read_b128 v[110:113], v43
	ds_read_b128 v[114:117], v78 offset:8192
	s_setprio 1
	s_waitcnt lgkmcnt(0)
	v_mfma_f32_32x32x16_bf16 v[16:31], v[106:109], v[114:117], v[16:31]
	v_mfma_f32_32x32x16_bf16 v[0:15], v[110:113], v[114:117], v[0:15]
	s_setprio 0
	s_waitcnt vmcnt(4)
	ds_write_b128 v38, v[86:89] offset:12288
	ds_write_b128 v39, v[80:83] offset:12288
	s_waitcnt vmcnt(3)
	ds_write_b128 v40, v[90:93] offset:20480
	s_waitcnt lgkmcnt(0)
	s_barrier
; DI float bflo(unsigned u) { return __uint_as_float(u << 16); }
; DI float bfhi(unsigned u) { return __uint_as_float(u & 0xffff0000u); }
; template <int TJ>
; DI void gemm_core(const u16* __restrict__ W, int ldw, const u16* __restrict__ X, int ldx, int K, f32x16 (&acc)[2][TJ], char* lds) {
;     ...
;   G_LOAD(wA, xA, 0);
;   G_LOAD(wB, xB, 1);
;   G_STORE(wA, xA, 0);
;   __syncthreads();
;   for (int kt = 0; kt < nk; kt += 2) {
;     if (kt + 2 < nk) G_LOAD(wA, xA, kt + 2);
;     G_COMPUTE(0);
;     G_STORE(wB, xB, 1);
;     __syncthreads();
;     if (kt + 3 < nk) G_LOAD(wB, xB, kt + 3);
;     G_COMPUTE(1);
;     if (kt + 2 < nk) G_STORE(wA, xA, 0);
;     __syncthreads();
;   }
; template <int TJ>
; DI void merge_tile(const Params& p, size_t t0, int nt, char* lds) {
;     ...
; #pragma unroll
;     for (int i = 0; i < 2; ++i)
; #pragma unroll
;       for (int j = 0; j < TJ; ++j)
; #pragma unroll
;         for (int e = 0; e < 8; ++e) { const unsigned sv = sgl[((i * TJ + j) * 8 + e) * 256]; ms[i][j][2 * e] += bflo(sv) * ag[i][j][2 * e]; ms[i][j][2 * e + 1] += bfhi(sv) * ag[i][j][2 * e + 1]; }
	global_load_dwordx4 v[80:83], v[36:37], off offset:960
	s_nop 0
	global_load_dwordx4 v[34:37], v[34:35], off offset:960
	s_nop 0
	global_load_dwordx4 v[86:89], v[32:33], off offset:960
	ds_read_b128 v[90:93], v41 offset:12288
	ds_read_b128 v[106:109], v64 offset:12288
	ds_read_b128 v[110:113], v79 offset:20480
	s_setprio 1
	s_waitcnt lgkmcnt(0)
	v_mfma_f32_32x32x16_bf16 v[16:31], v[90:93], v[110:113], v[16:31]
	v_mfma_f32_32x32x16_bf16 v[0:15], v[106:109], v[110:113], v[0:15]
	s_setprio 0
	ds_read_b128 v[90:93], v42 offset:12288
	ds_read_b128 v[106:109], v43 offset:12288
	ds_read_b128 v[110:113], v78 offset:20480
	s_setprio 1
	s_waitcnt lgkmcnt(0)
	v_mfma_f32_32x32x16_bf16 v[16:31], v[90:93], v[110:113], v[16:31]
	v_mfma_f32_32x32x16_bf16 v[0:15], v[106:109], v[110:113], v[0:15]
	s_setprio 0
	s_waitcnt vmcnt(4)
	ds_write_b128 v38, v[98:101]
	ds_write_b128 v39, v[94:97]
	s_waitcnt vmcnt(3)
	ds_write_b128 v40, v[102:105] offset:8192
	s_waitcnt lgkmcnt(0)
	s_barrier
	ds_read_b128 v[90:93], v41
	ds_read_b128 v[94:97], v64
	ds_read_b128 v[98:101], v79 offset:8192
	s_setprio 1
	s_waitcnt lgkmcnt(0)
	v_mfma_f32_32x32x16_bf16 v[16:31], v[90:93], v[98:101], v[16:31]
	v_mfma_f32_32x32x16_bf16 v[0:15], v[94:97], v[98:101], v[0:15]
	s_setprio 0
	ds_read_b128 v[90:93], v42
	ds_read_b128 v[94:97], v43
	ds_read_b128 v[98:101], v78 offset:8192
	s_setprio 1
	s_waitcnt lgkmcnt(0)
	v_mfma_f32_32x32x16_bf16 v[16:31], v[90:93], v[98:101], v[16:31]
	v_mfma_f32_32x32x16_bf16 v[0:15], v[94:97], v[98:101], v[0:15]
	s_setprio 0
	s_waitcnt vmcnt(1)
	ds_write_b128 v38, v[34:37] offset:12288
	ds_write_b128 v39, v[80:83] offset:12288
	s_waitcnt vmcnt(0)
	ds_write_b128 v40, v[86:89] offset:20480
	s_waitcnt lgkmcnt(0)
	s_barrier
	ds_read_b128 v[32:35], v41 offset:12288
	ds_read_b128 v[36:39], v64 offset:12288
	ds_read_b128 v[80:83], v79 offset:20480
	s_setprio 1
	s_waitcnt lgkmcnt(0)
	v_mfma_f32_32x32x16_bf16 v[16:31], v[32:35], v[80:83], v[16:31]
	v_mfma_f32_32x32x16_bf16 v[0:15], v[36:39], v[80:83], v[0:15]
	s_setprio 0
	ds_read_b128 v[32:35], v42 offset:12288
	ds_read_b128 v[36:39], v43 offset:12288
	ds_read_b128 v[40:43], v78 offset:20480
	s_setprio 1
	s_waitcnt lgkmcnt(0)
	v_mfma_f32_32x32x16_bf16 v[16:31], v[32:35], v[40:43], v[16:31]
	v_mfma_f32_32x32x16_bf16 v[0:15], v[36:39], v[40:43], v[0:15]
	s_setprio 0
	s_barrier
	ds_read2st64_b32 v[32:33], v85 offset0:128 offset1:132
	s_add_i32 s49, s49, 1
	s_add_u32 s40, s40, 0x100000
	s_addc_u32 s41, s41, 0
	s_add_u32 s38, s38, 0x200000
	s_waitcnt lgkmcnt(0)
	v_lshlrev_b32_e32 v34, 16, v32
	v_and_b32_e32 v35, 0xffff0000, v32
	s_nop 0
	v_fma_f32 v70, v16, v34, v70
	v_fma_f32 v71, v17, v35, v71
	v_lshlrev_b32_e32 v16, 16, v33
	v_and_b32_e32 v17, 0xffff0000, v33
	v_fma_f32 v72, v18, v16, v72
	v_fma_f32 v73, v19, v17, v73
	ds_read2st64_b32 v[16:17], v85 offset0:136 offset1:140
	s_addc_u32 s39, s39, 0
	s_cmp_lg_u32 s49, 4
	s_waitcnt lgkmcnt(0)
	v_lshlrev_b32_e32 v18, 16, v16
	v_and_b32_e32 v19, 0xffff0000, v16
	v_lshlrev_b32_e32 v16, 16, v17
	v_and_b32_e32 v17, 0xffff0000, v17
	v_fma_f32 v76, v22, v16, v76
	v_fma_f32 v77, v23, v17, v77
	ds_read2st64_b32 v[16:17], v85 offset0:144 offset1:148
	v_fma_f32 v74, v20, v18, v74
	v_fma_f32 v75, v21, v19, v75
	s_waitcnt lgkmcnt(0)
	v_lshlrev_b32_e32 v18, 16, v16
	v_and_b32_e32 v19, 0xffff0000, v16
	v_lshlrev_b32_e32 v16, 16, v17
	v_and_b32_e32 v17, 0xffff0000, v17
	v_fma_f32 v66, v26, v16, v66
	v_fma_f32 v67, v27, v17, v67
	ds_read2st64_b32 v[16:17], v85 offset0:152 offset1:156
	v_fma_f32 v62, v24, v18, v62
	v_fma_f32 v63, v25, v19, v63
	s_waitcnt lgkmcnt(0)
	v_lshlrev_b32_e32 v18, 16, v16
	v_and_b32_e32 v19, 0xffff0000, v16
	v_lshlrev_b32_e32 v16, 16, v17
	v_and_b32_e32 v17, 0xffff0000, v17
	v_fma_f32 v60, v30, v16, v60
	v_fma_f32 v61, v31, v17, v61
	ds_read2st64_b32 v[16:17], v85 offset0:160 offset1:164
	v_fma_f32 v68, v28, v18, v68
	v_fma_f32 v69, v29, v19, v69
	s_waitcnt lgkmcnt(0)
	v_lshlrev_b32_e32 v18, 16, v16
	v_and_b32_e32 v19, 0xffff0000, v16
	v_fma_f32 v52, v0, v18, v52
	v_fma_f32 v53, v1, v19, v53
	v_lshlrev_b32_e32 v0, 16, v17
	v_and_b32_e32 v1, 0xffff0000, v17
	v_fma_f32 v54, v2, v0, v54
	v_fma_f32 v55, v3, v1, v55
	ds_read2st64_b32 v[0:1], v85 offset0:168 offset1:172
	s_waitcnt lgkmcnt(0)
	v_lshlrev_b32_e32 v2, 16, v0
	v_and_b32_e32 v3, 0xffff0000, v0
	v_lshlrev_b32_e32 v0, 16, v1
	v_and_b32_e32 v1, 0xffff0000, v1
	v_fma_f32 v58, v6, v0, v58
	v_fma_f32 v59, v7, v1, v59
	ds_read2st64_b32 v[0:1], v85 offset0:176 offset1:180
	v_fma_f32 v56, v4, v2, v56
	v_fma_f32 v57, v5, v3, v57
	s_waitcnt lgkmcnt(0)
	v_lshlrev_b32_e32 v2, 16, v0
	v_and_b32_e32 v3, 0xffff0000, v0
	v_lshlrev_b32_e32 v0, 16, v1
	v_and_b32_e32 v1, 0xffff0000, v1
	v_fma_f32 v48, v10, v0, v48
	v_fma_f32 v49, v11, v1, v49
	ds_read2st64_b32 v[0:1], v85 offset0:184 offset1:188
	v_fma_f32 v46, v8, v2, v46
	v_fma_f32 v47, v9, v3, v47
	s_waitcnt lgkmcnt(0)
	v_lshlrev_b32_e32 v2, 16, v0
	v_and_b32_e32 v3, 0xffff0000, v0
	v_lshlrev_b32_e32 v0, 16, v1
	v_and_b32_e32 v1, 0xffff0000, v1
	v_fma_f32 v50, v12, v2, v50
	v_fma_f32 v51, v13, v3, v51
	v_fma_f32 v44, v14, v0, v44
	v_fma_f32 v45, v15, v1, v45
	s_cbranch_scc0 .LBB0_50

; DI int otid() { int t = threadIdx.x; asm volatile("" : "+v"(t)); return t; }
; template <int TJ>
; DI void gemm_core(const u16* __restrict__ W, int ldw, const u16* __restrict__ X, int ldx, int K, f32x16 (&acc)[2][TJ], char* lds) {
;   constexpr int XR = 64 * TJ;
;   constexpr int WBYTES = 128 * 64, XBYTES = XR * 64, STAGE = WBYTES + XBYTES;
;   const int tid = otid(), lane = tid & 63, wid = tid >> 6, r = lane & 31, h = lane >> 5;
;   const int wn = wid & 1, wt = wid >> 1;
;   u32x4 wA[2], xA[TJ], wB[2], xB[TJ];
;   const int lrow = tid >> 2, lch = tid & 3;
;   const u16* wp = W + (size_t)lrow * ldw + lch * 8;
;   const u16* xp = X + (size_t)lrow * ldx + lch * 8;
;   const int nk = K / 32;
;     ...
;   G_LOAD(wA, xA, 0);
;   G_LOAD(wB, xB, 1);
;   G_STORE(wA, xA, 0);
;   __syncthreads();
;   for (int kt = 0; kt < nk; kt += 2) {
;     if (kt + 2 < nk) G_LOAD(wA, xA, kt + 2);
;     G_COMPUTE(0);
;     G_STORE(wB, xB, 1);
;     __syncthreads();
;     if (kt + 3 < nk) G_LOAD(wB, xB, kt + 3);
;     G_COMPUTE(1);
;     if (kt + 2 < nk) G_STORE(wA, xA, 0);
;     __syncthreads();
;   }
.LBB0_52:
	v_mov_b32_e32 v18, v190
	s_add_u32 s0, s22, s28
	v_ashrrev_i32_e32 v16, 2, v18
	v_and_b32_e32 v19, 3, v18
	v_ashrrev_i32_e32 v17, 31, v16
	v_lshlrev_b64 v[0:1], 11, v[16:17]
	v_lshlrev_b32_e32 v64, 4, v19
	v_or_b32_e32 v2, v0, v64
	v_mov_b32_e32 v3, v1
	s_addc_u32 s1, s23, s29
	v_lshl_add_u64 v[4:5], s[0:1], 0, v[2:3]
	s_mov_b32 s0, 0x1cd20000
	v_add_co_u32_e32 v148, vcc, s0, v4
	v_lshl_add_u64 v[0:1], s[30:31], 0, v[0:1]
	s_nop 0
	v_addc_co_u32_e32 v149, vcc, 0, v5, vcc
	s_mov_b32 s0, 0x1cd40000
	v_lshl_add_u64 v[146:147], v[0:1], 0, v[64:65]
	global_load_dwordx4 v[0:3], v[148:149], off
	v_add_co_u32_e32 v150, vcc, s0, v4
	s_mov_b32 s0, 0x20000
	s_nop 0
	v_addc_co_u32_e32 v151, vcc, 0, v5, vcc
	global_load_dwordx4 v[4:7], v[150:151], off
	global_load_dwordx4 v[8:11], v[146:147], off
	v_add_co_u32_e32 v152, vcc, s0, v146
	v_lshlrev_b32_e32 v20, 11, v19
	s_nop 0
	v_addc_co_u32_e32 v153, vcc, 0, v147, vcc
	global_load_dwordx4 v[12:15], v[152:153], off
	v_lshlrev_b32_e32 v19, 5, v19
	v_lshlrev_b32_e32 v16, 4, v16
	v_xad_u32 v64, v16, v19, v20
	global_load_dwordx4 v[66:69], v[148:149], off offset:64
	global_load_dwordx4 v[70:73], v[150:151], off offset:64
	global_load_dwordx4 v[74:77], v[146:147], off offset:64
	global_load_dwordx4 v[78:81], v[152:153], off offset:64
	s_movk_i32 s18, 0xfc00
	v_bfe_u32 v17, v18, 5, 1
	s_waitcnt vmcnt(7)
	ds_write_b128 v64, v[0:3]
	v_add_u32_e32 v0, 0x400, v16
	v_xad_u32 v156, v0, v19, v20
	s_waitcnt vmcnt(6)
	ds_write_b128 v156, v[4:7]
	s_waitcnt vmcnt(5)
	ds_write_b128 v64, v[8:11] offset:8192
	s_waitcnt vmcnt(4)
	ds_write_b128 v156, v[12:15] offset:8192
	s_waitcnt lgkmcnt(0)
	s_barrier
	global_load_dwordx4 v[166:169], v[148:149], off offset:128
	global_load_dwordx4 v[170:173], v[150:151], off offset:128
	global_load_dwordx4 v[174:177], v[146:147], off offset:128
	global_load_dwordx4 v[178:181], v[152:153], off offset:128
	v_lshlrev_b32_e32 v2, 4, v18
	v_and_b32_e32 v3, 0x1f0, v2
	v_lshlrev_b32_e32 v5, 3, v18
	v_and_b32_e32 v2, 0x5f0, v2
	v_and_or_b32 v3, v5, s18, v3
	v_lshlrev_b32_e32 v0, 11, v17
	v_lshlrev_b32_e32 v1, 5, v17
	v_or_b32_e32 v4, 0x200, v2
	v_or_b32_e32 v5, 0x200, v3
	v_bitop3_b32 v161, v0, v1, v2 bitop3:0xf6
	v_bitop3_b32 v162, v0, v4, v1 bitop3:0xf6
	v_xad_u32 v163, v3, v1, v0
	v_xad_u32 v164, v5, v1, v0
	v_or_b32_e32 v0, 2, v17
	v_lshlrev_b32_e32 v1, 11, v0
	v_lshlrev_b32_e32 v0, 5, v0
	v_bitop3_b32 v157, v1, v0, v2 bitop3:0xf6
	v_bitop3_b32 v158, v1, v0, v4 bitop3:0xf6
	v_xad_u32 v159, v0, v3, v1
	v_xad_u32 v160, v5, v0, v1
	ds_read_b128 v[0:3], v161
	ds_read_b128 v[4:7], v162
	ds_read_b128 v[8:11], v163 offset:8192
	ds_read_b128 v[12:15], v164 offset:8192
	s_setprio 1
	s_waitcnt lgkmcnt(1)
	v_mfma_f32_32x32x16_bf16 v[48:63], v[0:3], v[8:11], 0
	s_waitcnt lgkmcnt(0)
	v_mfma_f32_32x32x16_bf16 v[32:47], v[0:3], v[12:15], 0
	v_mfma_f32_32x32x16_bf16 v[16:31], v[4:7], v[8:11], 0
	v_mfma_f32_32x32x16_bf16 v[0:15], v[4:7], v[12:15], 0
	s_setprio 0
	ds_read_b128 v[182:185], v157
	ds_read_b128 v[186:189], v158
	ds_read_b128 v[206:209], v159 offset:8192
	ds_read_b128 v[214:217], v160 offset:8192
	s_setprio 1
	s_waitcnt lgkmcnt(1)
	v_mfma_f32_32x32x16_bf16 v[48:63], v[182:185], v[206:209], v[48:63]
	s_waitcnt lgkmcnt(0)
	v_mfma_f32_32x32x16_bf16 v[32:47], v[182:185], v[214:217], v[32:47]
	v_mfma_f32_32x32x16_bf16 v[16:31], v[186:189], v[206:209], v[16:31]
	v_mfma_f32_32x32x16_bf16 v[0:15], v[186:189], v[214:217], v[0:15]
	s_setprio 0
	s_waitcnt vmcnt(7)
	ds_write_b128 v64, v[66:69] offset:16384
	s_waitcnt vmcnt(6)
	ds_write_b128 v156, v[70:73] offset:16384
	s_waitcnt vmcnt(5)
	ds_write_b128 v64, v[74:77] offset:24576
	s_waitcnt vmcnt(4)
	ds_write_b128 v156, v[78:81] offset:24576
	s_waitcnt lgkmcnt(0)
	s_barrier
	global_load_dwordx4 v[66:69], v[148:149], off offset:192
	global_load_dwordx4 v[70:73], v[146:147], off offset:192
	global_load_dwordx4 v[74:77], v[150:151], off offset:192
	global_load_dwordx4 v[78:81], v[152:153], off offset:192
	ds_read_b128 v[182:185], v161 offset:16384
	ds_read_b128 v[186:189], v162 offset:16384
	ds_read_b128 v[206:209], v163 offset:24576
	ds_read_b128 v[214:217], v164 offset:24576
	s_setprio 1
	s_waitcnt lgkmcnt(1)
	v_mfma_f32_32x32x16_bf16 v[48:63], v[182:185], v[206:209], v[48:63]
	s_waitcnt lgkmcnt(0)
	v_mfma_f32_32x32x16_bf16 v[32:47], v[182:185], v[214:217], v[32:47]
	v_mfma_f32_32x32x16_bf16 v[16:31], v[186:189], v[206:209], v[16:31]
	v_mfma_f32_32x32x16_bf16 v[0:15], v[186:189], v[214:217], v[0:15]
	s_setprio 0
	ds_read_b128 v[182:185], v157 offset:16384
	ds_read_b128 v[186:189], v158 offset:16384
	ds_read_b128 v[206:209], v159 offset:24576
	ds_read_b128 v[214:217], v160 offset:24576
	s_setprio 1
	s_waitcnt lgkmcnt(1)
	v_mfma_f32_32x32x16_bf16 v[48:63], v[182:185], v[206:209], v[48:63]
	s_waitcnt lgkmcnt(0)
	v_mfma_f32_32x32x16_bf16 v[32:47], v[182:185], v[214:217], v[32:47]
	v_mfma_f32_32x32x16_bf16 v[16:31], v[186:189], v[206:209], v[16:31]
	v_mfma_f32_32x32x16_bf16 v[0:15], v[186:189], v[214:217], v[0:15]
	s_setprio 0
	s_waitcnt vmcnt(7)
	ds_write_b128 v64, v[166:169]
	s_waitcnt vmcnt(6)
	ds_write_b128 v156, v[170:173]
	s_waitcnt vmcnt(5)
	ds_write_b128 v64, v[174:177] offset:8192
	s_waitcnt vmcnt(4)
	ds_write_b128 v156, v[178:181] offset:8192
	s_waitcnt lgkmcnt(0)
	s_barrier
; template <int TJ>
; DI void gemm_core(const u16* __restrict__ W, int ldw, const u16* __restrict__ X, int ldx, int K, f32x16 (&acc)[2][TJ], char* lds) {
;     ...
;   G_LOAD(wA, xA, 0);
;   G_LOAD(wB, xB, 1);
;   G_STORE(wA, xA, 0);
;   __syncthreads();
;   for (int kt = 0; kt < nk; kt += 2) {
;     if (kt + 2 < nk) G_LOAD(wA, xA, kt + 2);
;     G_COMPUTE(0);
;     G_STORE(wB, xB, 1);
;     __syncthreads();
;     if (kt + 3 < nk) G_LOAD(wB, xB, kt + 3);
;     G_COMPUTE(1);
;     if (kt + 2 < nk) G_STORE(wA, xA, 0);
;     __syncthreads();
	global_load_dwordx4 v[166:169], v[148:149], off offset:256
	global_load_dwordx4 v[170:173], v[146:147], off offset:256
	global_load_dwordx4 v[174:177], v[150:151], off offset:256
	global_load_dwordx4 v[178:181], v[152:153], off offset:256
	ds_read_b128 v[182:185], v161
	ds_read_b128 v[186:189], v162
	ds_read_b128 v[206:209], v163 offset:8192
	ds_read_b128 v[214:217], v164 offset:8192
	s_setprio 1
	s_waitcnt lgkmcnt(1)
	v_mfma_f32_32x32x16_bf16 v[48:63], v[182:185], v[206:209], v[48:63]
	s_waitcnt lgkmcnt(0)
	v_mfma_f32_32x32x16_bf16 v[32:47], v[182:185], v[214:217], v[32:47]
	v_mfma_f32_32x32x16_bf16 v[16:31], v[186:189], v[206:209], v[16:31]
	v_mfma_f32_32x32x16_bf16 v[0:15], v[186:189], v[214:217], v[0:15]
	s_setprio 0
	ds_read_b128 v[182:185], v157
	ds_read_b128 v[186:189], v158
	ds_read_b128 v[206:209], v159 offset:8192
	ds_read_b128 v[214:217], v160 offset:8192
	s_setprio 1
	s_waitcnt lgkmcnt(1)
	v_mfma_f32_32x32x16_bf16 v[48:63], v[182:185], v[206:209], v[48:63]
	s_waitcnt lgkmcnt(0)
	v_mfma_f32_32x32x16_bf16 v[32:47], v[182:185], v[214:217], v[32:47]
	v_mfma_f32_32x32x16_bf16 v[16:31], v[186:189], v[206:209], v[16:31]
	v_mfma_f32_32x32x16_bf16 v[0:15], v[186:189], v[214:217], v[0:15]
	s_setprio 0
	s_waitcnt vmcnt(7)
	ds_write_b128 v64, v[66:69] offset:16384
	s_waitcnt vmcnt(5)
	ds_write_b128 v156, v[74:77] offset:16384
	ds_write_b128 v64, v[70:73] offset:24576
	s_waitcnt vmcnt(4)
	ds_write_b128 v156, v[78:81] offset:24576
	s_waitcnt lgkmcnt(0)
	s_barrier
	global_load_dwordx4 v[66:69], v[148:149], off offset:320
	global_load_dwordx4 v[70:73], v[146:147], off offset:320
	global_load_dwordx4 v[74:77], v[150:151], off offset:320
	global_load_dwordx4 v[78:81], v[152:153], off offset:320
	ds_read_b128 v[182:185], v161 offset:16384
	ds_read_b128 v[186:189], v162 offset:16384
	ds_read_b128 v[206:209], v163 offset:24576
	ds_read_b128 v[214:217], v164 offset:24576
	s_setprio 1
	s_waitcnt lgkmcnt(1)
	v_mfma_f32_32x32x16_bf16 v[48:63], v[182:185], v[206:209], v[48:63]
	s_waitcnt lgkmcnt(0)
	v_mfma_f32_32x32x16_bf16 v[32:47], v[182:185], v[214:217], v[32:47]
	v_mfma_f32_32x32x16_bf16 v[16:31], v[186:189], v[206:209], v[16:31]
	v_mfma_f32_32x32x16_bf16 v[0:15], v[186:189], v[214:217], v[0:15]
	s_setprio 0
	ds_read_b128 v[182:185], v157 offset:16384
	ds_read_b128 v[186:189], v158 offset:16384
	ds_read_b128 v[206:209], v159 offset:24576
	ds_read_b128 v[214:217], v160 offset:24576
	s_setprio 1
	s_waitcnt lgkmcnt(1)
	v_mfma_f32_32x32x16_bf16 v[48:63], v[182:185], v[206:209], v[48:63]
	s_waitcnt lgkmcnt(0)
	v_mfma_f32_32x32x16_bf16 v[32:47], v[182:185], v[214:217], v[32:47]
	v_mfma_f32_32x32x16_bf16 v[16:31], v[186:189], v[206:209], v[16:31]
	v_mfma_f32_32x32x16_bf16 v[0:15], v[186:189], v[214:217], v[0:15]
	s_setprio 0
	s_waitcnt vmcnt(7)
	ds_write_b128 v64, v[166:169]
	s_waitcnt vmcnt(5)
	ds_write_b128 v156, v[174:177]
	ds_write_b128 v64, v[170:173] offset:8192
	s_waitcnt vmcnt(4)
	ds_write_b128 v156, v[178:181] offset:8192
	s_waitcnt lgkmcnt(0)
	s_barrier
	global_load_dwordx4 v[166:169], v[148:149], off offset:384
	global_load_dwordx4 v[170:173], v[146:147], off offset:384
	global_load_dwordx4 v[174:177], v[150:151], off offset:384
	global_load_dwordx4 v[178:181], v[152:153], off offset:384
	ds_read_b128 v[182:185], v161
	ds_read_b128 v[186:189], v162
	ds_read_b128 v[206:209], v163 offset:8192
	ds_read_b128 v[214:217], v164 offset:8192
	s_setprio 1
	s_waitcnt lgkmcnt(1)
	v_mfma_f32_32x32x16_bf16 v[48:63], v[182:185], v[206:209], v[48:63]
	s_waitcnt lgkmcnt(0)
	v_mfma_f32_32x32x16_bf16 v[32:47], v[182:185], v[214:217], v[32:47]
	v_mfma_f32_32x32x16_bf16 v[16:31], v[186:189], v[206:209], v[16:31]
	v_mfma_f32_32x32x16_bf16 v[0:15], v[186:189], v[214:217], v[0:15]
	s_setprio 0
	ds_read_b128 v[182:185], v157
	ds_read_b128 v[186:189], v158
	ds_read_b128 v[206:209], v159 offset:8192
	ds_read_b128 v[214:217], v160 offset:8192
	s_setprio 1
	s_waitcnt lgkmcnt(1)
	v_mfma_f32_32x32x16_bf16 v[48:63], v[182:185], v[206:209], v[48:63]
	s_waitcnt lgkmcnt(0)
	v_mfma_f32_32x32x16_bf16 v[32:47], v[182:185], v[214:217], v[32:47]
	v_mfma_f32_32x32x16_bf16 v[16:31], v[186:189], v[206:209], v[16:31]
	v_mfma_f32_32x32x16_bf16 v[0:15], v[186:189], v[214:217], v[0:15]
	s_setprio 0
	s_waitcnt vmcnt(7)
	ds_write_b128 v64, v[66:69] offset:16384
	s_waitcnt vmcnt(5)
	ds_write_b128 v156, v[74:77] offset:16384
	ds_write_b128 v64, v[70:73] offset:24576
	s_waitcnt vmcnt(4)
	ds_write_b128 v156, v[78:81] offset:24576
	s_waitcnt lgkmcnt(0)
	s_barrier
	global_load_dwordx4 v[66:69], v[148:149], off offset:448
	global_load_dwordx4 v[70:73], v[146:147], off offset:448
	global_load_dwordx4 v[74:77], v[150:151], off offset:448
	global_load_dwordx4 v[78:81], v[152:153], off offset:448
	ds_read_b128 v[182:185], v161 offset:16384
	ds_read_b128 v[186:189], v162 offset:16384
	ds_read_b128 v[206:209], v163 offset:24576
	ds_read_b128 v[214:217], v164 offset:24576
	s_setprio 1
	s_waitcnt lgkmcnt(1)
	v_mfma_f32_32x32x16_bf16 v[48:63], v[182:185], v[206:209], v[48:63]
	s_waitcnt lgkmcnt(0)
	v_mfma_f32_32x32x16_bf16 v[32:47], v[182:185], v[214:217], v[32:47]
	v_mfma_f32_32x32x16_bf16 v[16:31], v[186:189], v[206:209], v[16:31]
	v_mfma_f32_32x32x16_bf16 v[0:15], v[186:189], v[214:217], v[0:15]
	s_setprio 0
	ds_read_b128 v[182:185], v157 offset:16384
	ds_read_b128 v[186:189], v158 offset:16384
	ds_read_b128 v[206:209], v159 offset:24576
	ds_read_b128 v[214:217], v160 offset:24576
	s_setprio 1
	s_waitcnt lgkmcnt(1)
	v_mfma_f32_32x32x16_bf16 v[48:63], v[182:185], v[206:209], v[48:63]
	s_waitcnt lgkmcnt(0)
	v_mfma_f32_32x32x16_bf16 v[32:47], v[182:185], v[214:217], v[32:47]
	v_mfma_f32_32x32x16_bf16 v[16:31], v[186:189], v[206:209], v[16:31]
	v_mfma_f32_32x32x16_bf16 v[0:15], v[186:189], v[214:217], v[0:15]
	s_setprio 0
	s_waitcnt vmcnt(7)
	ds_write_b128 v64, v[166:169]
	s_waitcnt vmcnt(5)
	ds_write_b128 v156, v[174:177]
	ds_write_b128 v64, v[170:173] offset:8192
	s_waitcnt vmcnt(4)
	ds_write_b128 v156, v[178:181] offset:8192
	s_waitcnt lgkmcnt(0)
	s_barrier
; template <int TJ>
; DI void gemm_core(const u16* __restrict__ W, int ldw, const u16* __restrict__ X, int ldx, int K, f32x16 (&acc)[2][TJ], char* lds) {
;     ...
;   for (int kt = 0; kt < nk; kt += 2) {
;     if (kt + 2 < nk) G_LOAD(wA, xA, kt + 2);
;     G_COMPUTE(0);
;     G_STORE(wB, xB, 1);
;     __syncthreads();
;     if (kt + 3 < nk) G_LOAD(wB, xB, kt + 3);
;     G_COMPUTE(1);
;     if (kt + 2 < nk) G_STORE(wA, xA, 0);
;     __syncthreads();
	global_load_dwordx4 v[166:169], v[148:149], off offset:512
	global_load_dwordx4 v[170:173], v[146:147], off offset:512
	global_load_dwordx4 v[174:177], v[150:151], off offset:512
	global_load_dwordx4 v[178:181], v[152:153], off offset:512
	ds_read_b128 v[182:185], v161
	ds_read_b128 v[186:189], v162
	ds_read_b128 v[206:209], v163 offset:8192
	ds_read_b128 v[214:217], v164 offset:8192
	s_setprio 1
	s_waitcnt lgkmcnt(1)
	v_mfma_f32_32x32x16_bf16 v[48:63], v[182:185], v[206:209], v[48:63]
	s_waitcnt lgkmcnt(0)
	v_mfma_f32_32x32x16_bf16 v[32:47], v[182:185], v[214:217], v[32:47]
	v_mfma_f32_32x32x16_bf16 v[16:31], v[186:189], v[206:209], v[16:31]
	v_mfma_f32_32x32x16_bf16 v[0:15], v[186:189], v[214:217], v[0:15]
	s_setprio 0
	ds_read_b128 v[182:185], v157
	ds_read_b128 v[186:189], v158
	ds_read_b128 v[206:209], v159 offset:8192
	ds_read_b128 v[214:217], v160 offset:8192
	s_setprio 1
	s_waitcnt lgkmcnt(1)
	v_mfma_f32_32x32x16_bf16 v[48:63], v[182:185], v[206:209], v[48:63]
	s_waitcnt lgkmcnt(0)
	v_mfma_f32_32x32x16_bf16 v[32:47], v[182:185], v[214:217], v[32:47]
	v_mfma_f32_32x32x16_bf16 v[16:31], v[186:189], v[206:209], v[16:31]
	v_mfma_f32_32x32x16_bf16 v[0:15], v[186:189], v[214:217], v[0:15]
	s_setprio 0
	s_waitcnt vmcnt(7)
	ds_write_b128 v64, v[66:69] offset:16384
	s_waitcnt vmcnt(5)
	ds_write_b128 v156, v[74:77] offset:16384
	ds_write_b128 v64, v[70:73] offset:24576
	s_waitcnt vmcnt(4)
	ds_write_b128 v156, v[78:81] offset:24576
	s_waitcnt lgkmcnt(0)
	s_barrier
	global_load_dwordx4 v[66:69], v[148:149], off offset:576
	global_load_dwordx4 v[70:73], v[146:147], off offset:576
	global_load_dwordx4 v[74:77], v[150:151], off offset:576
	global_load_dwordx4 v[78:81], v[152:153], off offset:576
	ds_read_b128 v[182:185], v161 offset:16384
	ds_read_b128 v[186:189], v162 offset:16384
	ds_read_b128 v[206:209], v163 offset:24576
	ds_read_b128 v[214:217], v164 offset:24576
	s_setprio 1
	s_waitcnt lgkmcnt(1)
	v_mfma_f32_32x32x16_bf16 v[48:63], v[182:185], v[206:209], v[48:63]
	s_waitcnt lgkmcnt(0)
	v_mfma_f32_32x32x16_bf16 v[32:47], v[182:185], v[214:217], v[32:47]
	v_mfma_f32_32x32x16_bf16 v[16:31], v[186:189], v[206:209], v[16:31]
	v_mfma_f32_32x32x16_bf16 v[0:15], v[186:189], v[214:217], v[0:15]
	s_setprio 0
	ds_read_b128 v[182:185], v157 offset:16384
	ds_read_b128 v[186:189], v158 offset:16384
	ds_read_b128 v[206:209], v159 offset:24576
	ds_read_b128 v[214:217], v160 offset:24576
	s_setprio 1
	s_waitcnt lgkmcnt(1)
	v_mfma_f32_32x32x16_bf16 v[48:63], v[182:185], v[206:209], v[48:63]
	s_waitcnt lgkmcnt(0)
	v_mfma_f32_32x32x16_bf16 v[32:47], v[182:185], v[214:217], v[32:47]
	v_mfma_f32_32x32x16_bf16 v[16:31], v[186:189], v[206:209], v[16:31]
	v_mfma_f32_32x32x16_bf16 v[0:15], v[186:189], v[214:217], v[0:15]
	s_setprio 0
	s_waitcnt vmcnt(7)
	ds_write_b128 v64, v[166:169]
	s_waitcnt vmcnt(5)
	ds_write_b128 v156, v[174:177]
	ds_write_b128 v64, v[170:173] offset:8192
	s_waitcnt vmcnt(4)
	ds_write_b128 v156, v[178:181] offset:8192
	s_waitcnt lgkmcnt(0)
	s_barrier
	global_load_dwordx4 v[166:169], v[148:149], off offset:640
	global_load_dwordx4 v[170:173], v[146:147], off offset:640
	global_load_dwordx4 v[174:177], v[150:151], off offset:640
	global_load_dwordx4 v[178:181], v[152:153], off offset:640
	ds_read_b128 v[182:185], v161
	ds_read_b128 v[186:189], v162
	ds_read_b128 v[206:209], v163 offset:8192
	ds_read_b128 v[214:217], v164 offset:8192
	s_setprio 1
	s_waitcnt lgkmcnt(1)
	v_mfma_f32_32x32x16_bf16 v[48:63], v[182:185], v[206:209], v[48:63]
	s_waitcnt lgkmcnt(0)
	v_mfma_f32_32x32x16_bf16 v[32:47], v[182:185], v[214:217], v[32:47]
	v_mfma_f32_32x32x16_bf16 v[16:31], v[186:189], v[206:209], v[16:31]
	v_mfma_f32_32x32x16_bf16 v[0:15], v[186:189], v[214:217], v[0:15]
	s_setprio 0
	ds_read_b128 v[182:185], v157
	ds_read_b128 v[186:189], v158
	ds_read_b128 v[206:209], v159 offset:8192
	ds_read_b128 v[214:217], v160 offset:8192
	s_setprio 1
	s_waitcnt lgkmcnt(1)
	v_mfma_f32_32x32x16_bf16 v[48:63], v[182:185], v[206:209], v[48:63]
	s_waitcnt lgkmcnt(0)
	v_mfma_f32_32x32x16_bf16 v[32:47], v[182:185], v[214:217], v[32:47]
	v_mfma_f32_32x32x16_bf16 v[16:31], v[186:189], v[206:209], v[16:31]
	v_mfma_f32_32x32x16_bf16 v[0:15], v[186:189], v[214:217], v[0:15]
	s_setprio 0
	s_waitcnt vmcnt(7)
	ds_write_b128 v64, v[66:69] offset:16384
	s_waitcnt vmcnt(5)
	ds_write_b128 v156, v[74:77] offset:16384
	ds_write_b128 v64, v[70:73] offset:24576
	s_waitcnt vmcnt(4)
	ds_write_b128 v156, v[78:81] offset:24576
	s_waitcnt lgkmcnt(0)
	s_barrier
	global_load_dwordx4 v[66:69], v[148:149], off offset:704
	global_load_dwordx4 v[70:73], v[146:147], off offset:704
	global_load_dwordx4 v[74:77], v[150:151], off offset:704
	global_load_dwordx4 v[78:81], v[152:153], off offset:704
	ds_read_b128 v[182:185], v161 offset:16384
	ds_read_b128 v[186:189], v162 offset:16384
	ds_read_b128 v[206:209], v163 offset:24576
	ds_read_b128 v[214:217], v164 offset:24576
	s_setprio 1
	s_waitcnt lgkmcnt(1)
	v_mfma_f32_32x32x16_bf16 v[48:63], v[182:185], v[206:209], v[48:63]
	s_waitcnt lgkmcnt(0)
	v_mfma_f32_32x32x16_bf16 v[32:47], v[182:185], v[214:217], v[32:47]
	v_mfma_f32_32x32x16_bf16 v[16:31], v[186:189], v[206:209], v[16:31]
	v_mfma_f32_32x32x16_bf16 v[0:15], v[186:189], v[214:217], v[0:15]
	s_setprio 0
	ds_read_b128 v[182:185], v157 offset:16384
	ds_read_b128 v[186:189], v158 offset:16384
	ds_read_b128 v[206:209], v159 offset:24576
	ds_read_b128 v[214:217], v160 offset:24576
	s_setprio 1
	s_waitcnt lgkmcnt(1)
	v_mfma_f32_32x32x16_bf16 v[48:63], v[182:185], v[206:209], v[48:63]
	s_waitcnt lgkmcnt(0)
	v_mfma_f32_32x32x16_bf16 v[32:47], v[182:185], v[214:217], v[32:47]
	v_mfma_f32_32x32x16_bf16 v[16:31], v[186:189], v[206:209], v[16:31]
	v_mfma_f32_32x32x16_bf16 v[0:15], v[186:189], v[214:217], v[0:15]
	s_setprio 0
	s_waitcnt vmcnt(7)
	ds_write_b128 v64, v[166:169]
	s_waitcnt vmcnt(5)
	ds_write_b128 v156, v[174:177]
	ds_write_b128 v64, v[170:173] offset:8192
	s_waitcnt vmcnt(4)
	ds_write_b128 v156, v[178:181] offset:8192
	s_waitcnt lgkmcnt(0)
	s_barrier
; template <int TJ>
; DI void gemm_core(const u16* __restrict__ W, int ldw, const u16* __restrict__ X, int ldx, int K, f32x16 (&acc)[2][TJ], char* lds) {
;     ...
;   for (int kt = 0; kt < nk; kt += 2) {
;     if (kt + 2 < nk) G_LOAD(wA, xA, kt + 2);
;     G_COMPUTE(0);
;     G_STORE(wB, xB, 1);
;     __syncthreads();
;     if (kt + 3 < nk) G_LOAD(wB, xB, kt + 3);
;     G_COMPUTE(1);
;     if (kt + 2 < nk) G_STORE(wA, xA, 0);
;     __syncthreads();
	global_load_dwordx4 v[166:169], v[148:149], off offset:768
	global_load_dwordx4 v[170:173], v[146:147], off offset:768
	global_load_dwordx4 v[174:177], v[150:151], off offset:768
	global_load_dwordx4 v[178:181], v[152:153], off offset:768
	ds_read_b128 v[182:185], v161
	ds_read_b128 v[186:189], v162
	ds_read_b128 v[206:209], v163 offset:8192
	ds_read_b128 v[214:217], v164 offset:8192
	s_setprio 1
	s_waitcnt lgkmcnt(1)
	v_mfma_f32_32x32x16_bf16 v[48:63], v[182:185], v[206:209], v[48:63]
	s_waitcnt lgkmcnt(0)
	v_mfma_f32_32x32x16_bf16 v[32:47], v[182:185], v[214:217], v[32:47]
	v_mfma_f32_32x32x16_bf16 v[16:31], v[186:189], v[206:209], v[16:31]
	v_mfma_f32_32x32x16_bf16 v[0:15], v[186:189], v[214:217], v[0:15]
	s_setprio 0
	ds_read_b128 v[182:185], v157
	ds_read_b128 v[186:189], v158
	ds_read_b128 v[206:209], v159 offset:8192
	ds_read_b128 v[214:217], v160 offset:8192
	s_setprio 1
	s_waitcnt lgkmcnt(1)
	v_mfma_f32_32x32x16_bf16 v[48:63], v[182:185], v[206:209], v[48:63]
	s_waitcnt lgkmcnt(0)
	v_mfma_f32_32x32x16_bf16 v[32:47], v[182:185], v[214:217], v[32:47]
	v_mfma_f32_32x32x16_bf16 v[16:31], v[186:189], v[206:209], v[16:31]
	v_mfma_f32_32x32x16_bf16 v[0:15], v[186:189], v[214:217], v[0:15]
	s_setprio 0
	s_waitcnt vmcnt(7)
	ds_write_b128 v64, v[66:69] offset:16384
	s_waitcnt vmcnt(5)
	ds_write_b128 v156, v[74:77] offset:16384
	ds_write_b128 v64, v[70:73] offset:24576
	s_waitcnt vmcnt(4)
	ds_write_b128 v156, v[78:81] offset:24576
	s_waitcnt lgkmcnt(0)
	s_barrier
	global_load_dwordx4 v[66:69], v[148:149], off offset:832
	global_load_dwordx4 v[70:73], v[146:147], off offset:832
	global_load_dwordx4 v[74:77], v[150:151], off offset:832
	global_load_dwordx4 v[78:81], v[152:153], off offset:832
	ds_read_b128 v[182:185], v161 offset:16384
	ds_read_b128 v[186:189], v162 offset:16384
	ds_read_b128 v[206:209], v163 offset:24576
	ds_read_b128 v[214:217], v164 offset:24576
	s_setprio 1
	s_waitcnt lgkmcnt(1)
	v_mfma_f32_32x32x16_bf16 v[48:63], v[182:185], v[206:209], v[48:63]
	s_waitcnt lgkmcnt(0)
	v_mfma_f32_32x32x16_bf16 v[32:47], v[182:185], v[214:217], v[32:47]
	v_mfma_f32_32x32x16_bf16 v[16:31], v[186:189], v[206:209], v[16:31]
	v_mfma_f32_32x32x16_bf16 v[0:15], v[186:189], v[214:217], v[0:15]
	s_setprio 0
	ds_read_b128 v[182:185], v157 offset:16384
	ds_read_b128 v[186:189], v158 offset:16384
	ds_read_b128 v[206:209], v159 offset:24576
	ds_read_b128 v[214:217], v160 offset:24576
	s_setprio 1
	s_waitcnt lgkmcnt(1)
	v_mfma_f32_32x32x16_bf16 v[48:63], v[182:185], v[206:209], v[48:63]
	s_waitcnt lgkmcnt(0)
	v_mfma_f32_32x32x16_bf16 v[32:47], v[182:185], v[214:217], v[32:47]
	v_mfma_f32_32x32x16_bf16 v[16:31], v[186:189], v[206:209], v[16:31]
	v_mfma_f32_32x32x16_bf16 v[0:15], v[186:189], v[214:217], v[0:15]
	s_setprio 0
	s_waitcnt vmcnt(7)
	ds_write_b128 v64, v[166:169]
	s_waitcnt vmcnt(5)
	ds_write_b128 v156, v[174:177]
	ds_write_b128 v64, v[170:173] offset:8192
	s_waitcnt vmcnt(4)
	ds_write_b128 v156, v[178:181] offset:8192
	s_waitcnt lgkmcnt(0)
	s_barrier
	global_load_dwordx4 v[166:169], v[148:149], off offset:896
	global_load_dwordx4 v[170:173], v[146:147], off offset:896
	global_load_dwordx4 v[174:177], v[150:151], off offset:896
	global_load_dwordx4 v[178:181], v[152:153], off offset:896
	ds_read_b128 v[182:185], v161
	ds_read_b128 v[186:189], v162
	ds_read_b128 v[206:209], v163 offset:8192
	ds_read_b128 v[214:217], v164 offset:8192
	s_setprio 1
	s_waitcnt lgkmcnt(1)
	v_mfma_f32_32x32x16_bf16 v[48:63], v[182:185], v[206:209], v[48:63]
	s_waitcnt lgkmcnt(0)
	v_mfma_f32_32x32x16_bf16 v[32:47], v[182:185], v[214:217], v[32:47]
	v_mfma_f32_32x32x16_bf16 v[16:31], v[186:189], v[206:209], v[16:31]
	v_mfma_f32_32x32x16_bf16 v[0:15], v[186:189], v[214:217], v[0:15]
	s_setprio 0
	ds_read_b128 v[182:185], v157
	ds_read_b128 v[186:189], v158
	ds_read_b128 v[206:209], v159 offset:8192
	ds_read_b128 v[214:217], v160 offset:8192
	s_setprio 1
	s_waitcnt lgkmcnt(1)
	v_mfma_f32_32x32x16_bf16 v[48:63], v[182:185], v[206:209], v[48:63]
	s_waitcnt lgkmcnt(0)
	v_mfma_f32_32x32x16_bf16 v[32:47], v[182:185], v[214:217], v[32:47]
	v_mfma_f32_32x32x16_bf16 v[16:31], v[186:189], v[206:209], v[16:31]
	v_mfma_f32_32x32x16_bf16 v[0:15], v[186:189], v[214:217], v[0:15]
	s_setprio 0
	s_waitcnt vmcnt(7)
	ds_write_b128 v64, v[66:69] offset:16384
	s_waitcnt vmcnt(5)
	ds_write_b128 v156, v[74:77] offset:16384
	ds_write_b128 v64, v[70:73] offset:24576
	s_waitcnt vmcnt(4)
	ds_write_b128 v156, v[78:81] offset:24576
	s_waitcnt lgkmcnt(0)
	s_barrier
	global_load_dwordx4 v[66:69], v[148:149], off offset:960
	global_load_dwordx4 v[70:73], v[146:147], off offset:960
	global_load_dwordx4 v[74:77], v[150:151], off offset:960
	global_load_dwordx4 v[78:81], v[152:153], off offset:960
	ds_read_b128 v[182:185], v161 offset:16384
	ds_read_b128 v[186:189], v162 offset:16384
	ds_read_b128 v[206:209], v163 offset:24576
	ds_read_b128 v[214:217], v164 offset:24576
	s_setprio 1
	s_waitcnt lgkmcnt(1)
	v_mfma_f32_32x32x16_bf16 v[48:63], v[182:185], v[206:209], v[48:63]
	s_waitcnt lgkmcnt(0)
	v_mfma_f32_32x32x16_bf16 v[32:47], v[182:185], v[214:217], v[32:47]
	v_mfma_f32_32x32x16_bf16 v[16:31], v[186:189], v[206:209], v[16:31]
	v_mfma_f32_32x32x16_bf16 v[0:15], v[186:189], v[214:217], v[0:15]
	s_setprio 0
	ds_read_b128 v[182:185], v157 offset:16384
	ds_read_b128 v[186:189], v158 offset:16384
	ds_read_b128 v[206:209], v159 offset:24576
	ds_read_b128 v[214:217], v160 offset:24576
	s_setprio 1
	s_waitcnt lgkmcnt(1)
	v_mfma_f32_32x32x16_bf16 v[48:63], v[182:185], v[206:209], v[48:63]
	s_waitcnt lgkmcnt(0)
	v_mfma_f32_32x32x16_bf16 v[32:47], v[182:185], v[214:217], v[32:47]
	v_mfma_f32_32x32x16_bf16 v[16:31], v[186:189], v[206:209], v[16:31]
	v_mfma_f32_32x32x16_bf16 v[0:15], v[186:189], v[214:217], v[0:15]
	s_setprio 0
	s_waitcnt vmcnt(7)
	ds_write_b128 v64, v[166:169]
	s_waitcnt vmcnt(5)
	ds_write_b128 v156, v[174:177]
	ds_write_b128 v64, v[170:173] offset:8192
	s_waitcnt vmcnt(4)
	ds_write_b128 v156, v[178:181] offset:8192
	s_waitcnt lgkmcnt(0)
	s_barrier
; template <int TJ>
; DI void gemm_core(const u16* __restrict__ W, int ldw, const u16* __restrict__ X, int ldx, int K, f32x16 (&acc)[2][TJ], char* lds) {
;     ...
;   for (int kt = 0; kt < nk; kt += 2) {
;     if (kt + 2 < nk) G_LOAD(wA, xA, kt + 2);
;     G_COMPUTE(0);
;     G_STORE(wB, xB, 1);
;     __syncthreads();
;     if (kt + 3 < nk) G_LOAD(wB, xB, kt + 3);
;     G_COMPUTE(1);
;     if (kt + 2 < nk) G_STORE(wA, xA, 0);
;     __syncthreads();
	global_load_dwordx4 v[166:169], v[148:149], off offset:1024
	global_load_dwordx4 v[170:173], v[146:147], off offset:1024
	global_load_dwordx4 v[174:177], v[150:151], off offset:1024
	global_load_dwordx4 v[178:181], v[152:153], off offset:1024
	ds_read_b128 v[182:185], v161
	ds_read_b128 v[186:189], v162
	ds_read_b128 v[206:209], v163 offset:8192
	ds_read_b128 v[214:217], v164 offset:8192
	s_setprio 1
	s_waitcnt lgkmcnt(1)
	v_mfma_f32_32x32x16_bf16 v[48:63], v[182:185], v[206:209], v[48:63]
	s_waitcnt lgkmcnt(0)
	v_mfma_f32_32x32x16_bf16 v[32:47], v[182:185], v[214:217], v[32:47]
	v_mfma_f32_32x32x16_bf16 v[16:31], v[186:189], v[206:209], v[16:31]
	v_mfma_f32_32x32x16_bf16 v[0:15], v[186:189], v[214:217], v[0:15]
	s_setprio 0
	ds_read_b128 v[182:185], v157
	ds_read_b128 v[186:189], v158
	ds_read_b128 v[206:209], v159 offset:8192
	ds_read_b128 v[214:217], v160 offset:8192
	s_setprio 1
	s_waitcnt lgkmcnt(1)
	v_mfma_f32_32x32x16_bf16 v[48:63], v[182:185], v[206:209], v[48:63]
	s_waitcnt lgkmcnt(0)
	v_mfma_f32_32x32x16_bf16 v[32:47], v[182:185], v[214:217], v[32:47]
	v_mfma_f32_32x32x16_bf16 v[16:31], v[186:189], v[206:209], v[16:31]
	v_mfma_f32_32x32x16_bf16 v[0:15], v[186:189], v[214:217], v[0:15]
	s_setprio 0
	s_waitcnt vmcnt(7)
	ds_write_b128 v64, v[66:69] offset:16384
	s_waitcnt vmcnt(5)
	ds_write_b128 v156, v[74:77] offset:16384
	ds_write_b128 v64, v[70:73] offset:24576
	s_waitcnt vmcnt(4)
	ds_write_b128 v156, v[78:81] offset:24576
	s_waitcnt lgkmcnt(0)
	s_barrier
	global_load_dwordx4 v[66:69], v[148:149], off offset:1088
	global_load_dwordx4 v[70:73], v[146:147], off offset:1088
	global_load_dwordx4 v[74:77], v[150:151], off offset:1088
	global_load_dwordx4 v[78:81], v[152:153], off offset:1088
	ds_read_b128 v[182:185], v161 offset:16384
	ds_read_b128 v[186:189], v162 offset:16384
	ds_read_b128 v[206:209], v163 offset:24576
	ds_read_b128 v[214:217], v164 offset:24576
	s_setprio 1
	s_waitcnt lgkmcnt(1)
	v_mfma_f32_32x32x16_bf16 v[48:63], v[182:185], v[206:209], v[48:63]
	s_waitcnt lgkmcnt(0)
	v_mfma_f32_32x32x16_bf16 v[32:47], v[182:185], v[214:217], v[32:47]
	v_mfma_f32_32x32x16_bf16 v[16:31], v[186:189], v[206:209], v[16:31]
	v_mfma_f32_32x32x16_bf16 v[0:15], v[186:189], v[214:217], v[0:15]
	s_setprio 0
	ds_read_b128 v[182:185], v157 offset:16384
	ds_read_b128 v[186:189], v158 offset:16384
	ds_read_b128 v[206:209], v159 offset:24576
	ds_read_b128 v[214:217], v160 offset:24576
	s_setprio 1
	s_waitcnt lgkmcnt(1)
	v_mfma_f32_32x32x16_bf16 v[48:63], v[182:185], v[206:209], v[48:63]
	s_waitcnt lgkmcnt(0)
	v_mfma_f32_32x32x16_bf16 v[32:47], v[182:185], v[214:217], v[32:47]
	v_mfma_f32_32x32x16_bf16 v[16:31], v[186:189], v[206:209], v[16:31]
	v_mfma_f32_32x32x16_bf16 v[0:15], v[186:189], v[214:217], v[0:15]
	s_setprio 0
	s_waitcnt vmcnt(7)
	ds_write_b128 v64, v[166:169]
	s_waitcnt vmcnt(5)
	ds_write_b128 v156, v[174:177]
	ds_write_b128 v64, v[170:173] offset:8192
	s_waitcnt vmcnt(4)
	ds_write_b128 v156, v[178:181] offset:8192
	s_waitcnt lgkmcnt(0)
	s_barrier
	global_load_dwordx4 v[166:169], v[148:149], off offset:1152
	global_load_dwordx4 v[170:173], v[146:147], off offset:1152
	global_load_dwordx4 v[174:177], v[150:151], off offset:1152
	global_load_dwordx4 v[178:181], v[152:153], off offset:1152
	ds_read_b128 v[182:185], v161
	ds_read_b128 v[186:189], v162
	ds_read_b128 v[206:209], v163 offset:8192
	ds_read_b128 v[214:217], v164 offset:8192
	s_setprio 1
	s_waitcnt lgkmcnt(1)
	v_mfma_f32_32x32x16_bf16 v[48:63], v[182:185], v[206:209], v[48:63]
	s_waitcnt lgkmcnt(0)
	v_mfma_f32_32x32x16_bf16 v[32:47], v[182:185], v[214:217], v[32:47]
	v_mfma_f32_32x32x16_bf16 v[16:31], v[186:189], v[206:209], v[16:31]
	v_mfma_f32_32x32x16_bf16 v[0:15], v[186:189], v[214:217], v[0:15]
	s_setprio 0
	ds_read_b128 v[182:185], v157
	ds_read_b128 v[186:189], v158
	ds_read_b128 v[206:209], v159 offset:8192
	ds_read_b128 v[214:217], v160 offset:8192
	s_setprio 1
	s_waitcnt lgkmcnt(1)
	v_mfma_f32_32x32x16_bf16 v[48:63], v[182:185], v[206:209], v[48:63]
	s_waitcnt lgkmcnt(0)
	v_mfma_f32_32x32x16_bf16 v[32:47], v[182:185], v[214:217], v[32:47]
	v_mfma_f32_32x32x16_bf16 v[16:31], v[186:189], v[206:209], v[16:31]
	v_mfma_f32_32x32x16_bf16 v[0:15], v[186:189], v[214:217], v[0:15]
	s_setprio 0
	s_waitcnt vmcnt(7)
	ds_write_b128 v64, v[66:69] offset:16384
	s_waitcnt vmcnt(5)
	ds_write_b128 v156, v[74:77] offset:16384
	ds_write_b128 v64, v[70:73] offset:24576
	s_waitcnt vmcnt(4)
	ds_write_b128 v156, v[78:81] offset:24576
	s_waitcnt lgkmcnt(0)
	s_barrier
	global_load_dwordx4 v[66:69], v[148:149], off offset:1216
	global_load_dwordx4 v[70:73], v[146:147], off offset:1216
	global_load_dwordx4 v[74:77], v[150:151], off offset:1216
	global_load_dwordx4 v[78:81], v[152:153], off offset:1216
	ds_read_b128 v[182:185], v161 offset:16384
	ds_read_b128 v[186:189], v162 offset:16384
	ds_read_b128 v[206:209], v163 offset:24576
	ds_read_b128 v[214:217], v164 offset:24576
	s_setprio 1
	s_waitcnt lgkmcnt(1)
	v_mfma_f32_32x32x16_bf16 v[48:63], v[182:185], v[206:209], v[48:63]
	s_waitcnt lgkmcnt(0)
	v_mfma_f32_32x32x16_bf16 v[32:47], v[182:185], v[214:217], v[32:47]
	v_mfma_f32_32x32x16_bf16 v[16:31], v[186:189], v[206:209], v[16:31]
	v_mfma_f32_32x32x16_bf16 v[0:15], v[186:189], v[214:217], v[0:15]
	s_setprio 0
	ds_read_b128 v[182:185], v157 offset:16384
	ds_read_b128 v[186:189], v158 offset:16384
	ds_read_b128 v[206:209], v159 offset:24576
	ds_read_b128 v[214:217], v160 offset:24576
	s_setprio 1
	s_waitcnt lgkmcnt(1)
	v_mfma_f32_32x32x16_bf16 v[48:63], v[182:185], v[206:209], v[48:63]
	s_waitcnt lgkmcnt(0)
	v_mfma_f32_32x32x16_bf16 v[32:47], v[182:185], v[214:217], v[32:47]
	v_mfma_f32_32x32x16_bf16 v[16:31], v[186:189], v[206:209], v[16:31]
	v_mfma_f32_32x32x16_bf16 v[0:15], v[186:189], v[214:217], v[0:15]
	s_setprio 0
	s_waitcnt vmcnt(7)
	ds_write_b128 v64, v[166:169]
	s_waitcnt vmcnt(5)
	ds_write_b128 v156, v[174:177]
	ds_write_b128 v64, v[170:173] offset:8192
	s_waitcnt vmcnt(4)
	ds_write_b128 v156, v[178:181] offset:8192
	s_waitcnt lgkmcnt(0)
	s_barrier
; template <int TJ>
; DI void gemm_core(const u16* __restrict__ W, int ldw, const u16* __restrict__ X, int ldx, int K, f32x16 (&acc)[2][TJ], char* lds) {
;     ...
;   for (int kt = 0; kt < nk; kt += 2) {
;     if (kt + 2 < nk) G_LOAD(wA, xA, kt + 2);
;     G_COMPUTE(0);
;     G_STORE(wB, xB, 1);
;     __syncthreads();
;     if (kt + 3 < nk) G_LOAD(wB, xB, kt + 3);
;     G_COMPUTE(1);
;     if (kt + 2 < nk) G_STORE(wA, xA, 0);
;     __syncthreads();
	global_load_dwordx4 v[166:169], v[148:149], off offset:1280
	global_load_dwordx4 v[170:173], v[146:147], off offset:1280
	global_load_dwordx4 v[174:177], v[150:151], off offset:1280
	global_load_dwordx4 v[178:181], v[152:153], off offset:1280
	ds_read_b128 v[182:185], v161
	ds_read_b128 v[186:189], v162
	ds_read_b128 v[206:209], v163 offset:8192
	ds_read_b128 v[214:217], v164 offset:8192
	s_setprio 1
	s_waitcnt lgkmcnt(1)
	v_mfma_f32_32x32x16_bf16 v[48:63], v[182:185], v[206:209], v[48:63]
	s_waitcnt lgkmcnt(0)
	v_mfma_f32_32x32x16_bf16 v[32:47], v[182:185], v[214:217], v[32:47]
	v_mfma_f32_32x32x16_bf16 v[16:31], v[186:189], v[206:209], v[16:31]
	v_mfma_f32_32x32x16_bf16 v[0:15], v[186:189], v[214:217], v[0:15]
	s_setprio 0
	ds_read_b128 v[182:185], v157
	ds_read_b128 v[186:189], v158
	ds_read_b128 v[206:209], v159 offset:8192
	ds_read_b128 v[214:217], v160 offset:8192
	s_setprio 1
	s_waitcnt lgkmcnt(1)
	v_mfma_f32_32x32x16_bf16 v[48:63], v[182:185], v[206:209], v[48:63]
	s_waitcnt lgkmcnt(0)
	v_mfma_f32_32x32x16_bf16 v[32:47], v[182:185], v[214:217], v[32:47]
	v_mfma_f32_32x32x16_bf16 v[16:31], v[186:189], v[206:209], v[16:31]
	v_mfma_f32_32x32x16_bf16 v[0:15], v[186:189], v[214:217], v[0:15]
	s_setprio 0
	s_waitcnt vmcnt(7)
	ds_write_b128 v64, v[66:69] offset:16384
	s_waitcnt vmcnt(5)
	ds_write_b128 v156, v[74:77] offset:16384
	ds_write_b128 v64, v[70:73] offset:24576
	s_waitcnt vmcnt(4)
	ds_write_b128 v156, v[78:81] offset:24576
	s_waitcnt lgkmcnt(0)
	s_barrier
	global_load_dwordx4 v[66:69], v[148:149], off offset:1344
	global_load_dwordx4 v[70:73], v[146:147], off offset:1344
	global_load_dwordx4 v[74:77], v[150:151], off offset:1344
	global_load_dwordx4 v[78:81], v[152:153], off offset:1344
	ds_read_b128 v[182:185], v161 offset:16384
	ds_read_b128 v[186:189], v162 offset:16384
	ds_read_b128 v[206:209], v163 offset:24576
	ds_read_b128 v[214:217], v164 offset:24576
	s_setprio 1
	s_waitcnt lgkmcnt(1)
	v_mfma_f32_32x32x16_bf16 v[48:63], v[182:185], v[206:209], v[48:63]
	s_waitcnt lgkmcnt(0)
	v_mfma_f32_32x32x16_bf16 v[32:47], v[182:185], v[214:217], v[32:47]
	v_mfma_f32_32x32x16_bf16 v[16:31], v[186:189], v[206:209], v[16:31]
	v_mfma_f32_32x32x16_bf16 v[0:15], v[186:189], v[214:217], v[0:15]
	s_setprio 0
	ds_read_b128 v[182:185], v157 offset:16384
	ds_read_b128 v[186:189], v158 offset:16384
	ds_read_b128 v[206:209], v159 offset:24576
	ds_read_b128 v[214:217], v160 offset:24576
	s_setprio 1
	s_waitcnt lgkmcnt(1)
	v_mfma_f32_32x32x16_bf16 v[48:63], v[182:185], v[206:209], v[48:63]
	s_waitcnt lgkmcnt(0)
	v_mfma_f32_32x32x16_bf16 v[32:47], v[182:185], v[214:217], v[32:47]
	v_mfma_f32_32x32x16_bf16 v[16:31], v[186:189], v[206:209], v[16:31]
	v_mfma_f32_32x32x16_bf16 v[0:15], v[186:189], v[214:217], v[0:15]
	s_setprio 0
	s_waitcnt vmcnt(7)
	ds_write_b128 v64, v[166:169]
	s_waitcnt vmcnt(5)
	ds_write_b128 v156, v[174:177]
	ds_write_b128 v64, v[170:173] offset:8192
	s_waitcnt vmcnt(4)
	ds_write_b128 v156, v[178:181] offset:8192
	s_waitcnt lgkmcnt(0)
	s_barrier
	global_load_dwordx4 v[166:169], v[148:149], off offset:1408
	global_load_dwordx4 v[170:173], v[146:147], off offset:1408
	global_load_dwordx4 v[174:177], v[150:151], off offset:1408
	global_load_dwordx4 v[178:181], v[152:153], off offset:1408
	ds_read_b128 v[182:185], v161
	ds_read_b128 v[186:189], v162
	ds_read_b128 v[206:209], v163 offset:8192
	ds_read_b128 v[214:217], v164 offset:8192
	s_setprio 1
	s_waitcnt lgkmcnt(1)
	v_mfma_f32_32x32x16_bf16 v[48:63], v[182:185], v[206:209], v[48:63]
	s_waitcnt lgkmcnt(0)
	v_mfma_f32_32x32x16_bf16 v[32:47], v[182:185], v[214:217], v[32:47]
	v_mfma_f32_32x32x16_bf16 v[16:31], v[186:189], v[206:209], v[16:31]
	v_mfma_f32_32x32x16_bf16 v[0:15], v[186:189], v[214:217], v[0:15]
	s_setprio 0
	ds_read_b128 v[182:185], v157
	ds_read_b128 v[186:189], v158
	ds_read_b128 v[206:209], v159 offset:8192
	ds_read_b128 v[214:217], v160 offset:8192
	s_setprio 1
	s_waitcnt lgkmcnt(1)
	v_mfma_f32_32x32x16_bf16 v[48:63], v[182:185], v[206:209], v[48:63]
	s_waitcnt lgkmcnt(0)
	v_mfma_f32_32x32x16_bf16 v[32:47], v[182:185], v[214:217], v[32:47]
	v_mfma_f32_32x32x16_bf16 v[16:31], v[186:189], v[206:209], v[16:31]
	v_mfma_f32_32x32x16_bf16 v[0:15], v[186:189], v[214:217], v[0:15]
	s_setprio 0
	s_waitcnt vmcnt(7)
	ds_write_b128 v64, v[66:69] offset:16384
	s_waitcnt vmcnt(5)
	ds_write_b128 v156, v[74:77] offset:16384
	ds_write_b128 v64, v[70:73] offset:24576
	s_waitcnt vmcnt(4)
	ds_write_b128 v156, v[78:81] offset:24576
	s_waitcnt lgkmcnt(0)
	s_barrier
	global_load_dwordx4 v[66:69], v[148:149], off offset:1472
	global_load_dwordx4 v[70:73], v[146:147], off offset:1472
	global_load_dwordx4 v[74:77], v[150:151], off offset:1472
	global_load_dwordx4 v[78:81], v[152:153], off offset:1472
	ds_read_b128 v[182:185], v161 offset:16384
	ds_read_b128 v[186:189], v162 offset:16384
	ds_read_b128 v[206:209], v163 offset:24576
	ds_read_b128 v[214:217], v164 offset:24576
	s_setprio 1
	s_waitcnt lgkmcnt(1)
	v_mfma_f32_32x32x16_bf16 v[48:63], v[182:185], v[206:209], v[48:63]
	s_waitcnt lgkmcnt(0)
	v_mfma_f32_32x32x16_bf16 v[32:47], v[182:185], v[214:217], v[32:47]
	v_mfma_f32_32x32x16_bf16 v[16:31], v[186:189], v[206:209], v[16:31]
	v_mfma_f32_32x32x16_bf16 v[0:15], v[186:189], v[214:217], v[0:15]
	s_setprio 0
	ds_read_b128 v[182:185], v157 offset:16384
	ds_read_b128 v[186:189], v158 offset:16384
	ds_read_b128 v[206:209], v159 offset:24576
	ds_read_b128 v[214:217], v160 offset:24576
	s_setprio 1
	s_waitcnt lgkmcnt(1)
	v_mfma_f32_32x32x16_bf16 v[48:63], v[182:185], v[206:209], v[48:63]
	s_waitcnt lgkmcnt(0)
	v_mfma_f32_32x32x16_bf16 v[32:47], v[182:185], v[214:217], v[32:47]
	v_mfma_f32_32x32x16_bf16 v[16:31], v[186:189], v[206:209], v[16:31]
	v_mfma_f32_32x32x16_bf16 v[0:15], v[186:189], v[214:217], v[0:15]
	s_setprio 0
	s_waitcnt vmcnt(7)
	ds_write_b128 v64, v[166:169]
	s_waitcnt vmcnt(5)
	ds_write_b128 v156, v[174:177]
	ds_write_b128 v64, v[170:173] offset:8192
	s_waitcnt vmcnt(4)
	ds_write_b128 v156, v[178:181] offset:8192
	s_waitcnt lgkmcnt(0)
	s_barrier
; template <int TJ>
; DI void gemm_core(const u16* __restrict__ W, int ldw, const u16* __restrict__ X, int ldx, int K, f32x16 (&acc)[2][TJ], char* lds) {
;     ...
;   for (int kt = 0; kt < nk; kt += 2) {
;     if (kt + 2 < nk) G_LOAD(wA, xA, kt + 2);
;     G_COMPUTE(0);
;     G_STORE(wB, xB, 1);
;     __syncthreads();
;     if (kt + 3 < nk) G_LOAD(wB, xB, kt + 3);
;     G_COMPUTE(1);
;     if (kt + 2 < nk) G_STORE(wA, xA, 0);
;     __syncthreads();
	global_load_dwordx4 v[166:169], v[148:149], off offset:1536
	global_load_dwordx4 v[170:173], v[146:147], off offset:1536
	global_load_dwordx4 v[174:177], v[150:151], off offset:1536
	global_load_dwordx4 v[178:181], v[152:153], off offset:1536
	ds_read_b128 v[182:185], v161
	ds_read_b128 v[186:189], v162
	ds_read_b128 v[206:209], v163 offset:8192
	ds_read_b128 v[214:217], v164 offset:8192
	s_setprio 1
	s_waitcnt lgkmcnt(1)
	v_mfma_f32_32x32x16_bf16 v[48:63], v[182:185], v[206:209], v[48:63]
	s_waitcnt lgkmcnt(0)
	v_mfma_f32_32x32x16_bf16 v[32:47], v[182:185], v[214:217], v[32:47]
	v_mfma_f32_32x32x16_bf16 v[16:31], v[186:189], v[206:209], v[16:31]
	v_mfma_f32_32x32x16_bf16 v[0:15], v[186:189], v[214:217], v[0:15]
	s_setprio 0
	ds_read_b128 v[182:185], v157
	ds_read_b128 v[186:189], v158
	ds_read_b128 v[206:209], v159 offset:8192
	ds_read_b128 v[214:217], v160 offset:8192
	s_setprio 1
	s_waitcnt lgkmcnt(1)
	v_mfma_f32_32x32x16_bf16 v[48:63], v[182:185], v[206:209], v[48:63]
	s_waitcnt lgkmcnt(0)
	v_mfma_f32_32x32x16_bf16 v[32:47], v[182:185], v[214:217], v[32:47]
	v_mfma_f32_32x32x16_bf16 v[16:31], v[186:189], v[206:209], v[16:31]
	v_mfma_f32_32x32x16_bf16 v[0:15], v[186:189], v[214:217], v[0:15]
	s_setprio 0
	s_waitcnt vmcnt(7)
	ds_write_b128 v64, v[66:69] offset:16384
	s_waitcnt vmcnt(5)
	ds_write_b128 v156, v[74:77] offset:16384
	ds_write_b128 v64, v[70:73] offset:24576
	s_waitcnt vmcnt(4)
	ds_write_b128 v156, v[78:81] offset:24576
	s_waitcnt lgkmcnt(0)
	s_barrier
	global_load_dwordx4 v[66:69], v[148:149], off offset:1600
	global_load_dwordx4 v[70:73], v[146:147], off offset:1600
	global_load_dwordx4 v[74:77], v[150:151], off offset:1600
	global_load_dwordx4 v[78:81], v[152:153], off offset:1600
	ds_read_b128 v[182:185], v161 offset:16384
	ds_read_b128 v[186:189], v162 offset:16384
	ds_read_b128 v[206:209], v163 offset:24576
	ds_read_b128 v[214:217], v164 offset:24576
	s_setprio 1
	s_waitcnt lgkmcnt(1)
	v_mfma_f32_32x32x16_bf16 v[48:63], v[182:185], v[206:209], v[48:63]
	s_waitcnt lgkmcnt(0)
	v_mfma_f32_32x32x16_bf16 v[32:47], v[182:185], v[214:217], v[32:47]
	v_mfma_f32_32x32x16_bf16 v[16:31], v[186:189], v[206:209], v[16:31]
	v_mfma_f32_32x32x16_bf16 v[0:15], v[186:189], v[214:217], v[0:15]
	s_setprio 0
	ds_read_b128 v[182:185], v157 offset:16384
	ds_read_b128 v[186:189], v158 offset:16384
	ds_read_b128 v[206:209], v159 offset:24576
	ds_read_b128 v[214:217], v160 offset:24576
	s_setprio 1
	s_waitcnt lgkmcnt(1)
	v_mfma_f32_32x32x16_bf16 v[48:63], v[182:185], v[206:209], v[48:63]
	s_waitcnt lgkmcnt(0)
	v_mfma_f32_32x32x16_bf16 v[32:47], v[182:185], v[214:217], v[32:47]
	v_mfma_f32_32x32x16_bf16 v[16:31], v[186:189], v[206:209], v[16:31]
	v_mfma_f32_32x32x16_bf16 v[0:15], v[186:189], v[214:217], v[0:15]
	s_setprio 0
	s_waitcnt vmcnt(7)
	ds_write_b128 v64, v[166:169]
	s_waitcnt vmcnt(5)
	ds_write_b128 v156, v[174:177]
	ds_write_b128 v64, v[170:173] offset:8192
	s_waitcnt vmcnt(4)
	ds_write_b128 v156, v[178:181] offset:8192
	s_waitcnt lgkmcnt(0)
	s_barrier
	global_load_dwordx4 v[166:169], v[148:149], off offset:1664
	global_load_dwordx4 v[170:173], v[146:147], off offset:1664
	global_load_dwordx4 v[174:177], v[150:151], off offset:1664
	global_load_dwordx4 v[178:181], v[152:153], off offset:1664
	ds_read_b128 v[182:185], v161
	ds_read_b128 v[186:189], v162
	ds_read_b128 v[206:209], v163 offset:8192
	ds_read_b128 v[214:217], v164 offset:8192
	s_setprio 1
	s_waitcnt lgkmcnt(1)
	v_mfma_f32_32x32x16_bf16 v[48:63], v[182:185], v[206:209], v[48:63]
	s_waitcnt lgkmcnt(0)
	v_mfma_f32_32x32x16_bf16 v[32:47], v[182:185], v[214:217], v[32:47]
	v_mfma_f32_32x32x16_bf16 v[16:31], v[186:189], v[206:209], v[16:31]
	v_mfma_f32_32x32x16_bf16 v[0:15], v[186:189], v[214:217], v[0:15]
	s_setprio 0
	ds_read_b128 v[182:185], v157
	ds_read_b128 v[186:189], v158
	ds_read_b128 v[206:209], v159 offset:8192
	ds_read_b128 v[214:217], v160 offset:8192
	s_setprio 1
	s_waitcnt lgkmcnt(1)
	v_mfma_f32_32x32x16_bf16 v[48:63], v[182:185], v[206:209], v[48:63]
	s_waitcnt lgkmcnt(0)
	v_mfma_f32_32x32x16_bf16 v[32:47], v[182:185], v[214:217], v[32:47]
	v_mfma_f32_32x32x16_bf16 v[16:31], v[186:189], v[206:209], v[16:31]
	v_mfma_f32_32x32x16_bf16 v[0:15], v[186:189], v[214:217], v[0:15]
	s_setprio 0
	s_waitcnt vmcnt(7)
	ds_write_b128 v64, v[66:69] offset:16384
	s_waitcnt vmcnt(5)
	ds_write_b128 v156, v[74:77] offset:16384
	ds_write_b128 v64, v[70:73] offset:24576
	s_waitcnt vmcnt(4)
	ds_write_b128 v156, v[78:81] offset:24576
	s_waitcnt lgkmcnt(0)
	s_barrier
	global_load_dwordx4 v[66:69], v[148:149], off offset:1728
	global_load_dwordx4 v[70:73], v[146:147], off offset:1728
	global_load_dwordx4 v[74:77], v[150:151], off offset:1728
	global_load_dwordx4 v[78:81], v[152:153], off offset:1728
	ds_read_b128 v[182:185], v161 offset:16384
	ds_read_b128 v[186:189], v162 offset:16384
	ds_read_b128 v[206:209], v163 offset:24576
	ds_read_b128 v[214:217], v164 offset:24576
	s_setprio 1
	s_waitcnt lgkmcnt(1)
	v_mfma_f32_32x32x16_bf16 v[48:63], v[182:185], v[206:209], v[48:63]
	s_waitcnt lgkmcnt(0)
	v_mfma_f32_32x32x16_bf16 v[32:47], v[182:185], v[214:217], v[32:47]
	v_mfma_f32_32x32x16_bf16 v[16:31], v[186:189], v[206:209], v[16:31]
	v_mfma_f32_32x32x16_bf16 v[0:15], v[186:189], v[214:217], v[0:15]
	s_setprio 0
	ds_read_b128 v[182:185], v157 offset:16384
	ds_read_b128 v[186:189], v158 offset:16384
	ds_read_b128 v[206:209], v159 offset:24576
	ds_read_b128 v[214:217], v160 offset:24576
	s_setprio 1
	s_waitcnt lgkmcnt(1)
	v_mfma_f32_32x32x16_bf16 v[48:63], v[182:185], v[206:209], v[48:63]
	s_waitcnt lgkmcnt(0)
	v_mfma_f32_32x32x16_bf16 v[32:47], v[182:185], v[214:217], v[32:47]
	v_mfma_f32_32x32x16_bf16 v[16:31], v[186:189], v[206:209], v[16:31]
	v_mfma_f32_32x32x16_bf16 v[0:15], v[186:189], v[214:217], v[0:15]
	s_setprio 0
	s_waitcnt vmcnt(7)
	ds_write_b128 v64, v[166:169]
	s_waitcnt vmcnt(5)
	ds_write_b128 v156, v[174:177]
	ds_write_b128 v64, v[170:173] offset:8192
	s_waitcnt vmcnt(4)
	ds_write_b128 v156, v[178:181] offset:8192
	s_waitcnt lgkmcnt(0)
	s_barrier
; template <int TJ>
; DI void gemm_core(const u16* __restrict__ W, int ldw, const u16* __restrict__ X, int ldx, int K, f32x16 (&acc)[2][TJ], char* lds) {
;     ...
;   for (int kt = 0; kt < nk; kt += 2) {
;     if (kt + 2 < nk) G_LOAD(wA, xA, kt + 2);
;     G_COMPUTE(0);
;     G_STORE(wB, xB, 1);
;     __syncthreads();
;     if (kt + 3 < nk) G_LOAD(wB, xB, kt + 3);
;     G_COMPUTE(1);
;     if (kt + 2 < nk) G_STORE(wA, xA, 0);
;     __syncthreads();
	global_load_dwordx4 v[166:169], v[148:149], off offset:1792
	global_load_dwordx4 v[170:173], v[146:147], off offset:1792
	global_load_dwordx4 v[174:177], v[150:151], off offset:1792
	global_load_dwordx4 v[178:181], v[152:153], off offset:1792
	ds_read_b128 v[182:185], v161
	ds_read_b128 v[186:189], v162
	ds_read_b128 v[206:209], v163 offset:8192
	ds_read_b128 v[214:217], v164 offset:8192
	s_setprio 1
	s_waitcnt lgkmcnt(1)
	v_mfma_f32_32x32x16_bf16 v[48:63], v[182:185], v[206:209], v[48:63]
	s_waitcnt lgkmcnt(0)
	v_mfma_f32_32x32x16_bf16 v[32:47], v[182:185], v[214:217], v[32:47]
	v_mfma_f32_32x32x16_bf16 v[16:31], v[186:189], v[206:209], v[16:31]
	v_mfma_f32_32x32x16_bf16 v[0:15], v[186:189], v[214:217], v[0:15]
	s_setprio 0
	ds_read_b128 v[182:185], v157
	ds_read_b128 v[186:189], v158
	ds_read_b128 v[206:209], v159 offset:8192
	ds_read_b128 v[214:217], v160 offset:8192
	s_setprio 1
	s_waitcnt lgkmcnt(1)
	v_mfma_f32_32x32x16_bf16 v[48:63], v[182:185], v[206:209], v[48:63]
	s_waitcnt lgkmcnt(0)
	v_mfma_f32_32x32x16_bf16 v[32:47], v[182:185], v[214:217], v[32:47]
	v_mfma_f32_32x32x16_bf16 v[16:31], v[186:189], v[206:209], v[16:31]
	v_mfma_f32_32x32x16_bf16 v[0:15], v[186:189], v[214:217], v[0:15]
	s_setprio 0
	s_waitcnt vmcnt(7)
	ds_write_b128 v64, v[66:69] offset:16384
	s_waitcnt vmcnt(5)
	ds_write_b128 v156, v[74:77] offset:16384
	ds_write_b128 v64, v[70:73] offset:24576
	s_waitcnt vmcnt(4)
	ds_write_b128 v156, v[78:81] offset:24576
	s_waitcnt lgkmcnt(0)
	s_barrier
	global_load_dwordx4 v[66:69], v[148:149], off offset:1856
	global_load_dwordx4 v[70:73], v[146:147], off offset:1856
	global_load_dwordx4 v[74:77], v[150:151], off offset:1856
	global_load_dwordx4 v[78:81], v[152:153], off offset:1856
	ds_read_b128 v[182:185], v161 offset:16384
	ds_read_b128 v[186:189], v162 offset:16384
	ds_read_b128 v[206:209], v163 offset:24576
	ds_read_b128 v[214:217], v164 offset:24576
	s_setprio 1
	s_waitcnt lgkmcnt(1)
	v_mfma_f32_32x32x16_bf16 v[48:63], v[182:185], v[206:209], v[48:63]
	s_waitcnt lgkmcnt(0)
	v_mfma_f32_32x32x16_bf16 v[32:47], v[182:185], v[214:217], v[32:47]
	v_mfma_f32_32x32x16_bf16 v[16:31], v[186:189], v[206:209], v[16:31]
	v_mfma_f32_32x32x16_bf16 v[0:15], v[186:189], v[214:217], v[0:15]
	s_setprio 0
	ds_read_b128 v[182:185], v157 offset:16384
	ds_read_b128 v[186:189], v158 offset:16384
	ds_read_b128 v[206:209], v159 offset:24576
	ds_read_b128 v[214:217], v160 offset:24576
	s_setprio 1
	s_waitcnt lgkmcnt(1)
	v_mfma_f32_32x32x16_bf16 v[48:63], v[182:185], v[206:209], v[48:63]
	s_waitcnt lgkmcnt(0)
	v_mfma_f32_32x32x16_bf16 v[32:47], v[182:185], v[214:217], v[32:47]
	v_mfma_f32_32x32x16_bf16 v[16:31], v[186:189], v[206:209], v[16:31]
	v_mfma_f32_32x32x16_bf16 v[0:15], v[186:189], v[214:217], v[0:15]
	s_setprio 0
	s_waitcnt vmcnt(7)
	ds_write_b128 v64, v[166:169]
	s_waitcnt vmcnt(5)
	ds_write_b128 v156, v[174:177]
	ds_write_b128 v64, v[170:173] offset:8192
	s_waitcnt vmcnt(4)
	ds_write_b128 v156, v[178:181] offset:8192
	s_waitcnt lgkmcnt(0)
	s_barrier
	global_load_dwordx4 v[166:169], v[148:149], off offset:1920
	global_load_dwordx4 v[170:173], v[146:147], off offset:1920
	global_load_dwordx4 v[174:177], v[150:151], off offset:1920
	global_load_dwordx4 v[178:181], v[152:153], off offset:1920
	ds_read_b128 v[182:185], v161
	ds_read_b128 v[186:189], v162
	ds_read_b128 v[206:209], v163 offset:8192
	ds_read_b128 v[214:217], v164 offset:8192
	s_setprio 1
	s_waitcnt lgkmcnt(1)
	v_mfma_f32_32x32x16_bf16 v[48:63], v[182:185], v[206:209], v[48:63]
	s_waitcnt lgkmcnt(0)
	v_mfma_f32_32x32x16_bf16 v[32:47], v[182:185], v[214:217], v[32:47]
	v_mfma_f32_32x32x16_bf16 v[16:31], v[186:189], v[206:209], v[16:31]
	v_mfma_f32_32x32x16_bf16 v[0:15], v[186:189], v[214:217], v[0:15]
	s_setprio 0
	ds_read_b128 v[182:185], v157
	ds_read_b128 v[186:189], v158
	ds_read_b128 v[206:209], v159 offset:8192
	ds_read_b128 v[214:217], v160 offset:8192
	s_setprio 1
	s_waitcnt lgkmcnt(1)
	v_mfma_f32_32x32x16_bf16 v[48:63], v[182:185], v[206:209], v[48:63]
	s_waitcnt lgkmcnt(0)
	v_mfma_f32_32x32x16_bf16 v[32:47], v[182:185], v[214:217], v[32:47]
	v_mfma_f32_32x32x16_bf16 v[16:31], v[186:189], v[206:209], v[16:31]
	v_mfma_f32_32x32x16_bf16 v[0:15], v[186:189], v[214:217], v[0:15]
	s_setprio 0
	s_waitcnt vmcnt(7)
	ds_write_b128 v64, v[66:69] offset:16384
	s_waitcnt vmcnt(5)
	ds_write_b128 v156, v[74:77] offset:16384
	ds_write_b128 v64, v[70:73] offset:24576
	s_waitcnt vmcnt(4)
	ds_write_b128 v156, v[78:81] offset:24576
	s_waitcnt lgkmcnt(0)
	s_barrier
	global_load_dwordx4 v[66:69], v[148:149], off offset:1984
	global_load_dwordx4 v[70:73], v[146:147], off offset:1984
	global_load_dwordx4 v[74:77], v[150:151], off offset:1984
	global_load_dwordx4 v[78:81], v[152:153], off offset:1984
	ds_read_b128 v[146:149], v161 offset:16384
	ds_read_b128 v[150:153], v162 offset:16384
	ds_read_b128 v[182:185], v163 offset:24576
	ds_read_b128 v[186:189], v164 offset:24576
	s_setprio 1
	s_waitcnt lgkmcnt(1)
	v_mfma_f32_32x32x16_bf16 v[48:63], v[146:149], v[182:185], v[48:63]
	s_waitcnt lgkmcnt(0)
	v_mfma_f32_32x32x16_bf16 v[32:47], v[146:149], v[186:189], v[32:47]
	v_mfma_f32_32x32x16_bf16 v[16:31], v[150:153], v[182:185], v[16:31]
	v_mfma_f32_32x32x16_bf16 v[0:15], v[150:153], v[186:189], v[0:15]
	s_setprio 0
	ds_read_b128 v[146:149], v157 offset:16384
	ds_read_b128 v[150:153], v158 offset:16384
	ds_read_b128 v[182:185], v159 offset:24576
	ds_read_b128 v[186:189], v160 offset:24576
	s_setprio 1
	s_waitcnt lgkmcnt(1)
	v_mfma_f32_32x32x16_bf16 v[48:63], v[146:149], v[182:185], v[48:63]
	s_waitcnt lgkmcnt(0)
	v_mfma_f32_32x32x16_bf16 v[32:47], v[146:149], v[186:189], v[32:47]
	v_mfma_f32_32x32x16_bf16 v[16:31], v[150:153], v[182:185], v[16:31]
	v_mfma_f32_32x32x16_bf16 v[0:15], v[150:153], v[186:189], v[0:15]
	s_setprio 0
	s_waitcnt vmcnt(7)
	ds_write_b128 v64, v[166:169]
	s_waitcnt vmcnt(5)
	ds_write_b128 v156, v[174:177]
	ds_write_b128 v64, v[170:173] offset:8192
	s_waitcnt vmcnt(4)
	ds_write_b128 v156, v[178:181] offset:8192
	s_waitcnt lgkmcnt(0)
	s_barrier
; DI unsigned cvtpk(float lo, float hi) { f32x2_t v = {lo, hi}; bf16x2_t b = __builtin_convertvector(v, bf16x2_t); return __builtin_bit_cast(unsigned, b); }
; DI float sigmoidf_(float x) { return __builtin_amdgcn_rcpf(1.f + __expf(-x)); }
; template <int TJ>
; DI void gemm_core(const u16* __restrict__ W, int ldw, const u16* __restrict__ X, int ldx, int K, f32x16 (&acc)[2][TJ], char* lds) {
;     ...
;   for (int kt = 0; kt < nk; kt += 2) {
;     if (kt + 2 < nk) G_LOAD(wA, xA, kt + 2);
;     G_COMPUTE(0);
;     G_STORE(wB, xB, 1);
;     __syncthreads();
;     if (kt + 3 < nk) G_LOAD(wB, xB, kt + 3);
;     G_COMPUTE(1);
;     if (kt + 2 < nk) G_STORE(wA, xA, 0);
;     __syncthreads();
; template <int TJ>
; DI void merge_tile(const Params& p, size_t t0, int nt, char* lds) {
;     ...
;         for (int e = 0; e < 8; ++e) sgl[((i * TJ + j) * 8 + e) * 256] = cvtpk(sigmoidf_(ag[i][j][2 * e]), sigmoidf_(ag[i][j][2 * e + 1]));
	ds_read_b128 v[146:149], v161
	ds_read_b128 v[150:153], v162
	ds_read_b128 v[166:169], v163 offset:8192
	ds_read_b128 v[170:173], v164 offset:8192
	s_setprio 1
	s_waitcnt lgkmcnt(1)
	v_mfma_f32_32x32x16_bf16 v[48:63], v[146:149], v[166:169], v[48:63]
	s_waitcnt lgkmcnt(0)
	v_mfma_f32_32x32x16_bf16 v[32:47], v[146:149], v[170:173], v[32:47]
	v_mfma_f32_32x32x16_bf16 v[16:31], v[150:153], v[166:169], v[16:31]
	v_mfma_f32_32x32x16_bf16 v[0:15], v[150:153], v[170:173], v[0:15]
	s_setprio 0
	ds_read_b128 v[146:149], v157
	ds_read_b128 v[150:153], v158
	ds_read_b128 v[166:169], v159 offset:8192
	ds_read_b128 v[170:173], v160 offset:8192
	s_setprio 1
	s_waitcnt lgkmcnt(1)
	v_mfma_f32_32x32x16_bf16 v[48:63], v[146:149], v[166:169], v[48:63]
	s_waitcnt lgkmcnt(0)
	v_mfma_f32_32x32x16_bf16 v[32:47], v[146:149], v[170:173], v[32:47]
	v_mfma_f32_32x32x16_bf16 v[16:31], v[150:153], v[166:169], v[16:31]
	v_mfma_f32_32x32x16_bf16 v[0:15], v[150:153], v[170:173], v[0:15]
	s_setprio 0
	s_waitcnt vmcnt(3)
	ds_write_b128 v64, v[66:69] offset:16384
	s_waitcnt vmcnt(1)
	ds_write_b128 v156, v[74:77] offset:16384
	ds_write_b128 v64, v[70:73] offset:24576
	s_waitcnt vmcnt(0)
	ds_write_b128 v156, v[78:81] offset:24576
	s_waitcnt lgkmcnt(0)
	s_barrier
	ds_read_b128 v[66:69], v161 offset:16384
	ds_read_b128 v[70:73], v162 offset:16384
	ds_read_b128 v[74:77], v163 offset:24576
	ds_read_b128 v[78:81], v164 offset:24576
	s_setprio 1
	s_waitcnt lgkmcnt(1)
	v_mfma_f32_32x32x16_bf16 v[48:63], v[66:69], v[74:77], v[48:63]
	s_waitcnt lgkmcnt(0)
	v_mfma_f32_32x32x16_bf16 v[32:47], v[66:69], v[78:81], v[32:47]
	v_mfma_f32_32x32x16_bf16 v[16:31], v[70:73], v[74:77], v[16:31]
	v_mfma_f32_32x32x16_bf16 v[0:15], v[70:73], v[78:81], v[0:15]
	s_setprio 0
	ds_read_b128 v[66:69], v157 offset:16384
	ds_read_b128 v[70:73], v158 offset:16384
	ds_read_b128 v[74:77], v159 offset:24576
	ds_read_b128 v[78:81], v160 offset:24576
	s_setprio 1
	s_waitcnt lgkmcnt(1)
	v_mfma_f32_32x32x16_bf16 v[48:63], v[66:69], v[74:77], v[48:63]
	s_waitcnt lgkmcnt(0)
	v_mfma_f32_32x32x16_bf16 v[32:47], v[66:69], v[78:81], v[32:47]
	v_mfma_f32_32x32x16_bf16 v[16:31], v[70:73], v[74:77], v[16:31]
	v_mfma_f32_32x32x16_bf16 v[0:15], v[70:73], v[78:81], v[0:15]
	s_setprio 0
	s_nop 6
	v_mul_f32_e32 v48, 0xbfb8aa3b, v48
	v_mul_f32_e32 v49, 0xbfb8aa3b, v49
	v_mul_f32_e32 v32, 0xbfb8aa3b, v32
	v_mul_f32_e32 v33, 0xbfb8aa3b, v33
	v_mul_f32_e32 v16, 0xbfb8aa3b, v16
	v_mul_f32_e32 v17, 0xbfb8aa3b, v17
	v_mul_f32_e32 v0, 0xbfb8aa3b, v0
	v_mul_f32_e32 v1, 0xbfb8aa3b, v1
	v_exp_f32_e32 v48, v48
	v_exp_f32_e32 v49, v49
	v_exp_f32_e32 v32, v32
	v_exp_f32_e32 v33, v33
	v_exp_f32_e32 v16, v16
	v_exp_f32_e32 v17, v17
	v_exp_f32_e32 v0, v0
	v_exp_f32_e32 v1, v1
	v_add_f32_e32 v48, 1.0, v48
	v_add_f32_e32 v49, 1.0, v49
	v_add_f32_e32 v32, 1.0, v32
	v_add_f32_e32 v33, 1.0, v33
	v_add_f32_e32 v16, 1.0, v16
	v_add_f32_e32 v17, 1.0, v17
	v_add_f32_e32 v0, 1.0, v0
	v_add_f32_e32 v1, 1.0, v1
	v_rcp_f32_e32 v48, v48
	v_rcp_f32_e32 v49, v49
	v_rcp_f32_e32 v32, v32
	v_rcp_f32_e32 v33, v33
	v_rcp_f32_e32 v16, v16
	v_rcp_f32_e32 v17, v17
	v_rcp_f32_e32 v0, v0
	v_rcp_f32_e32 v1, v1
	v_cvt_pk_bf16_f32 v48, v48, v49
	v_mul_f32_e32 v49, 0xbfb8aa3b, v50
	v_mul_f32_e32 v50, 0xbfb8aa3b, v51
	v_cvt_pk_bf16_f32 v32, v32, v33
	v_mul_f32_e32 v33, 0xbfb8aa3b, v34
	v_mul_f32_e32 v34, 0xbfb8aa3b, v35
	v_cvt_pk_bf16_f32 v16, v16, v17
	v_mul_f32_e32 v17, 0xbfb8aa3b, v18
	v_mul_f32_e32 v18, 0xbfb8aa3b, v19
	v_cvt_pk_bf16_f32 v0, v0, v1
	v_mul_f32_e32 v1, 0xbfb8aa3b, v2
	v_mul_f32_e32 v2, 0xbfb8aa3b, v3
	v_exp_f32_e32 v49, v49
	v_exp_f32_e32 v50, v50
	v_exp_f32_e32 v33, v33
	v_exp_f32_e32 v34, v34
	v_exp_f32_e32 v17, v17
	v_exp_f32_e32 v18, v18
	v_exp_f32_e32 v1, v1
	v_exp_f32_e32 v2, v2
	v_add_f32_e32 v49, 1.0, v49
	v_add_f32_e32 v50, 1.0, v50
	v_add_f32_e32 v33, 1.0, v33
	v_add_f32_e32 v34, 1.0, v34
	v_add_f32_e32 v17, 1.0, v17
	v_add_f32_e32 v18, 1.0, v18
	v_add_f32_e32 v1, 1.0, v1
	v_add_f32_e32 v2, 1.0, v2
	v_rcp_f32_e32 v49, v49
	v_rcp_f32_e32 v50, v50
	v_rcp_f32_e32 v33, v33
	v_rcp_f32_e32 v34, v34
	v_rcp_f32_e32 v17, v17
	v_rcp_f32_e32 v18, v18
	v_rcp_f32_e32 v1, v1
	v_rcp_f32_e32 v2, v2
	v_cvt_pk_bf16_f32 v49, v49, v50
	v_cvt_pk_bf16_f32 v33, v33, v34
	v_cvt_pk_bf16_f32 v17, v17, v18
	v_cvt_pk_bf16_f32 v1, v1, v2
	s_barrier
; DI unsigned cvtpk(float lo, float hi) { f32x2_t v = {lo, hi}; bf16x2_t b = __builtin_convertvector(v, bf16x2_t); return __builtin_bit_cast(unsigned, b); }
; DI float sigmoidf_(float x) { return __builtin_amdgcn_rcpf(1.f + __expf(-x)); }
; template <int TJ>
; DI void merge_tile(const Params& p, size_t t0, int nt, char* lds) {
;     ...
;     unsigned* sgl = (unsigned*)(lds + 32768) + tid;
; #pragma unroll
;     for (int i = 0; i < 2; ++i)
; #pragma unroll
;       for (int j = 0; j < TJ; ++j)
; #pragma unroll
;         for (int e = 0; e < 8; ++e) sgl[((i * TJ + j) * 8 + e) * 256] = cvtpk(sigmoidf_(ag[i][j][2 * e]), sigmoidf_(ag[i][j][2 * e + 1]));
	ds_write2st64_b32 v155, v48, v49 offset0:128 offset1:132
	v_mul_f32_e32 v48, 0xbfb8aa3b, v52
	v_mul_f32_e32 v49, 0xbfb8aa3b, v53
	ds_write2st64_b32 v155, v32, v33 offset0:160 offset1:164
	v_mul_f32_e32 v32, 0xbfb8aa3b, v36
	v_mul_f32_e32 v33, 0xbfb8aa3b, v37
	ds_write2st64_b32 v155, v16, v17 offset0:192 offset1:196
	v_mul_f32_e32 v16, 0xbfb8aa3b, v20
	v_mul_f32_e32 v17, 0xbfb8aa3b, v21
	ds_write2st64_b32 v155, v0, v1 offset0:224 offset1:228
	v_mul_f32_e32 v0, 0xbfb8aa3b, v4
	v_mul_f32_e32 v1, 0xbfb8aa3b, v5
	v_exp_f32_e32 v48, v48
	v_exp_f32_e32 v49, v49
	v_exp_f32_e32 v32, v32
	v_exp_f32_e32 v33, v33
	v_exp_f32_e32 v16, v16
	v_exp_f32_e32 v17, v17
	v_exp_f32_e32 v0, v0
	v_exp_f32_e32 v1, v1
	v_add_f32_e32 v48, 1.0, v48
	v_add_f32_e32 v49, 1.0, v49
	v_add_f32_e32 v32, 1.0, v32
	v_add_f32_e32 v33, 1.0, v33
	v_add_f32_e32 v16, 1.0, v16
	v_add_f32_e32 v17, 1.0, v17
	v_add_f32_e32 v0, 1.0, v0
	v_add_f32_e32 v1, 1.0, v1
	v_rcp_f32_e32 v48, v48
	v_rcp_f32_e32 v49, v49
	v_rcp_f32_e32 v32, v32
	v_rcp_f32_e32 v33, v33
	v_rcp_f32_e32 v16, v16
	v_rcp_f32_e32 v17, v17
	v_rcp_f32_e32 v0, v0
	v_rcp_f32_e32 v1, v1
	v_cvt_pk_bf16_f32 v48, v48, v49
	v_mul_f32_e32 v49, 0xbfb8aa3b, v54
	v_mul_f32_e32 v50, 0xbfb8aa3b, v55
	v_cvt_pk_bf16_f32 v32, v32, v33
	v_mul_f32_e32 v33, 0xbfb8aa3b, v38
	v_mul_f32_e32 v34, 0xbfb8aa3b, v39
	v_cvt_pk_bf16_f32 v16, v16, v17
	v_mul_f32_e32 v17, 0xbfb8aa3b, v22
	v_mul_f32_e32 v18, 0xbfb8aa3b, v23
	v_cvt_pk_bf16_f32 v0, v0, v1
	v_mul_f32_e32 v1, 0xbfb8aa3b, v6
	v_mul_f32_e32 v2, 0xbfb8aa3b, v7
	v_exp_f32_e32 v49, v49
	v_exp_f32_e32 v50, v50
	v_exp_f32_e32 v33, v33
	v_exp_f32_e32 v34, v34
	v_exp_f32_e32 v17, v17
	v_exp_f32_e32 v18, v18
	v_exp_f32_e32 v1, v1
	v_exp_f32_e32 v2, v2
	v_add_f32_e32 v49, 1.0, v49
	v_add_f32_e32 v50, 1.0, v50
	v_add_f32_e32 v33, 1.0, v33
	v_add_f32_e32 v34, 1.0, v34
	v_add_f32_e32 v17, 1.0, v17
	v_add_f32_e32 v18, 1.0, v18
	v_add_f32_e32 v1, 1.0, v1
	v_add_f32_e32 v2, 1.0, v2
	v_rcp_f32_e32 v49, v49
	v_rcp_f32_e32 v50, v50
	v_rcp_f32_e32 v33, v33
	v_rcp_f32_e32 v34, v34
	v_rcp_f32_e32 v17, v17
	v_rcp_f32_e32 v18, v18
	v_rcp_f32_e32 v1, v1
	v_rcp_f32_e32 v2, v2
	v_cvt_pk_bf16_f32 v49, v49, v50
	v_cvt_pk_bf16_f32 v33, v33, v34
	v_cvt_pk_bf16_f32 v17, v17, v18
	v_cvt_pk_bf16_f32 v1, v1, v2
	ds_write2st64_b32 v155, v48, v49 offset0:136 offset1:140
	v_mul_f32_e32 v48, 0xbfb8aa3b, v56
	v_mul_f32_e32 v49, 0xbfb8aa3b, v57
	ds_write2st64_b32 v155, v32, v33 offset0:168 offset1:172
	v_mul_f32_e32 v32, 0xbfb8aa3b, v40
	v_mul_f32_e32 v33, 0xbfb8aa3b, v41
	ds_write2st64_b32 v155, v16, v17 offset0:200 offset1:204
	v_mul_f32_e32 v16, 0xbfb8aa3b, v24
	v_mul_f32_e32 v17, 0xbfb8aa3b, v25
	ds_write2st64_b32 v155, v0, v1 offset0:232 offset1:236
	v_mul_f32_e32 v0, 0xbfb8aa3b, v8
	v_mul_f32_e32 v1, 0xbfb8aa3b, v9
	v_exp_f32_e32 v48, v48
	v_exp_f32_e32 v49, v49
	v_exp_f32_e32 v32, v32
	v_exp_f32_e32 v33, v33
	v_exp_f32_e32 v16, v16
	v_exp_f32_e32 v17, v17
	v_exp_f32_e32 v0, v0
	v_exp_f32_e32 v1, v1
	v_add_f32_e32 v48, 1.0, v48
	v_add_f32_e32 v49, 1.0, v49
	v_add_f32_e32 v32, 1.0, v32
	v_add_f32_e32 v33, 1.0, v33
	v_add_f32_e32 v16, 1.0, v16
	v_add_f32_e32 v17, 1.0, v17
	v_add_f32_e32 v0, 1.0, v0
	v_add_f32_e32 v1, 1.0, v1
	v_rcp_f32_e32 v48, v48
	v_rcp_f32_e32 v49, v49
	v_rcp_f32_e32 v32, v32
	v_rcp_f32_e32 v33, v33
	v_rcp_f32_e32 v16, v16
	v_rcp_f32_e32 v17, v17
	v_rcp_f32_e32 v0, v0
	v_rcp_f32_e32 v1, v1
	v_cvt_pk_bf16_f32 v48, v48, v49
	v_mul_f32_e32 v49, 0xbfb8aa3b, v58
	v_mul_f32_e32 v50, 0xbfb8aa3b, v59
	v_cvt_pk_bf16_f32 v32, v32, v33
	v_mul_f32_e32 v33, 0xbfb8aa3b, v42
	v_mul_f32_e32 v34, 0xbfb8aa3b, v43
	v_cvt_pk_bf16_f32 v16, v16, v17
	v_mul_f32_e32 v17, 0xbfb8aa3b, v26
	v_mul_f32_e32 v18, 0xbfb8aa3b, v27
	v_cvt_pk_bf16_f32 v0, v0, v1
	v_mul_f32_e32 v1, 0xbfb8aa3b, v10
	v_mul_f32_e32 v2, 0xbfb8aa3b, v11
	v_exp_f32_e32 v49, v49
	v_exp_f32_e32 v50, v50
	v_exp_f32_e32 v33, v33
	v_exp_f32_e32 v34, v34
	v_exp_f32_e32 v17, v17
	v_exp_f32_e32 v18, v18
	v_exp_f32_e32 v1, v1
	v_exp_f32_e32 v2, v2
	v_add_f32_e32 v49, 1.0, v49
	v_add_f32_e32 v50, 1.0, v50
	v_add_f32_e32 v33, 1.0, v33
	v_add_f32_e32 v34, 1.0, v34
	v_add_f32_e32 v17, 1.0, v17
	v_add_f32_e32 v18, 1.0, v18
	v_add_f32_e32 v1, 1.0, v1
	v_add_f32_e32 v2, 1.0, v2
	v_rcp_f32_e32 v49, v49
	v_rcp_f32_e32 v50, v50
	v_rcp_f32_e32 v33, v33
	v_rcp_f32_e32 v34, v34
	v_rcp_f32_e32 v17, v17
	v_rcp_f32_e32 v18, v18
	v_rcp_f32_e32 v1, v1
	v_rcp_f32_e32 v2, v2
	v_cvt_pk_bf16_f32 v49, v49, v50
	v_cvt_pk_bf16_f32 v33, v33, v34
	v_cvt_pk_bf16_f32 v17, v17, v18
	v_cvt_pk_bf16_f32 v1, v1, v2
	ds_write2st64_b32 v155, v48, v49 offset0:144 offset1:148
	v_mul_f32_e32 v48, 0xbfb8aa3b, v60
	v_mul_f32_e32 v49, 0xbfb8aa3b, v61
	ds_write2st64_b32 v155, v32, v33 offset0:176 offset1:180
	v_mul_f32_e32 v32, 0xbfb8aa3b, v44
	v_mul_f32_e32 v33, 0xbfb8aa3b, v45
	ds_write2st64_b32 v155, v16, v17 offset0:208 offset1:212
	v_mul_f32_e32 v16, 0xbfb8aa3b, v28
	v_mul_f32_e32 v17, 0xbfb8aa3b, v29
	ds_write2st64_b32 v155, v0, v1 offset0:240 offset1:244
	v_mul_f32_e32 v0, 0xbfb8aa3b, v12
	v_mul_f32_e32 v1, 0xbfb8aa3b, v13
	v_exp_f32_e32 v48, v48
	v_exp_f32_e32 v49, v49
	v_exp_f32_e32 v32, v32
	v_exp_f32_e32 v33, v33
	v_exp_f32_e32 v16, v16
	v_exp_f32_e32 v17, v17
	v_exp_f32_e32 v0, v0
	v_exp_f32_e32 v1, v1
	v_add_f32_e32 v48, 1.0, v48
	v_add_f32_e32 v49, 1.0, v49
	v_add_f32_e32 v32, 1.0, v32
	v_add_f32_e32 v33, 1.0, v33
	v_add_f32_e32 v16, 1.0, v16
	v_add_f32_e32 v17, 1.0, v17
	v_add_f32_e32 v0, 1.0, v0
	v_add_f32_e32 v1, 1.0, v1
	v_rcp_f32_e32 v48, v48
	v_rcp_f32_e32 v49, v49
	v_rcp_f32_e32 v32, v32
	v_rcp_f32_e32 v33, v33
	v_rcp_f32_e32 v16, v16
	v_rcp_f32_e32 v17, v17
	v_rcp_f32_e32 v0, v0
	v_rcp_f32_e32 v1, v1
; DI unsigned cvtpk(float lo, float hi) { f32x2_t v = {lo, hi}; bf16x2_t b = __builtin_convertvector(v, bf16x2_t); return __builtin_bit_cast(unsigned, b); }
; DI float sigmoidf_(float x) { return __builtin_amdgcn_rcpf(1.f + __expf(-x)); }
; DI f32x16 fzero() { f32x16 z; for (int i = 0; i < 16; ++i) z[i] = 0.f; return z; }
; template <int TJ>
; DI void gemm_core(const u16* __restrict__ W, int ldw, const u16* __restrict__ X, int ldx, int K, f32x16 (&acc)[2][TJ], char* lds) {
;     ...
;   G_LOAD(wA, xA, 0);
;   G_LOAD(wB, xB, 1);
;   G_STORE(wA, xA, 0);
;   __syncthreads();
;   for (int kt = 0; kt < nk; kt += 2) {
;     if (kt + 2 < nk) G_LOAD(wA, xA, kt + 2);
;     G_COMPUTE(0);
;     G_STORE(wB, xB, 1);
;     __syncthreads();
; template <int TJ>
; DI void merge_tile(const Params& p, size_t t0, int nt, char* lds) {
;     ...
;         for (int e = 0; e < 8; ++e) sgl[((i * TJ + j) * 8 + e) * 256] = cvtpk(sigmoidf_(ag[i][j][2 * e]), sigmoidf_(ag[i][j][2 * e + 1]));
; #pragma unroll
;     for (int i = 0; i < 2; ++i)
; #pragma unroll
;       for (int j = 0; j < TJ; ++j) ag[i][j] = fzero();
;     gemm_core<TJ>(Wu + ((size_t)br * 1024 + nt * 128) * 512, 512, P + t0 * PW + zc, PW, 512, ag, lds);
	v_cvt_pk_bf16_f32 v48, v48, v49
	v_mul_f32_e32 v49, 0xbfb8aa3b, v62
	v_mul_f32_e32 v50, 0xbfb8aa3b, v63
	v_cvt_pk_bf16_f32 v32, v32, v33
	v_mul_f32_e32 v33, 0xbfb8aa3b, v46
	v_mul_f32_e32 v34, 0xbfb8aa3b, v47
	v_cvt_pk_bf16_f32 v16, v16, v17
	v_mul_f32_e32 v17, 0xbfb8aa3b, v30
	v_mul_f32_e32 v18, 0xbfb8aa3b, v31
	v_cvt_pk_bf16_f32 v0, v0, v1
	v_mul_f32_e32 v1, 0xbfb8aa3b, v14
	v_mul_f32_e32 v2, 0xbfb8aa3b, v15
	v_exp_f32_e32 v49, v49
	v_exp_f32_e32 v50, v50
	v_exp_f32_e32 v33, v33
	v_exp_f32_e32 v34, v34
	v_exp_f32_e32 v17, v17
	v_exp_f32_e32 v18, v18
	v_exp_f32_e32 v1, v1
	v_exp_f32_e32 v2, v2
	v_add_f32_e32 v49, 1.0, v49
	v_add_f32_e32 v50, 1.0, v50
	v_add_f32_e32 v33, 1.0, v33
	v_add_f32_e32 v34, 1.0, v34
	v_add_f32_e32 v17, 1.0, v17
	v_add_f32_e32 v18, 1.0, v18
	v_add_f32_e32 v1, 1.0, v1
	v_add_f32_e32 v2, 1.0, v2
	v_rcp_f32_e32 v49, v49
	v_rcp_f32_e32 v50, v50
	v_rcp_f32_e32 v33, v33
	v_rcp_f32_e32 v34, v34
	v_rcp_f32_e32 v17, v17
	v_rcp_f32_e32 v18, v18
	v_rcp_f32_e32 v1, v1
	v_rcp_f32_e32 v2, v2
	v_cvt_pk_bf16_f32 v49, v49, v50
	v_cvt_pk_bf16_f32 v33, v33, v34
	v_cvt_pk_bf16_f32 v17, v17, v18
	v_cvt_pk_bf16_f32 v1, v1, v2
	s_lshl_b64 s[0:1], s[36:37], 1
	v_mov_b32_e32 v18, v190
	ds_write2st64_b32 v155, v48, v49 offset0:152 offset1:156
	ds_write2st64_b32 v155, v32, v33 offset0:184 offset1:188
	ds_write2st64_b32 v155, v16, v17 offset0:216 offset1:220
	ds_write2st64_b32 v155, v0, v1 offset0:248 offset1:252
	s_add_u32 s0, s39, s0
	s_addc_u32 s1, s40, s1
	v_ashrrev_i32_e32 v16, 2, v18
	v_and_b32_e32 v19, 3, v18
	v_ashrrev_i32_e32 v17, 31, v16
	v_lshlrev_b64 v[0:1], 10, v[16:17]
	v_lshlrev_b32_e32 v64, 4, v19
	s_add_u32 s36, s22, s2
	v_or_b32_e32 v0, v0, v64
	s_addc_u32 s37, s23, s3
	v_lshl_add_u64 v[4:5], s[36:37], 0, v[0:1]
	v_mov_b64_e32 v[0:1], s[0:1]
	v_mad_i64_i32 v[0:1], s[0:1], v16, s89, v[0:1]
	s_mov_b32 s0, 0x1d520000
	s_nop 0
	v_add_co_u32_e32 v68, vcc, s0, v4
	s_mov_b32 s0, 0x1d530000
	s_nop 0
	v_addc_co_u32_e32 v69, vcc, 0, v5, vcc
	v_lshl_add_u64 v[66:67], v[0:1], 0, v[64:65]
	global_load_dwordx4 v[0:3], v[68:69], off
	v_add_co_u32_e32 v70, vcc, s0, v4
	v_lshlrev_b32_e32 v20, 11, v19
	s_nop 0
	v_addc_co_u32_e32 v71, vcc, 0, v5, vcc
	global_load_dwordx4 v[4:7], v[70:71], off
	global_load_dwordx4 v[8:11], v[66:67], off
	v_add_co_u32_e32 v72, vcc, s25, v66
	v_lshlrev_b32_e32 v19, 5, v19
	s_nop 0
	v_addc_co_u32_e32 v73, vcc, 0, v67, vcc
	global_load_dwordx4 v[12:15], v[72:73], off
	v_lshlrev_b32_e32 v16, 4, v16
	v_xad_u32 v64, v16, v19, v20
	global_load_dwordx4 v[148:151], v[68:69], off offset:64
	global_load_dwordx4 v[156:159], v[70:71], off offset:64
	global_load_dwordx4 v[160:163], v[66:67], off offset:64
	global_load_dwordx4 v[164:167], v[72:73], off offset:64
	v_bfe_u32 v17, v18, 5, 1
	s_waitcnt vmcnt(7)
	ds_write_b128 v64, v[0:3]
	v_add_u32_e32 v0, 0x400, v16
	v_xad_u32 v74, v0, v19, v20
	s_waitcnt vmcnt(6)
	ds_write_b128 v74, v[4:7]
	s_waitcnt vmcnt(5)
	ds_write_b128 v64, v[8:11] offset:8192
	s_waitcnt vmcnt(4)
	ds_write_b128 v74, v[12:15] offset:8192
	s_waitcnt lgkmcnt(0)
	s_barrier
	global_load_dwordx4 v[168:171], v[68:69], off offset:128
	global_load_dwordx4 v[172:175], v[70:71], off offset:128
	global_load_dwordx4 v[176:179], v[66:67], off offset:128
	global_load_dwordx4 v[180:183], v[72:73], off offset:128
	v_lshlrev_b32_e32 v2, 4, v18
	v_and_b32_e32 v3, 0x1f0, v2
	v_lshlrev_b32_e32 v5, 3, v18
	v_and_b32_e32 v2, 0x5f0, v2
	v_and_or_b32 v3, v5, s18, v3
	v_lshlrev_b32_e32 v0, 11, v17
	v_lshlrev_b32_e32 v1, 5, v17
	v_or_b32_e32 v4, 0x200, v2
	v_or_b32_e32 v5, 0x200, v3
	v_bitop3_b32 v79, v0, v1, v2 bitop3:0xf6
	v_bitop3_b32 v80, v0, v4, v1 bitop3:0xf6
	v_xad_u32 v81, v3, v1, v0
	v_xad_u32 v146, v5, v1, v0
	v_or_b32_e32 v0, 2, v17
	v_lshlrev_b32_e32 v1, 11, v0
	v_lshlrev_b32_e32 v0, 5, v0
	v_bitop3_b32 v75, v1, v0, v2 bitop3:0xf6
	v_bitop3_b32 v76, v1, v0, v4 bitop3:0xf6
	v_xad_u32 v77, v0, v3, v1
	v_xad_u32 v78, v5, v0, v1
	ds_read_b128 v[0:3], v79
	ds_read_b128 v[4:7], v80
	ds_read_b128 v[8:11], v81 offset:8192
	ds_read_b128 v[12:15], v146 offset:8192
	s_setprio 1
	s_waitcnt lgkmcnt(1)
	v_mfma_f32_32x32x16_bf16 v[48:63], v[0:3], v[8:11], 0
	s_waitcnt lgkmcnt(0)
	v_mfma_f32_32x32x16_bf16 v[32:47], v[0:3], v[12:15], 0
	v_mfma_f32_32x32x16_bf16 v[16:31], v[4:7], v[8:11], 0
	v_mfma_f32_32x32x16_bf16 v[0:15], v[4:7], v[12:15], 0
	s_setprio 0
	ds_read_b128 v[184:187], v75
	ds_read_b128 v[206:209], v76
	ds_read_b128 v[214:217], v77 offset:8192
	ds_read_b128 v[218:221], v78 offset:8192
	s_setprio 1
	s_waitcnt lgkmcnt(1)
	v_mfma_f32_32x32x16_bf16 v[48:63], v[184:187], v[214:217], v[48:63]
	s_waitcnt lgkmcnt(0)
	v_mfma_f32_32x32x16_bf16 v[32:47], v[184:187], v[218:221], v[32:47]
	v_mfma_f32_32x32x16_bf16 v[16:31], v[206:209], v[214:217], v[16:31]
	v_mfma_f32_32x32x16_bf16 v[0:15], v[206:209], v[218:221], v[0:15]
	s_setprio 0
	s_waitcnt vmcnt(7)
	ds_write_b128 v64, v[148:151] offset:16384
	s_waitcnt vmcnt(6)
	ds_write_b128 v74, v[156:159] offset:16384
	s_waitcnt vmcnt(5)
	ds_write_b128 v64, v[160:163] offset:24576
	s_waitcnt vmcnt(4)
	ds_write_b128 v74, v[164:167] offset:24576
	s_waitcnt lgkmcnt(0)
	s_barrier
; template <int TJ>
; DI void gemm_core(const u16* __restrict__ W, int ldw, const u16* __restrict__ X, int ldx, int K, f32x16 (&acc)[2][TJ], char* lds) {
;     ...
;   for (int kt = 0; kt < nk; kt += 2) {
;     if (kt + 2 < nk) G_LOAD(wA, xA, kt + 2);
;     G_COMPUTE(0);
;     G_STORE(wB, xB, 1);
;     __syncthreads();
;     if (kt + 3 < nk) G_LOAD(wB, xB, kt + 3);
;     G_COMPUTE(1);
;     if (kt + 2 < nk) G_STORE(wA, xA, 0);
;     __syncthreads();
	global_load_dwordx4 v[148:151], v[68:69], off offset:192
	global_load_dwordx4 v[156:159], v[66:67], off offset:192
	global_load_dwordx4 v[160:163], v[70:71], off offset:192
	global_load_dwordx4 v[164:167], v[72:73], off offset:192
	ds_read_b128 v[184:187], v79 offset:16384
	ds_read_b128 v[206:209], v80 offset:16384
	ds_read_b128 v[214:217], v81 offset:24576
	ds_read_b128 v[218:221], v146 offset:24576
	s_setprio 1
	s_waitcnt lgkmcnt(1)
	v_mfma_f32_32x32x16_bf16 v[48:63], v[184:187], v[214:217], v[48:63]
	s_waitcnt lgkmcnt(0)
	v_mfma_f32_32x32x16_bf16 v[32:47], v[184:187], v[218:221], v[32:47]
	v_mfma_f32_32x32x16_bf16 v[16:31], v[206:209], v[214:217], v[16:31]
	v_mfma_f32_32x32x16_bf16 v[0:15], v[206:209], v[218:221], v[0:15]
	s_setprio 0
	ds_read_b128 v[184:187], v75 offset:16384
	ds_read_b128 v[206:209], v76 offset:16384
	ds_read_b128 v[214:217], v77 offset:24576
	ds_read_b128 v[218:221], v78 offset:24576
	s_setprio 1
	s_waitcnt lgkmcnt(1)
	v_mfma_f32_32x32x16_bf16 v[48:63], v[184:187], v[214:217], v[48:63]
	s_waitcnt lgkmcnt(0)
	v_mfma_f32_32x32x16_bf16 v[32:47], v[184:187], v[218:221], v[32:47]
	v_mfma_f32_32x32x16_bf16 v[16:31], v[206:209], v[214:217], v[16:31]
	v_mfma_f32_32x32x16_bf16 v[0:15], v[206:209], v[218:221], v[0:15]
	s_setprio 0
	s_waitcnt vmcnt(7)
	ds_write_b128 v64, v[168:171]
	s_waitcnt vmcnt(6)
	ds_write_b128 v74, v[172:175]
	s_waitcnt vmcnt(5)
	ds_write_b128 v64, v[176:179] offset:8192
	s_waitcnt vmcnt(4)
	ds_write_b128 v74, v[180:183] offset:8192
	s_waitcnt lgkmcnt(0)
	s_barrier
	global_load_dwordx4 v[168:171], v[68:69], off offset:256
	global_load_dwordx4 v[172:175], v[66:67], off offset:256
	global_load_dwordx4 v[176:179], v[70:71], off offset:256
	global_load_dwordx4 v[180:183], v[72:73], off offset:256
	ds_read_b128 v[184:187], v79
	ds_read_b128 v[206:209], v80
	ds_read_b128 v[214:217], v81 offset:8192
	ds_read_b128 v[218:221], v146 offset:8192
	s_setprio 1
	s_waitcnt lgkmcnt(1)
	v_mfma_f32_32x32x16_bf16 v[48:63], v[184:187], v[214:217], v[48:63]
	s_waitcnt lgkmcnt(0)
	v_mfma_f32_32x32x16_bf16 v[32:47], v[184:187], v[218:221], v[32:47]
	v_mfma_f32_32x32x16_bf16 v[16:31], v[206:209], v[214:217], v[16:31]
	v_mfma_f32_32x32x16_bf16 v[0:15], v[206:209], v[218:221], v[0:15]
	s_setprio 0
	ds_read_b128 v[184:187], v75
	ds_read_b128 v[206:209], v76
	ds_read_b128 v[214:217], v77 offset:8192
	ds_read_b128 v[218:221], v78 offset:8192
	s_setprio 1
	s_waitcnt lgkmcnt(1)
	v_mfma_f32_32x32x16_bf16 v[48:63], v[184:187], v[214:217], v[48:63]
	s_waitcnt lgkmcnt(0)
	v_mfma_f32_32x32x16_bf16 v[32:47], v[184:187], v[218:221], v[32:47]
	v_mfma_f32_32x32x16_bf16 v[16:31], v[206:209], v[214:217], v[16:31]
	v_mfma_f32_32x32x16_bf16 v[0:15], v[206:209], v[218:221], v[0:15]
	s_setprio 0
	s_waitcnt vmcnt(7)
	ds_write_b128 v64, v[148:151] offset:16384
	s_waitcnt vmcnt(5)
	ds_write_b128 v74, v[160:163] offset:16384
	ds_write_b128 v64, v[156:159] offset:24576
	s_waitcnt vmcnt(4)
	ds_write_b128 v74, v[164:167] offset:24576
	s_waitcnt lgkmcnt(0)
	s_barrier
	global_load_dwordx4 v[148:151], v[68:69], off offset:320
	global_load_dwordx4 v[156:159], v[66:67], off offset:320
	global_load_dwordx4 v[160:163], v[70:71], off offset:320
	global_load_dwordx4 v[164:167], v[72:73], off offset:320
	ds_read_b128 v[184:187], v79 offset:16384
	ds_read_b128 v[206:209], v80 offset:16384
	ds_read_b128 v[214:217], v81 offset:24576
	ds_read_b128 v[218:221], v146 offset:24576
	s_setprio 1
	s_waitcnt lgkmcnt(1)
	v_mfma_f32_32x32x16_bf16 v[48:63], v[184:187], v[214:217], v[48:63]
	s_waitcnt lgkmcnt(0)
	v_mfma_f32_32x32x16_bf16 v[32:47], v[184:187], v[218:221], v[32:47]
	v_mfma_f32_32x32x16_bf16 v[16:31], v[206:209], v[214:217], v[16:31]
	v_mfma_f32_32x32x16_bf16 v[0:15], v[206:209], v[218:221], v[0:15]
	s_setprio 0
	ds_read_b128 v[184:187], v75 offset:16384
	ds_read_b128 v[206:209], v76 offset:16384
	ds_read_b128 v[214:217], v77 offset:24576
	ds_read_b128 v[218:221], v78 offset:24576
	s_setprio 1
	s_waitcnt lgkmcnt(1)
	v_mfma_f32_32x32x16_bf16 v[48:63], v[184:187], v[214:217], v[48:63]
	s_waitcnt lgkmcnt(0)
	v_mfma_f32_32x32x16_bf16 v[32:47], v[184:187], v[218:221], v[32:47]
	v_mfma_f32_32x32x16_bf16 v[16:31], v[206:209], v[214:217], v[16:31]
	v_mfma_f32_32x32x16_bf16 v[0:15], v[206:209], v[218:221], v[0:15]
	s_setprio 0
	s_waitcnt vmcnt(7)
	ds_write_b128 v64, v[168:171]
	s_waitcnt vmcnt(5)
	ds_write_b128 v74, v[176:179]
	ds_write_b128 v64, v[172:175] offset:8192
	s_waitcnt vmcnt(4)
	ds_write_b128 v74, v[180:183] offset:8192
	s_waitcnt lgkmcnt(0)
	s_barrier
	global_load_dwordx4 v[168:171], v[68:69], off offset:384
	global_load_dwordx4 v[172:175], v[66:67], off offset:384
	global_load_dwordx4 v[176:179], v[70:71], off offset:384
	global_load_dwordx4 v[180:183], v[72:73], off offset:384
	ds_read_b128 v[184:187], v79
	ds_read_b128 v[206:209], v80
	ds_read_b128 v[214:217], v81 offset:8192
	ds_read_b128 v[218:221], v146 offset:8192
	s_setprio 1
	s_waitcnt lgkmcnt(1)
	v_mfma_f32_32x32x16_bf16 v[48:63], v[184:187], v[214:217], v[48:63]
	s_waitcnt lgkmcnt(0)
	v_mfma_f32_32x32x16_bf16 v[32:47], v[184:187], v[218:221], v[32:47]
	v_mfma_f32_32x32x16_bf16 v[16:31], v[206:209], v[214:217], v[16:31]
	v_mfma_f32_32x32x16_bf16 v[0:15], v[206:209], v[218:221], v[0:15]
	s_setprio 0
	ds_read_b128 v[184:187], v75
	ds_read_b128 v[206:209], v76
	ds_read_b128 v[214:217], v77 offset:8192
	ds_read_b128 v[218:221], v78 offset:8192
	s_setprio 1
	s_waitcnt lgkmcnt(1)
	v_mfma_f32_32x32x16_bf16 v[48:63], v[184:187], v[214:217], v[48:63]
	s_waitcnt lgkmcnt(0)
	v_mfma_f32_32x32x16_bf16 v[32:47], v[184:187], v[218:221], v[32:47]
	v_mfma_f32_32x32x16_bf16 v[16:31], v[206:209], v[214:217], v[16:31]
	v_mfma_f32_32x32x16_bf16 v[0:15], v[206:209], v[218:221], v[0:15]
	s_setprio 0
	s_waitcnt vmcnt(7)
	ds_write_b128 v64, v[148:151] offset:16384
	s_waitcnt vmcnt(5)
	ds_write_b128 v74, v[160:163] offset:16384
	ds_write_b128 v64, v[156:159] offset:24576
	s_waitcnt vmcnt(4)
	ds_write_b128 v74, v[164:167] offset:24576
	s_waitcnt lgkmcnt(0)
	s_barrier
; template <int TJ>
; DI void gemm_core(const u16* __restrict__ W, int ldw, const u16* __restrict__ X, int ldx, int K, f32x16 (&acc)[2][TJ], char* lds) {
;     ...
;   for (int kt = 0; kt < nk; kt += 2) {
;     if (kt + 2 < nk) G_LOAD(wA, xA, kt + 2);
;     G_COMPUTE(0);
;     G_STORE(wB, xB, 1);
;     __syncthreads();
;     if (kt + 3 < nk) G_LOAD(wB, xB, kt + 3);
;     G_COMPUTE(1);
;     if (kt + 2 < nk) G_STORE(wA, xA, 0);
;     __syncthreads();
	global_load_dwordx4 v[148:151], v[68:69], off offset:448
	global_load_dwordx4 v[156:159], v[66:67], off offset:448
	global_load_dwordx4 v[160:163], v[70:71], off offset:448
	global_load_dwordx4 v[164:167], v[72:73], off offset:448
	ds_read_b128 v[184:187], v79 offset:16384
	ds_read_b128 v[206:209], v80 offset:16384
	ds_read_b128 v[214:217], v81 offset:24576
	ds_read_b128 v[218:221], v146 offset:24576
	s_setprio 1
	s_waitcnt lgkmcnt(1)
	v_mfma_f32_32x32x16_bf16 v[48:63], v[184:187], v[214:217], v[48:63]
	s_waitcnt lgkmcnt(0)
	v_mfma_f32_32x32x16_bf16 v[32:47], v[184:187], v[218:221], v[32:47]
	v_mfma_f32_32x32x16_bf16 v[16:31], v[206:209], v[214:217], v[16:31]
	v_mfma_f32_32x32x16_bf16 v[0:15], v[206:209], v[218:221], v[0:15]
	s_setprio 0
	ds_read_b128 v[184:187], v75 offset:16384
	ds_read_b128 v[206:209], v76 offset:16384
	ds_read_b128 v[214:217], v77 offset:24576
	ds_read_b128 v[218:221], v78 offset:24576
	s_setprio 1
	s_waitcnt lgkmcnt(1)
	v_mfma_f32_32x32x16_bf16 v[48:63], v[184:187], v[214:217], v[48:63]
	s_waitcnt lgkmcnt(0)
	v_mfma_f32_32x32x16_bf16 v[32:47], v[184:187], v[218:221], v[32:47]
	v_mfma_f32_32x32x16_bf16 v[16:31], v[206:209], v[214:217], v[16:31]
	v_mfma_f32_32x32x16_bf16 v[0:15], v[206:209], v[218:221], v[0:15]
	s_setprio 0
	s_waitcnt vmcnt(7)
	ds_write_b128 v64, v[168:171]
	s_waitcnt vmcnt(5)
	ds_write_b128 v74, v[176:179]
	ds_write_b128 v64, v[172:175] offset:8192
	s_waitcnt vmcnt(4)
	ds_write_b128 v74, v[180:183] offset:8192
	s_waitcnt lgkmcnt(0)
	s_barrier
	global_load_dwordx4 v[168:171], v[68:69], off offset:512
	global_load_dwordx4 v[172:175], v[66:67], off offset:512
	global_load_dwordx4 v[176:179], v[70:71], off offset:512
	global_load_dwordx4 v[180:183], v[72:73], off offset:512
	ds_read_b128 v[184:187], v79
	ds_read_b128 v[206:209], v80
	ds_read_b128 v[214:217], v81 offset:8192
	ds_read_b128 v[218:221], v146 offset:8192
	s_setprio 1
	s_waitcnt lgkmcnt(1)
	v_mfma_f32_32x32x16_bf16 v[48:63], v[184:187], v[214:217], v[48:63]
	s_waitcnt lgkmcnt(0)
	v_mfma_f32_32x32x16_bf16 v[32:47], v[184:187], v[218:221], v[32:47]
	v_mfma_f32_32x32x16_bf16 v[16:31], v[206:209], v[214:217], v[16:31]
	v_mfma_f32_32x32x16_bf16 v[0:15], v[206:209], v[218:221], v[0:15]
	s_setprio 0
	ds_read_b128 v[184:187], v75
	ds_read_b128 v[206:209], v76
	ds_read_b128 v[214:217], v77 offset:8192
	ds_read_b128 v[218:221], v78 offset:8192
	s_setprio 1
	s_waitcnt lgkmcnt(1)
	v_mfma_f32_32x32x16_bf16 v[48:63], v[184:187], v[214:217], v[48:63]
	s_waitcnt lgkmcnt(0)
	v_mfma_f32_32x32x16_bf16 v[32:47], v[184:187], v[218:221], v[32:47]
	v_mfma_f32_32x32x16_bf16 v[16:31], v[206:209], v[214:217], v[16:31]
	v_mfma_f32_32x32x16_bf16 v[0:15], v[206:209], v[218:221], v[0:15]
	s_setprio 0
	s_waitcnt vmcnt(7)
	ds_write_b128 v64, v[148:151] offset:16384
	s_waitcnt vmcnt(5)
	ds_write_b128 v74, v[160:163] offset:16384
	ds_write_b128 v64, v[156:159] offset:24576
	s_waitcnt vmcnt(4)
	ds_write_b128 v74, v[164:167] offset:24576
	s_waitcnt lgkmcnt(0)
	s_barrier
	global_load_dwordx4 v[148:151], v[68:69], off offset:576
	global_load_dwordx4 v[156:159], v[66:67], off offset:576
	global_load_dwordx4 v[160:163], v[70:71], off offset:576
	global_load_dwordx4 v[164:167], v[72:73], off offset:576
	ds_read_b128 v[184:187], v79 offset:16384
	ds_read_b128 v[206:209], v80 offset:16384
	ds_read_b128 v[214:217], v81 offset:24576
	ds_read_b128 v[218:221], v146 offset:24576
	s_setprio 1
	s_waitcnt lgkmcnt(1)
	v_mfma_f32_32x32x16_bf16 v[48:63], v[184:187], v[214:217], v[48:63]
	s_waitcnt lgkmcnt(0)
	v_mfma_f32_32x32x16_bf16 v[32:47], v[184:187], v[218:221], v[32:47]
	v_mfma_f32_32x32x16_bf16 v[16:31], v[206:209], v[214:217], v[16:31]
	v_mfma_f32_32x32x16_bf16 v[0:15], v[206:209], v[218:221], v[0:15]
	s_setprio 0
	ds_read_b128 v[184:187], v75 offset:16384
	ds_read_b128 v[206:209], v76 offset:16384
	ds_read_b128 v[214:217], v77 offset:24576
	ds_read_b128 v[218:221], v78 offset:24576
	s_setprio 1
	s_waitcnt lgkmcnt(1)
	v_mfma_f32_32x32x16_bf16 v[48:63], v[184:187], v[214:217], v[48:63]
	s_waitcnt lgkmcnt(0)
	v_mfma_f32_32x32x16_bf16 v[32:47], v[184:187], v[218:221], v[32:47]
	v_mfma_f32_32x32x16_bf16 v[16:31], v[206:209], v[214:217], v[16:31]
	v_mfma_f32_32x32x16_bf16 v[0:15], v[206:209], v[218:221], v[0:15]
	s_setprio 0
	s_waitcnt vmcnt(7)
	ds_write_b128 v64, v[168:171]
	s_waitcnt vmcnt(5)
	ds_write_b128 v74, v[176:179]
	ds_write_b128 v64, v[172:175] offset:8192
	s_waitcnt vmcnt(4)
	ds_write_b128 v74, v[180:183] offset:8192
	s_waitcnt lgkmcnt(0)
	s_barrier
	global_load_dwordx4 v[168:171], v[68:69], off offset:640
	global_load_dwordx4 v[172:175], v[66:67], off offset:640
	global_load_dwordx4 v[176:179], v[70:71], off offset:640
	global_load_dwordx4 v[180:183], v[72:73], off offset:640
	ds_read_b128 v[184:187], v79
	ds_read_b128 v[206:209], v80
	ds_read_b128 v[214:217], v81 offset:8192
	ds_read_b128 v[218:221], v146 offset:8192
	s_setprio 1
	s_waitcnt lgkmcnt(1)
	v_mfma_f32_32x32x16_bf16 v[48:63], v[184:187], v[214:217], v[48:63]
	s_waitcnt lgkmcnt(0)
	v_mfma_f32_32x32x16_bf16 v[32:47], v[184:187], v[218:221], v[32:47]
	v_mfma_f32_32x32x16_bf16 v[16:31], v[206:209], v[214:217], v[16:31]
	v_mfma_f32_32x32x16_bf16 v[0:15], v[206:209], v[218:221], v[0:15]
	s_setprio 0
	ds_read_b128 v[184:187], v75
	ds_read_b128 v[206:209], v76
	ds_read_b128 v[214:217], v77 offset:8192
	ds_read_b128 v[218:221], v78 offset:8192
	s_setprio 1
	s_waitcnt lgkmcnt(1)
	v_mfma_f32_32x32x16_bf16 v[48:63], v[184:187], v[214:217], v[48:63]
	s_waitcnt lgkmcnt(0)
	v_mfma_f32_32x32x16_bf16 v[32:47], v[184:187], v[218:221], v[32:47]
	v_mfma_f32_32x32x16_bf16 v[16:31], v[206:209], v[214:217], v[16:31]
	v_mfma_f32_32x32x16_bf16 v[0:15], v[206:209], v[218:221], v[0:15]
	s_setprio 0
	s_waitcnt vmcnt(7)
	ds_write_b128 v64, v[148:151] offset:16384
	s_waitcnt vmcnt(5)
	ds_write_b128 v74, v[160:163] offset:16384
	ds_write_b128 v64, v[156:159] offset:24576
	s_waitcnt vmcnt(4)
	ds_write_b128 v74, v[164:167] offset:24576
	s_waitcnt lgkmcnt(0)
	s_barrier
; template <int TJ>
; DI void gemm_core(const u16* __restrict__ W, int ldw, const u16* __restrict__ X, int ldx, int K, f32x16 (&acc)[2][TJ], char* lds) {
;     ...
;   for (int kt = 0; kt < nk; kt += 2) {
;     if (kt + 2 < nk) G_LOAD(wA, xA, kt + 2);
;     G_COMPUTE(0);
;     G_STORE(wB, xB, 1);
;     __syncthreads();
;     if (kt + 3 < nk) G_LOAD(wB, xB, kt + 3);
;     G_COMPUTE(1);
;     if (kt + 2 < nk) G_STORE(wA, xA, 0);
;     __syncthreads();
	global_load_dwordx4 v[148:151], v[68:69], off offset:704
	global_load_dwordx4 v[156:159], v[66:67], off offset:704
	global_load_dwordx4 v[160:163], v[70:71], off offset:704
	global_load_dwordx4 v[164:167], v[72:73], off offset:704
	ds_read_b128 v[184:187], v79 offset:16384
	ds_read_b128 v[206:209], v80 offset:16384
	ds_read_b128 v[214:217], v81 offset:24576
	ds_read_b128 v[218:221], v146 offset:24576
	s_setprio 1
	s_waitcnt lgkmcnt(1)
	v_mfma_f32_32x32x16_bf16 v[48:63], v[184:187], v[214:217], v[48:63]
	s_waitcnt lgkmcnt(0)
	v_mfma_f32_32x32x16_bf16 v[32:47], v[184:187], v[218:221], v[32:47]
	v_mfma_f32_32x32x16_bf16 v[16:31], v[206:209], v[214:217], v[16:31]
	v_mfma_f32_32x32x16_bf16 v[0:15], v[206:209], v[218:221], v[0:15]
	s_setprio 0
	ds_read_b128 v[184:187], v75 offset:16384
	ds_read_b128 v[206:209], v76 offset:16384
	ds_read_b128 v[214:217], v77 offset:24576
	ds_read_b128 v[218:221], v78 offset:24576
	s_setprio 1
	s_waitcnt lgkmcnt(1)
	v_mfma_f32_32x32x16_bf16 v[48:63], v[184:187], v[214:217], v[48:63]
	s_waitcnt lgkmcnt(0)
	v_mfma_f32_32x32x16_bf16 v[32:47], v[184:187], v[218:221], v[32:47]
	v_mfma_f32_32x32x16_bf16 v[16:31], v[206:209], v[214:217], v[16:31]
	v_mfma_f32_32x32x16_bf16 v[0:15], v[206:209], v[218:221], v[0:15]
	s_setprio 0
	s_waitcnt vmcnt(7)
	ds_write_b128 v64, v[168:171]
	s_waitcnt vmcnt(5)
	ds_write_b128 v74, v[176:179]
	ds_write_b128 v64, v[172:175] offset:8192
	s_waitcnt vmcnt(4)
	ds_write_b128 v74, v[180:183] offset:8192
	s_waitcnt lgkmcnt(0)
	s_barrier
	global_load_dwordx4 v[168:171], v[68:69], off offset:768
	global_load_dwordx4 v[172:175], v[66:67], off offset:768
	global_load_dwordx4 v[176:179], v[70:71], off offset:768
	global_load_dwordx4 v[180:183], v[72:73], off offset:768
	ds_read_b128 v[184:187], v79
	ds_read_b128 v[206:209], v80
	ds_read_b128 v[214:217], v81 offset:8192
	ds_read_b128 v[218:221], v146 offset:8192
	s_setprio 1
	s_waitcnt lgkmcnt(1)
	v_mfma_f32_32x32x16_bf16 v[48:63], v[184:187], v[214:217], v[48:63]
	s_waitcnt lgkmcnt(0)
	v_mfma_f32_32x32x16_bf16 v[32:47], v[184:187], v[218:221], v[32:47]
	v_mfma_f32_32x32x16_bf16 v[16:31], v[206:209], v[214:217], v[16:31]
	v_mfma_f32_32x32x16_bf16 v[0:15], v[206:209], v[218:221], v[0:15]
	s_setprio 0
	ds_read_b128 v[184:187], v75
	ds_read_b128 v[206:209], v76
	ds_read_b128 v[214:217], v77 offset:8192
	ds_read_b128 v[218:221], v78 offset:8192
	s_setprio 1
	s_waitcnt lgkmcnt(1)
	v_mfma_f32_32x32x16_bf16 v[48:63], v[184:187], v[214:217], v[48:63]
	s_waitcnt lgkmcnt(0)
	v_mfma_f32_32x32x16_bf16 v[32:47], v[184:187], v[218:221], v[32:47]
	v_mfma_f32_32x32x16_bf16 v[16:31], v[206:209], v[214:217], v[16:31]
	v_mfma_f32_32x32x16_bf16 v[0:15], v[206:209], v[218:221], v[0:15]
	s_setprio 0
	s_waitcnt vmcnt(7)
	ds_write_b128 v64, v[148:151] offset:16384
	s_waitcnt vmcnt(5)
	ds_write_b128 v74, v[160:163] offset:16384
	ds_write_b128 v64, v[156:159] offset:24576
	s_waitcnt vmcnt(4)
	ds_write_b128 v74, v[164:167] offset:24576
	s_waitcnt lgkmcnt(0)
	s_barrier
	global_load_dwordx4 v[148:151], v[68:69], off offset:832
	global_load_dwordx4 v[156:159], v[66:67], off offset:832
	global_load_dwordx4 v[160:163], v[70:71], off offset:832
	global_load_dwordx4 v[164:167], v[72:73], off offset:832
	ds_read_b128 v[184:187], v79 offset:16384
	ds_read_b128 v[206:209], v80 offset:16384
	ds_read_b128 v[214:217], v81 offset:24576
	ds_read_b128 v[218:221], v146 offset:24576
	s_setprio 1
	s_waitcnt lgkmcnt(1)
	v_mfma_f32_32x32x16_bf16 v[48:63], v[184:187], v[214:217], v[48:63]
	s_waitcnt lgkmcnt(0)
	v_mfma_f32_32x32x16_bf16 v[32:47], v[184:187], v[218:221], v[32:47]
	v_mfma_f32_32x32x16_bf16 v[16:31], v[206:209], v[214:217], v[16:31]
	v_mfma_f32_32x32x16_bf16 v[0:15], v[206:209], v[218:221], v[0:15]
	s_setprio 0
	ds_read_b128 v[184:187], v75 offset:16384
	ds_read_b128 v[206:209], v76 offset:16384
	ds_read_b128 v[214:217], v77 offset:24576
	ds_read_b128 v[218:221], v78 offset:24576
	s_setprio 1
	s_waitcnt lgkmcnt(1)
	v_mfma_f32_32x32x16_bf16 v[48:63], v[184:187], v[214:217], v[48:63]
	s_waitcnt lgkmcnt(0)
	v_mfma_f32_32x32x16_bf16 v[32:47], v[184:187], v[218:221], v[32:47]
	v_mfma_f32_32x32x16_bf16 v[16:31], v[206:209], v[214:217], v[16:31]
	v_mfma_f32_32x32x16_bf16 v[0:15], v[206:209], v[218:221], v[0:15]
	s_setprio 0
	s_waitcnt vmcnt(7)
	ds_write_b128 v64, v[168:171]
	s_waitcnt vmcnt(5)
	ds_write_b128 v74, v[176:179]
	ds_write_b128 v64, v[172:175] offset:8192
	s_waitcnt vmcnt(4)
	ds_write_b128 v74, v[180:183] offset:8192
	s_waitcnt lgkmcnt(0)
	s_barrier
	global_load_dwordx4 v[168:171], v[68:69], off offset:896
	global_load_dwordx4 v[172:175], v[66:67], off offset:896
	global_load_dwordx4 v[176:179], v[70:71], off offset:896
	global_load_dwordx4 v[180:183], v[72:73], off offset:896
	ds_read_b128 v[184:187], v79
	ds_read_b128 v[206:209], v80
	ds_read_b128 v[214:217], v81 offset:8192
	ds_read_b128 v[218:221], v146 offset:8192
	s_setprio 1
	s_waitcnt lgkmcnt(1)
	v_mfma_f32_32x32x16_bf16 v[48:63], v[184:187], v[214:217], v[48:63]
	s_waitcnt lgkmcnt(0)
	v_mfma_f32_32x32x16_bf16 v[32:47], v[184:187], v[218:221], v[32:47]
	v_mfma_f32_32x32x16_bf16 v[16:31], v[206:209], v[214:217], v[16:31]
	v_mfma_f32_32x32x16_bf16 v[0:15], v[206:209], v[218:221], v[0:15]
	s_setprio 0
	ds_read_b128 v[184:187], v75
	ds_read_b128 v[206:209], v76
	ds_read_b128 v[214:217], v77 offset:8192
	ds_read_b128 v[218:221], v78 offset:8192
	s_setprio 1
	s_waitcnt lgkmcnt(1)
	v_mfma_f32_32x32x16_bf16 v[48:63], v[184:187], v[214:217], v[48:63]
	s_waitcnt lgkmcnt(0)
	v_mfma_f32_32x32x16_bf16 v[32:47], v[184:187], v[218:221], v[32:47]
	v_mfma_f32_32x32x16_bf16 v[16:31], v[206:209], v[214:217], v[16:31]
	v_mfma_f32_32x32x16_bf16 v[0:15], v[206:209], v[218:221], v[0:15]
	s_setprio 0
	s_waitcnt vmcnt(7)
	ds_write_b128 v64, v[148:151] offset:16384
	s_waitcnt vmcnt(5)
	ds_write_b128 v74, v[160:163] offset:16384
	ds_write_b128 v64, v[156:159] offset:24576
	s_waitcnt vmcnt(4)
	ds_write_b128 v74, v[164:167] offset:24576
	s_waitcnt lgkmcnt(0)
	s_barrier
; template <int TJ>
; DI void gemm_core(const u16* __restrict__ W, int ldw, const u16* __restrict__ X, int ldx, int K, f32x16 (&acc)[2][TJ], char* lds) {
;     ...
;   for (int kt = 0; kt < nk; kt += 2) {
;     if (kt + 2 < nk) G_LOAD(wA, xA, kt + 2);
;     G_COMPUTE(0);
;     G_STORE(wB, xB, 1);
;     __syncthreads();
;     if (kt + 3 < nk) G_LOAD(wB, xB, kt + 3);
;     G_COMPUTE(1);
;     if (kt + 2 < nk) G_STORE(wA, xA, 0);
;     __syncthreads();
	global_load_dwordx4 v[148:151], v[68:69], off offset:960
	s_nop 0
	global_load_dwordx4 v[66:69], v[66:67], off offset:960
	s_nop 0
	global_load_dwordx4 v[156:159], v[70:71], off offset:960
	s_nop 0
	global_load_dwordx4 v[70:73], v[72:73], off offset:960
	ds_read_b128 v[160:163], v79 offset:16384
	ds_read_b128 v[164:167], v80 offset:16384
	ds_read_b128 v[184:187], v81 offset:24576
	ds_read_b128 v[206:209], v146 offset:24576
	s_setprio 1
	s_waitcnt lgkmcnt(1)
	v_mfma_f32_32x32x16_bf16 v[48:63], v[160:163], v[184:187], v[48:63]
	s_waitcnt lgkmcnt(0)
	v_mfma_f32_32x32x16_bf16 v[32:47], v[160:163], v[206:209], v[32:47]
	v_mfma_f32_32x32x16_bf16 v[16:31], v[164:167], v[184:187], v[16:31]
	v_mfma_f32_32x32x16_bf16 v[0:15], v[164:167], v[206:209], v[0:15]
	s_setprio 0
	ds_read_b128 v[160:163], v75 offset:16384
	ds_read_b128 v[164:167], v76 offset:16384
	ds_read_b128 v[184:187], v77 offset:24576
	ds_read_b128 v[206:209], v78 offset:24576
	s_setprio 1
	s_waitcnt lgkmcnt(1)
	v_mfma_f32_32x32x16_bf16 v[48:63], v[160:163], v[184:187], v[48:63]
	s_waitcnt lgkmcnt(0)
	v_mfma_f32_32x32x16_bf16 v[32:47], v[160:163], v[206:209], v[32:47]
	v_mfma_f32_32x32x16_bf16 v[16:31], v[164:167], v[184:187], v[16:31]
	v_mfma_f32_32x32x16_bf16 v[0:15], v[164:167], v[206:209], v[0:15]
	s_setprio 0
	s_waitcnt vmcnt(7)
	ds_write_b128 v64, v[168:171]
	s_waitcnt vmcnt(5)
	ds_write_b128 v74, v[176:179]
	ds_write_b128 v64, v[172:175] offset:8192
	s_waitcnt vmcnt(4)
	ds_write_b128 v74, v[180:183] offset:8192
	s_waitcnt lgkmcnt(0)
	s_barrier
	ds_read_b128 v[160:163], v79
	ds_read_b128 v[164:167], v80
	ds_read_b128 v[168:171], v81 offset:8192
	ds_read_b128 v[172:175], v146 offset:8192
	s_setprio 1
	s_waitcnt lgkmcnt(1)
	v_mfma_f32_32x32x16_bf16 v[48:63], v[160:163], v[168:171], v[48:63]
	s_waitcnt lgkmcnt(0)
	v_mfma_f32_32x32x16_bf16 v[32:47], v[160:163], v[172:175], v[32:47]
	v_mfma_f32_32x32x16_bf16 v[16:31], v[164:167], v[168:171], v[16:31]
	v_mfma_f32_32x32x16_bf16 v[0:15], v[164:167], v[172:175], v[0:15]
	s_setprio 0
	ds_read_b128 v[160:163], v75
	ds_read_b128 v[164:167], v76
	ds_read_b128 v[168:171], v77 offset:8192
	ds_read_b128 v[172:175], v78 offset:8192
	s_setprio 1
	s_waitcnt lgkmcnt(1)
	v_mfma_f32_32x32x16_bf16 v[48:63], v[160:163], v[168:171], v[48:63]
	s_waitcnt lgkmcnt(0)
	v_mfma_f32_32x32x16_bf16 v[32:47], v[160:163], v[172:175], v[32:47]
	v_mfma_f32_32x32x16_bf16 v[16:31], v[164:167], v[168:171], v[16:31]
	v_mfma_f32_32x32x16_bf16 v[0:15], v[164:167], v[172:175], v[0:15]
	s_setprio 0
	s_waitcnt vmcnt(3)
	ds_write_b128 v64, v[148:151] offset:16384
	s_waitcnt vmcnt(1)
	ds_write_b128 v74, v[156:159] offset:16384
	ds_write_b128 v64, v[66:69] offset:24576
	s_waitcnt vmcnt(0)
	ds_write_b128 v74, v[70:73] offset:24576
	s_waitcnt lgkmcnt(0)
	s_barrier
	ds_read_b128 v[66:69], v79 offset:16384
	ds_read_b128 v[70:73], v80 offset:16384
	ds_read_b128 v[148:151], v81 offset:24576
	ds_read_b128 v[156:159], v146 offset:24576
	s_setprio 1
	s_waitcnt lgkmcnt(1)
	v_mfma_f32_32x32x16_bf16 v[48:63], v[66:69], v[148:151], v[48:63]
	s_waitcnt lgkmcnt(0)
	v_mfma_f32_32x32x16_bf16 v[32:47], v[66:69], v[156:159], v[32:47]
	v_mfma_f32_32x32x16_bf16 v[16:31], v[70:73], v[148:151], v[16:31]
	v_mfma_f32_32x32x16_bf16 v[0:15], v[70:73], v[156:159], v[0:15]
	s_setprio 0
	ds_read_b128 v[66:69], v75 offset:16384
	ds_read_b128 v[70:73], v76 offset:16384
	ds_read_b128 v[74:77], v77 offset:24576
	ds_read_b128 v[78:81], v78 offset:24576
	s_setprio 1
	s_waitcnt lgkmcnt(1)
	v_mfma_f32_32x32x16_bf16 v[48:63], v[66:69], v[74:77], v[48:63]
	s_waitcnt lgkmcnt(0)
	v_mfma_f32_32x32x16_bf16 v[32:47], v[66:69], v[78:81], v[32:47]
	v_mfma_f32_32x32x16_bf16 v[16:31], v[70:73], v[74:77], v[16:31]
	v_mfma_f32_32x32x16_bf16 v[0:15], v[70:73], v[78:81], v[0:15]
	s_setprio 0
	s_barrier
; DI unsigned cvtpk(float lo, float hi) { f32x2_t v = {lo, hi}; bf16x2_t b = __builtin_convertvector(v, bf16x2_t); return __builtin_bit_cast(unsigned, b); }
; DI float bflo(unsigned u) { return __uint_as_float(u << 16); }
; DI float bfhi(unsigned u) { return __uint_as_float(u & 0xffff0000u); }
; DI float sigmoidf_(float x) { return __builtin_amdgcn_rcpf(1.f + __expf(-x)); }
; DI f32x16 fzero() { f32x16 z; for (int i = 0; i < 16; ++i) z[i] = 0.f; return z; }
; template <int TJ>
; DI void merge_tile(const Params& p, size_t t0, int nt, char* lds) {
;     ...
;   for (int br = 0; br < 4; ++br) {
;     const int zc = br == 0 ? C_AZ : br == 1 ? C_BZ : br == 2 ? C_CZ : C_DZ;
;     f32x16 ag[2][TJ];
; #pragma unroll
;     for (int i = 0; i < 2; ++i)
; #pragma unroll
;       for (int j = 0; j < TJ; ++j) ag[i][j] = fzero();
;     gemm_core<TJ>(Wm + ((size_t)br * 1024 + nt * 128) * 1024, 1024, H + t0 * 1024, 1024, 1024, ag, lds);
;     unsigned* sgl = (unsigned*)(lds + 32768) + tid;
; #pragma unroll
;     for (int i = 0; i < 2; ++i)
; #pragma unroll
;       for (int j = 0; j < TJ; ++j)
; #pragma unroll
;         for (int e = 0; e < 8; ++e) sgl[((i * TJ + j) * 8 + e) * 256] = cvtpk(sigmoidf_(ag[i][j][2 * e]), sigmoidf_(ag[i][j][2 * e + 1]));
; #pragma unroll
;     for (int i = 0; i < 2; ++i)
; #pragma unroll
;       for (int j = 0; j < TJ; ++j) ag[i][j] = fzero();
;     gemm_core<TJ>(Wu + ((size_t)br * 1024 + nt * 128) * 512, 512, P + t0 * PW + zc, PW, 512, ag, lds);
; #pragma unroll
;     for (int i = 0; i < 2; ++i)
; #pragma unroll
;       for (int j = 0; j < TJ; ++j)
; #pragma unroll
;         for (int e = 0; e < 8; ++e) { const unsigned sv = sgl[((i * TJ + j) * 8 + e) * 256]; ms[i][j][2 * e] += bflo(sv) * ag[i][j][2 * e]; ms[i][j][2 * e + 1] += bfhi(sv) * ag[i][j][2 * e + 1]; }
;   }
	ds_read2st64_b32 v[66:67], v155 offset0:128 offset1:132
	s_add_i32 s41, s41, 1
	s_add_u32 s2, s2, 0x100000
	s_addc_u32 s3, s3, 0
	s_add_u32 s28, s28, 0x200000
	s_waitcnt lgkmcnt(0)
	v_lshlrev_b32_e32 v68, 16, v66
	v_and_b32_e32 v69, 0xffff0000, v66
	v_fma_f32 v138, v48, v68, v138
	v_fma_f32 v139, v49, v69, v139
	v_lshlrev_b32_e32 v48, 16, v67
	v_and_b32_e32 v49, 0xffff0000, v67
	v_fma_f32 v140, v50, v48, v140
	v_fma_f32 v141, v51, v49, v141
	ds_read2st64_b32 v[48:49], v155 offset0:136 offset1:140
	s_addc_u32 s29, s29, 0
	s_cmp_lg_u32 s41, 4
	s_waitcnt lgkmcnt(0)
	v_lshlrev_b32_e32 v50, 16, v48
	v_and_b32_e32 v51, 0xffff0000, v48
	v_lshlrev_b32_e32 v48, 16, v49
	v_and_b32_e32 v49, 0xffff0000, v49
	v_fma_f32 v144, v54, v48, v144
	v_fma_f32 v145, v55, v49, v145
	ds_read2st64_b32 v[48:49], v155 offset0:144 offset1:148
	v_fma_f32 v142, v52, v50, v142
	v_fma_f32 v143, v53, v51, v143
	s_waitcnt lgkmcnt(0)
	v_lshlrev_b32_e32 v50, 16, v48
	v_and_b32_e32 v51, 0xffff0000, v48
	v_lshlrev_b32_e32 v48, 16, v49
	v_and_b32_e32 v49, 0xffff0000, v49
	v_fma_f32 v134, v58, v48, v134
	v_fma_f32 v135, v59, v49, v135
	ds_read2st64_b32 v[48:49], v155 offset0:152 offset1:156
	v_fma_f32 v132, v56, v50, v132
	v_fma_f32 v133, v57, v51, v133
	s_waitcnt lgkmcnt(0)
	v_lshlrev_b32_e32 v50, 16, v48
	v_and_b32_e32 v51, 0xffff0000, v48
	v_lshlrev_b32_e32 v48, 16, v49
	v_and_b32_e32 v49, 0xffff0000, v49
	v_fma_f32 v130, v62, v48, v130
	v_fma_f32 v131, v63, v49, v131
	ds_read2st64_b32 v[48:49], v155 offset0:160 offset1:164
	v_fma_f32 v136, v60, v50, v136
	v_fma_f32 v137, v61, v51, v137
	s_waitcnt lgkmcnt(0)
	v_lshlrev_b32_e32 v50, 16, v48
	v_and_b32_e32 v51, 0xffff0000, v48
	v_fma_f32 v122, v32, v50, v122
	v_fma_f32 v123, v33, v51, v123
	v_lshlrev_b32_e32 v32, 16, v49
	v_and_b32_e32 v33, 0xffff0000, v49
	v_fma_f32 v124, v34, v32, v124
	v_fma_f32 v125, v35, v33, v125
	ds_read2st64_b32 v[32:33], v155 offset0:168 offset1:172
	s_waitcnt lgkmcnt(0)
	v_lshlrev_b32_e32 v34, 16, v32
	v_and_b32_e32 v35, 0xffff0000, v32
	v_lshlrev_b32_e32 v32, 16, v33
	v_and_b32_e32 v33, 0xffff0000, v33
	v_fma_f32 v128, v38, v32, v128
	v_fma_f32 v129, v39, v33, v129
	ds_read2st64_b32 v[32:33], v155 offset0:176 offset1:180
	v_fma_f32 v126, v36, v34, v126
	v_fma_f32 v127, v37, v35, v127
	s_waitcnt lgkmcnt(0)
	v_lshlrev_b32_e32 v34, 16, v32
	v_and_b32_e32 v35, 0xffff0000, v32
	v_lshlrev_b32_e32 v32, 16, v33
	v_and_b32_e32 v33, 0xffff0000, v33
	v_fma_f32 v118, v42, v32, v118
	v_fma_f32 v119, v43, v33, v119
	ds_read2st64_b32 v[32:33], v155 offset0:184 offset1:188
	v_fma_f32 v116, v40, v34, v116
	v_fma_f32 v117, v41, v35, v117
	s_waitcnt lgkmcnt(0)
	v_lshlrev_b32_e32 v34, 16, v32
	v_and_b32_e32 v35, 0xffff0000, v32
	v_lshlrev_b32_e32 v32, 16, v33
	v_and_b32_e32 v33, 0xffff0000, v33
	v_fma_f32 v114, v46, v32, v114
	v_fma_f32 v115, v47, v33, v115
	ds_read2st64_b32 v[32:33], v155 offset0:192 offset1:196
	v_fma_f32 v120, v44, v34, v120
	v_fma_f32 v121, v45, v35, v121
	s_waitcnt lgkmcnt(0)
	v_lshlrev_b32_e32 v34, 16, v32
	v_and_b32_e32 v35, 0xffff0000, v32
	v_fma_f32 v106, v16, v34, v106
	v_fma_f32 v107, v17, v35, v107
	v_lshlrev_b32_e32 v16, 16, v33
	v_and_b32_e32 v17, 0xffff0000, v33
	v_fma_f32 v108, v18, v16, v108
	v_fma_f32 v109, v19, v17, v109
	ds_read2st64_b32 v[16:17], v155 offset0:200 offset1:204
	s_waitcnt lgkmcnt(0)
	v_lshlrev_b32_e32 v18, 16, v16
	v_and_b32_e32 v19, 0xffff0000, v16
	v_lshlrev_b32_e32 v16, 16, v17
	v_and_b32_e32 v17, 0xffff0000, v17
	v_fma_f32 v112, v22, v16, v112
	v_fma_f32 v113, v23, v17, v113
	ds_read2st64_b32 v[16:17], v155 offset0:208 offset1:212
	v_fma_f32 v110, v20, v18, v110
	v_fma_f32 v111, v21, v19, v111
	s_waitcnt lgkmcnt(0)
	v_lshlrev_b32_e32 v18, 16, v16
	v_and_b32_e32 v19, 0xffff0000, v16
	v_lshlrev_b32_e32 v16, 16, v17
	v_and_b32_e32 v17, 0xffff0000, v17
	v_fma_f32 v102, v26, v16, v102
	v_fma_f32 v103, v27, v17, v103
	ds_read2st64_b32 v[16:17], v155 offset0:216 offset1:220
	v_fma_f32 v100, v24, v18, v100
	v_fma_f32 v101, v25, v19, v101
	s_waitcnt lgkmcnt(0)
	v_lshlrev_b32_e32 v18, 16, v16
	v_and_b32_e32 v19, 0xffff0000, v16
	v_lshlrev_b32_e32 v16, 16, v17
	v_and_b32_e32 v17, 0xffff0000, v17
	v_fma_f32 v98, v30, v16, v98
	v_fma_f32 v99, v31, v17, v99
	ds_read2st64_b32 v[16:17], v155 offset0:224 offset1:228
	v_fma_f32 v104, v28, v18, v104
	v_fma_f32 v105, v29, v19, v105
	s_waitcnt lgkmcnt(0)
	v_lshlrev_b32_e32 v18, 16, v16
	v_and_b32_e32 v19, 0xffff0000, v16
	v_fma_f32 v90, v0, v18, v90
	v_fma_f32 v91, v1, v19, v91
	v_lshlrev_b32_e32 v0, 16, v17
	v_and_b32_e32 v1, 0xffff0000, v17
	v_fma_f32 v92, v2, v0, v92
	v_fma_f32 v93, v3, v1, v93
	ds_read2st64_b32 v[0:1], v155 offset0:232 offset1:236
	s_waitcnt lgkmcnt(0)
	v_lshlrev_b32_e32 v2, 16, v0
	v_and_b32_e32 v3, 0xffff0000, v0
	v_lshlrev_b32_e32 v0, 16, v1
	v_and_b32_e32 v1, 0xffff0000, v1
	v_fma_f32 v96, v6, v0, v96
	v_fma_f32 v97, v7, v1, v97
	ds_read2st64_b32 v[0:1], v155 offset0:240 offset1:244
	v_fma_f32 v94, v4, v2, v94
	v_fma_f32 v95, v5, v3, v95
	s_waitcnt lgkmcnt(0)
	v_lshlrev_b32_e32 v2, 16, v0
	v_and_b32_e32 v3, 0xffff0000, v0
	v_lshlrev_b32_e32 v0, 16, v1
	v_and_b32_e32 v1, 0xffff0000, v1
	v_fma_f32 v86, v10, v0, v86
	v_fma_f32 v87, v11, v1, v87
	ds_read2st64_b32 v[0:1], v155 offset0:248 offset1:252
	v_fma_f32 v84, v8, v2, v84
	v_fma_f32 v85, v9, v3, v85
	s_waitcnt lgkmcnt(0)
	v_lshlrev_b32_e32 v2, 16, v0
	v_and_b32_e32 v3, 0xffff0000, v0
	v_lshlrev_b32_e32 v0, 16, v1
	v_and_b32_e32 v1, 0xffff0000, v1
	v_fma_f32 v88, v12, v2, v88
	v_fma_f32 v89, v13, v3, v89
	v_fma_f32 v82, v14, v0, v82
	v_fma_f32 v83, v15, v1, v83
	s_cbranch_scc0 .LBB0_39
